# K-loop: the two consecutive waits before each pre-MFMA barrier merged into one s_waitcnt vmcnt(8) lgkmcnt(0)
# speedup vs baseline: 1.0029x; 1.0015x over previous
; #define PG8_STAGE(bufoff, gbase, voff) do { _Pragma("unroll") for (int _i = 0; _i < 2; ++_i) \
;         __builtin_amdgcn_global_load_lds((const unsigned*)((const char*)(gbase) + (voff)[_i]), (LAS unsigned*)(lds + (bufoff) + ldsw + _i * 8192), 16, 0, 0); } while (0)
; #define PG8_LDA(dst, b, h) do { _Pragma("unroll") for (int m = 0; m < 4; ++m) _Pragma("unroll") for (int k = 0; k < 2; ++k) dst[m][k] = *(const LAS bf16x8*)(lds + PG8_SA(b, h) + aoff + m * 2048 + k * 1024); } while (0)
; #define PG8_LDB(dst, b, h) do { _Pragma("unroll") for (int n = 0; n < 2; ++n) _Pragma("unroll") for (int k = 0; k < 2; ++k) dst[n][k] = *(const LAS bf16x8*)(lds + PG8_SB(b, h) + boff + n * 2048 + k * 1024); } while (0)
; #define PG8_MMA(ai, bj, At, Bt) do { __builtin_amdgcn_s_setprio(1); _Pragma("unroll") for (int m = 0; m < 4; ++m) _Pragma("unroll") for (int n = 0; n < 2; ++n) _Pragma("unroll") for (int k = 0; k < 2; ++k) \
;         acc[ai][bj][m][n] = __builtin_amdgcn_mfma_f32_16x16x32_bf16(Bt[n][k], At[m][k], acc[ai][bj][m][n], 0, 0, 0); __builtin_amdgcn_s_setprio(0); } while (0)
; #define PG8_WAIT_V(n) asm volatile("s_waitcnt vmcnt(" #n ")" ::: "memory")
; #define PG8_WAIT_L(n) asm volatile("s_waitcnt lgkmcnt(" #n ")" ::: "memory")
; #define PG8_BAR __builtin_amdgcn_s_barrier()
; #define PG8_SCHED __builtin_amdgcn_sched_barrier(0)
; template <class Epi, class Sched = StaticOrder, bool ALIGN_EPI = true>
; __device__ __forceinline__ void gemm_phase(LAS unsigned char* lds, const Gemm g, const Sched& S, const Epi& E) {
;     ...
;         for (int t = 0; t < nt; t += 2) {
;             const bool last = (t == nt - 2);
;             const char* a1 = cA + (size_t)(t + 1) * kstep;
;             const char* a2 = last ? nA : cA + (size_t)(t + 2) * kstep; const char* b2 = last ? nB : cB + (size_t)(t + 2) * kstep;
;             const char* a3 = a2 + kstep; const char* b3 = b2 + kstep;
;             PG8_LDB(B0, 0, 0); PG8_LDB(B1, 0, 1); PG8_SCHED; PG8_LDA(At, 0, 0); PG8_STAGE(PG8_SA(1, 1), a1 + hstep, voffA);
;             PG8_WAIT_V(8); PG8_WAIT_L(0); PG8_BAR; PG8_MMA(0, 0, At, B0); PG8_MMA(0, 1, At, B1); PG8_BAR; PG8_SCHED;
;             PG8_LDA(At, 0, 1); PG8_STAGE(PG8_SB(0, 0), b2, voffB); PG8_STAGE(PG8_SB(0, 1), b2 + hstep, voffB); PG8_STAGE(PG8_SA(0, 0), a2, voffA);
;             PG8_WAIT_V(8); PG8_WAIT_L(0); PG8_BAR; PG8_MMA(1, 0, At, B0); PG8_MMA(1, 1, At, B1); PG8_BAR; PG8_SCHED;
.Lmy_nb_106:
	s_add_u32 s16, s80, 0xfff80080
	s_addc_u32 s17, s81, -1
	s_add_i32 s33, 0, 0x10000
	s_cmp_eq_u32 s49, 28
	s_cselect_b32 vcc_hi, s30, s17
	s_cselect_b32 vcc_lo, s31, s16
	v_add_u32_e32 v142, s33, v144
	s_cselect_b32 s47, s21, s43
	s_cselect_b32 s46, s36, s37
	s_add_i32 s70, 0, 0x14000
	ds_read_b128 v[148:151], v142
	ds_read_b128 v[160:163], v142 offset:1024
	ds_read_b128 v[164:167], v142 offset:2048
	ds_read_b128 v[168:171], v142 offset:3072
	v_add_u32_e32 v142, s70, v144
	ds_read_b128 v[172:175], v142
	ds_read_b128 v[176:179], v142 offset:1024
	ds_read_b128 v[180:183], v142 offset:2048
	ds_read_b128 v[184:187], v142 offset:3072
	v_lshl_add_u64 v[142:143], s[80:81], 0, v[138:139]
	s_add_i32 m0, s7, 0xc000
	ds_read_b128 v[188:191], v146
	ds_read_b128 v[192:195], v146 offset:1024
	ds_read_b128 v[210:213], v146 offset:2048
	ds_read_b128 v[214:217], v146 offset:3072
	ds_read_b128 v[218:221], v146 offset:4096
	ds_read_b128 v[222:225], v146 offset:5120
	ds_read_b128 v[226:229], v146 offset:6144
	ds_read_b128 v[230:233], v146 offset:7168
	global_load_lds_dwordx4 v[142:143], off
	s_add_i32 m0, s7, 0xe000
	v_lshl_add_u64 v[142:143], s[80:81], 0, v[140:141]
	global_load_lds_dwordx4 v[142:143], off
	s_waitcnt vmcnt(8) lgkmcnt(0)
	s_barrier
	v_mfma_f32_16x16x32_bf16 v[126:129], v[148:151], v[188:191], 0
	v_mfma_f32_16x16x32_bf16 v[122:125], v[164:167], v[188:191], 0
	v_mfma_f32_16x16x32_bf16 v[118:121], v[148:151], v[210:213], 0
	v_mfma_f32_16x16x32_bf16 v[110:113], v[164:167], v[210:213], 0
	v_mfma_f32_16x16x32_bf16 v[102:105], v[148:151], v[218:221], 0
	v_mfma_f32_16x16x32_bf16 v[94:97], v[164:167], v[218:221], 0
	v_mfma_f32_16x16x32_bf16 v[82:85], v[148:151], v[226:229], 0
	v_mfma_f32_16x16x32_bf16 v[74:77], v[164:167], v[226:229], 0
	v_mfma_f32_16x16x32_bf16 v[126:129], v[160:163], v[192:195], v[126:129]
	v_mfma_f32_16x16x32_bf16 v[122:125], v[168:171], v[192:195], v[122:125]
	v_mfma_f32_16x16x32_bf16 v[118:121], v[160:163], v[214:217], v[118:121]
	v_mfma_f32_16x16x32_bf16 v[110:113], v[168:171], v[214:217], v[110:113]
	v_mfma_f32_16x16x32_bf16 v[102:105], v[160:163], v[222:225], v[102:105]
	v_mfma_f32_16x16x32_bf16 v[94:97], v[168:171], v[222:225], v[94:97]
	v_mfma_f32_16x16x32_bf16 v[82:85], v[160:163], v[230:233], v[82:85]
	v_mfma_f32_16x16x32_bf16 v[74:77], v[168:171], v[230:233], v[74:77]
	v_mfma_f32_16x16x32_bf16 v[114:117], v[172:175], v[188:191], 0
	v_mfma_f32_16x16x32_bf16 v[106:109], v[180:183], v[188:191], 0
	v_mfma_f32_16x16x32_bf16 v[98:101], v[172:175], v[210:213], 0
	v_mfma_f32_16x16x32_bf16 v[90:93], v[180:183], v[210:213], 0
	v_mfma_f32_16x16x32_bf16 v[86:89], v[172:175], v[218:221], 0
	v_mfma_f32_16x16x32_bf16 v[78:81], v[180:183], v[218:221], 0
	v_mfma_f32_16x16x32_bf16 v[70:73], v[172:175], v[226:229], 0
	v_mfma_f32_16x16x32_bf16 v[66:69], v[180:183], v[226:229], 0
	v_mfma_f32_16x16x32_bf16 v[114:117], v[176:179], v[192:195], v[114:117]
	v_mfma_f32_16x16x32_bf16 v[106:109], v[184:187], v[192:195], v[106:109]
	v_mfma_f32_16x16x32_bf16 v[98:101], v[176:179], v[214:217], v[98:101]
	v_mfma_f32_16x16x32_bf16 v[90:93], v[184:187], v[214:217], v[90:93]
	v_mfma_f32_16x16x32_bf16 v[86:89], v[176:179], v[222:225], v[86:89]
	v_mfma_f32_16x16x32_bf16 v[78:81], v[184:187], v[222:225], v[78:81]
	v_mfma_f32_16x16x32_bf16 v[70:73], v[176:179], v[230:233], v[70:73]
	v_mfma_f32_16x16x32_bf16 v[66:69], v[184:187], v[230:233], v[66:69]
	s_barrier
	s_add_i32 s16, s33, s5
	v_lshl_add_u64 v[142:143], s[46:47], 0, v[134:135]
	s_mov_b32 m0, s16
	ds_read_b128 v[188:191], v146 offset:16384
	ds_read_b128 v[192:195], v146 offset:17408
	ds_read_b128 v[210:213], v146 offset:18432
	ds_read_b128 v[214:217], v146 offset:19456
	ds_read_b128 v[218:221], v146 offset:20480
	ds_read_b128 v[222:225], v146 offset:21504
	ds_read_b128 v[226:229], v146 offset:22528
	ds_read_b128 v[230:233], v146 offset:23552
	global_load_lds_dwordx4 v[142:143], off
	s_add_i32 m0, s16, 0x2000
	s_add_u32 s16, s46, 0x80000
	v_lshl_add_u64 v[152:153], s[46:47], 0, v[130:131]
	s_addc_u32 s17, s47, 0
	s_add_i32 s33, s70, s5
	global_load_lds_dwordx4 v[152:153], off
	v_lshl_add_u64 v[196:197], s[16:17], 0, v[134:135]
	s_mov_b32 m0, s33
	v_lshl_add_u64 v[234:235], vcc, 0, v[132:133]
	global_load_lds_dwordx4 v[196:197], off
	s_add_i32 m0, s33, 0x2000
	v_lshl_add_u64 v[196:197], s[16:17], 0, v[130:131]
	global_load_lds_dwordx4 v[196:197], off
	s_mov_b32 m0, s7
	v_lshl_add_u64 v[196:197], vcc, 0, v[136:137]
	global_load_lds_dwordx4 v[196:197], off
	s_mov_b32 m0, s8
	s_nop 0
	global_load_lds_dwordx4 v[234:235], off
	s_waitcnt vmcnt(8) lgkmcnt(0)
	s_barrier
; #define PG8_STAGE(bufoff, gbase, voff) do { _Pragma("unroll") for (int _i = 0; _i < 2; ++_i) \
;         __builtin_amdgcn_global_load_lds((const unsigned*)((const char*)(gbase) + (voff)[_i]), (LAS unsigned*)(lds + (bufoff) + ldsw + _i * 8192), 16, 0, 0); } while (0)
; #define PG8_LDA(dst, b, h) do { _Pragma("unroll") for (int m = 0; m < 4; ++m) _Pragma("unroll") for (int k = 0; k < 2; ++k) dst[m][k] = *(const LAS bf16x8*)(lds + PG8_SA(b, h) + aoff + m * 2048 + k * 1024); } while (0)
; #define PG8_LDB(dst, b, h) do { _Pragma("unroll") for (int n = 0; n < 2; ++n) _Pragma("unroll") for (int k = 0; k < 2; ++k) dst[n][k] = *(const LAS bf16x8*)(lds + PG8_SB(b, h) + boff + n * 2048 + k * 1024); } while (0)
; #define PG8_MMA(ai, bj, At, Bt) do { __builtin_amdgcn_s_setprio(1); _Pragma("unroll") for (int m = 0; m < 4; ++m) _Pragma("unroll") for (int n = 0; n < 2; ++n) _Pragma("unroll") for (int k = 0; k < 2; ++k) \
;         acc[ai][bj][m][n] = __builtin_amdgcn_mfma_f32_16x16x32_bf16(Bt[n][k], At[m][k], acc[ai][bj][m][n], 0, 0, 0); __builtin_amdgcn_s_setprio(0); } while (0)
; #define PG8_WAIT_V(n) asm volatile("s_waitcnt vmcnt(" #n ")" ::: "memory")
; #define PG8_WAIT_L(n) asm volatile("s_waitcnt lgkmcnt(" #n ")" ::: "memory")
; #define PG8_BAR __builtin_amdgcn_s_barrier()
; #define PG8_SCHED __builtin_amdgcn_sched_barrier(0)
; template <class Epi, class Sched = StaticOrder, bool ALIGN_EPI = true>
; __device__ __forceinline__ void gemm_phase(LAS unsigned char* lds, const Gemm g, const Sched& S, const Epi& E) {
;     ...
;             PG8_WAIT_V(8); PG8_WAIT_L(0); PG8_BAR; PG8_MMA(1, 0, At, B0); PG8_MMA(1, 1, At, B1); PG8_BAR; PG8_SCHED;
;             PG8_LDB(B0, 1, 0); PG8_LDB(B1, 1, 1); PG8_SCHED; PG8_LDA(At, 1, 0); PG8_STAGE(PG8_SA(0, 1), a2 + hstep, voffA);
;             PG8_WAIT_V(8); PG8_WAIT_L(0); PG8_BAR; PG8_MMA(0, 0, At, B0); PG8_MMA(0, 1, At, B1); PG8_BAR; PG8_SCHED;
	v_mfma_f32_16x16x32_bf16 v[62:65], v[148:151], v[188:191], 0
	v_mfma_f32_16x16x32_bf16 v[58:61], v[164:167], v[188:191], 0
	v_mfma_f32_16x16x32_bf16 v[54:57], v[148:151], v[210:213], 0
	v_mfma_f32_16x16x32_bf16 v[46:49], v[164:167], v[210:213], 0
	v_mfma_f32_16x16x32_bf16 v[38:41], v[148:151], v[218:221], 0
	v_mfma_f32_16x16x32_bf16 v[30:33], v[164:167], v[218:221], 0
	v_mfma_f32_16x16x32_bf16 v[22:25], v[148:151], v[226:229], 0
	v_mfma_f32_16x16x32_bf16 v[14:17], v[164:167], v[226:229], 0
	v_mfma_f32_16x16x32_bf16 v[62:65], v[160:163], v[192:195], v[62:65]
	v_mfma_f32_16x16x32_bf16 v[58:61], v[168:171], v[192:195], v[58:61]
	v_mfma_f32_16x16x32_bf16 v[54:57], v[160:163], v[214:217], v[54:57]
	v_mfma_f32_16x16x32_bf16 v[46:49], v[168:171], v[214:217], v[46:49]
	v_mfma_f32_16x16x32_bf16 v[38:41], v[160:163], v[222:225], v[38:41]
	v_mfma_f32_16x16x32_bf16 v[30:33], v[168:171], v[222:225], v[30:33]
	v_mfma_f32_16x16x32_bf16 v[22:25], v[160:163], v[230:233], v[22:25]
	v_mfma_f32_16x16x32_bf16 v[14:17], v[168:171], v[230:233], v[14:17]
	v_mfma_f32_16x16x32_bf16 v[50:53], v[172:175], v[188:191], 0
	v_mfma_f32_16x16x32_bf16 v[42:45], v[180:183], v[188:191], 0
	v_mfma_f32_16x16x32_bf16 v[34:37], v[172:175], v[210:213], 0
	v_mfma_f32_16x16x32_bf16 v[26:29], v[180:183], v[210:213], 0
	v_mfma_f32_16x16x32_bf16 v[18:21], v[172:175], v[218:221], 0
	v_mfma_f32_16x16x32_bf16 v[10:13], v[180:183], v[218:221], 0
	v_mfma_f32_16x16x32_bf16 v[6:9], v[172:175], v[226:229], 0
	v_mfma_f32_16x16x32_bf16 v[2:5], v[180:183], v[226:229], 0
	v_mfma_f32_16x16x32_bf16 v[50:53], v[176:179], v[192:195], v[50:53]
	v_mfma_f32_16x16x32_bf16 v[42:45], v[184:187], v[192:195], v[42:45]
	v_mfma_f32_16x16x32_bf16 v[34:37], v[176:179], v[214:217], v[34:37]
	v_mfma_f32_16x16x32_bf16 v[26:29], v[184:187], v[214:217], v[26:29]
	v_mfma_f32_16x16x32_bf16 v[18:21], v[176:179], v[222:225], v[18:21]
	v_mfma_f32_16x16x32_bf16 v[10:13], v[184:187], v[222:225], v[10:13]
	v_mfma_f32_16x16x32_bf16 v[6:9], v[176:179], v[230:233], v[6:9]
	v_mfma_f32_16x16x32_bf16 v[2:5], v[184:187], v[230:233], v[2:5]
	s_barrier
	s_add_i32 s33, 0, 0x18000
	v_add_u32_e32 v147, s33, v144
	s_add_i32 s70, 0, 0x1c000
	ds_read_b128 v[148:151], v147
	ds_read_b128 v[160:163], v147 offset:1024
	ds_read_b128 v[164:167], v147 offset:2048
	ds_read_b128 v[168:171], v147 offset:3072
	v_add_u32_e32 v147, s70, v144
	ds_read_b128 v[172:175], v147
	ds_read_b128 v[176:179], v147 offset:1024
	ds_read_b128 v[180:183], v147 offset:2048
	ds_read_b128 v[184:187], v147 offset:3072
	s_add_u32 s16, vcc_lo, 0x80000
	s_addc_u32 s17, vcc_hi, 0
	s_mov_b32 m0, s9
	v_lshl_add_u64 v[236:237], s[16:17], 0, v[136:137]
	ds_read_b128 v[188:191], v146 offset:32768
	ds_read_b128 v[192:195], v146 offset:33792
	ds_read_b128 v[210:213], v146 offset:34816
	ds_read_b128 v[214:217], v146 offset:35840
	ds_read_b128 v[218:221], v146 offset:36864
	ds_read_b128 v[222:225], v146 offset:37888
	ds_read_b128 v[226:229], v146 offset:38912
	ds_read_b128 v[230:233], v146 offset:39936
	global_load_lds_dwordx4 v[236:237], off
	s_mov_b32 m0, s10
	v_lshl_add_u64 v[236:237], s[16:17], 0, v[132:133]
	global_load_lds_dwordx4 v[236:237], off
	s_waitcnt vmcnt(8) lgkmcnt(0)
	s_barrier
	v_mfma_f32_16x16x32_bf16 v[126:129], v[148:151], v[188:191], v[126:129]
	v_mfma_f32_16x16x32_bf16 v[122:125], v[164:167], v[188:191], v[122:125]
	v_mfma_f32_16x16x32_bf16 v[118:121], v[148:151], v[210:213], v[118:121]
	v_mfma_f32_16x16x32_bf16 v[110:113], v[164:167], v[210:213], v[110:113]
	v_mfma_f32_16x16x32_bf16 v[102:105], v[148:151], v[218:221], v[102:105]
	v_mfma_f32_16x16x32_bf16 v[94:97], v[164:167], v[218:221], v[94:97]
	v_mfma_f32_16x16x32_bf16 v[82:85], v[148:151], v[226:229], v[82:85]
	v_mfma_f32_16x16x32_bf16 v[74:77], v[164:167], v[226:229], v[74:77]
	v_mfma_f32_16x16x32_bf16 v[126:129], v[160:163], v[192:195], v[126:129]
	v_mfma_f32_16x16x32_bf16 v[122:125], v[168:171], v[192:195], v[122:125]
	v_mfma_f32_16x16x32_bf16 v[118:121], v[160:163], v[214:217], v[118:121]
	v_mfma_f32_16x16x32_bf16 v[110:113], v[168:171], v[214:217], v[110:113]
	v_mfma_f32_16x16x32_bf16 v[102:105], v[160:163], v[222:225], v[102:105]
	v_mfma_f32_16x16x32_bf16 v[94:97], v[168:171], v[222:225], v[94:97]
	v_mfma_f32_16x16x32_bf16 v[82:85], v[160:163], v[230:233], v[82:85]
	v_mfma_f32_16x16x32_bf16 v[74:77], v[168:171], v[230:233], v[74:77]
	v_mfma_f32_16x16x32_bf16 v[114:117], v[172:175], v[188:191], v[114:117]
	v_mfma_f32_16x16x32_bf16 v[106:109], v[180:183], v[188:191], v[106:109]
	v_mfma_f32_16x16x32_bf16 v[98:101], v[172:175], v[210:213], v[98:101]
	v_mfma_f32_16x16x32_bf16 v[90:93], v[180:183], v[210:213], v[90:93]
	v_mfma_f32_16x16x32_bf16 v[86:89], v[172:175], v[218:221], v[86:89]
	v_mfma_f32_16x16x32_bf16 v[78:81], v[180:183], v[218:221], v[78:81]
	v_mfma_f32_16x16x32_bf16 v[70:73], v[172:175], v[226:229], v[70:73]
	v_mfma_f32_16x16x32_bf16 v[66:69], v[180:183], v[226:229], v[66:69]
	v_mfma_f32_16x16x32_bf16 v[114:117], v[176:179], v[192:195], v[114:117]
	v_mfma_f32_16x16x32_bf16 v[106:109], v[184:187], v[192:195], v[106:109]
	v_mfma_f32_16x16x32_bf16 v[98:101], v[176:179], v[214:217], v[98:101]
	v_mfma_f32_16x16x32_bf16 v[90:93], v[184:187], v[214:217], v[90:93]
	v_mfma_f32_16x16x32_bf16 v[86:89], v[176:179], v[222:225], v[86:89]
	v_mfma_f32_16x16x32_bf16 v[78:81], v[184:187], v[222:225], v[78:81]
	v_mfma_f32_16x16x32_bf16 v[70:73], v[176:179], v[230:233], v[70:73]
	v_mfma_f32_16x16x32_bf16 v[66:69], v[184:187], v[230:233], v[66:69]
	s_barrier
; #define PG8_STAGE(bufoff, gbase, voff) do { _Pragma("unroll") for (int _i = 0; _i < 2; ++_i) \
;         __builtin_amdgcn_global_load_lds((const unsigned*)((const char*)(gbase) + (voff)[_i]), (LAS unsigned*)(lds + (bufoff) + ldsw + _i * 8192), 16, 0, 0); } while (0)
; #define PG8_LDA(dst, b, h) do { _Pragma("unroll") for (int m = 0; m < 4; ++m) _Pragma("unroll") for (int k = 0; k < 2; ++k) dst[m][k] = *(const LAS bf16x8*)(lds + PG8_SA(b, h) + aoff + m * 2048 + k * 1024); } while (0)
; #define PG8_LDB(dst, b, h) do { _Pragma("unroll") for (int n = 0; n < 2; ++n) _Pragma("unroll") for (int k = 0; k < 2; ++k) dst[n][k] = *(const LAS bf16x8*)(lds + PG8_SB(b, h) + boff + n * 2048 + k * 1024); } while (0)
; #define PG8_WAIT_V(n) asm volatile("s_waitcnt vmcnt(" #n ")" ::: "memory")
; template <class Epi, class Sched = StaticOrder, bool ALIGN_EPI = true>
; __device__ __forceinline__ void gemm_phase(LAS unsigned char* lds, const Gemm g, const Sched& S, const Epi& E) {
;     ...
;         for (int t = 0; t < nt; t += 2) {
;             const bool last = (t == nt - 2);
;             const char* a1 = cA + (size_t)(t + 1) * kstep;
;             const char* a2 = last ? nA : cA + (size_t)(t + 2) * kstep; const char* b2 = last ? nB : cB + (size_t)(t + 2) * kstep;
;             const char* a3 = a2 + kstep; const char* b3 = b2 + kstep;
;             PG8_LDB(B0, 0, 0); PG8_LDB(B1, 0, 1); PG8_SCHED; PG8_LDA(At, 0, 0); PG8_STAGE(PG8_SA(1, 1), a1 + hstep, voffA);
;             PG8_WAIT_V(8); PG8_WAIT_L(0); PG8_BAR; PG8_MMA(0, 0, At, B0); PG8_MMA(0, 1, At, B1); PG8_BAR; PG8_SCHED;
;             PG8_LDA(At, 0, 1); PG8_STAGE(PG8_SB(0, 0), b2, voffB); PG8_STAGE(PG8_SB(0, 1), b2 + hstep, voffB); PG8_STAGE(PG8_SA(0, 0), a2, voffA);
;             PG8_WAIT_V(8); PG8_WAIT_L(0); PG8_BAR; PG8_MMA(1, 0, At, B0); PG8_MMA(1, 1, At, B1); PG8_BAR; PG8_SCHED;
;             PG8_LDB(B0, 1, 0); PG8_LDB(B1, 1, 1); PG8_SCHED; PG8_LDA(At, 1, 0); PG8_STAGE(PG8_SA(0, 1), a2 + hstep, voffA);
;             PG8_WAIT_V(8); PG8_WAIT_L(0); PG8_BAR; PG8_MMA(0, 0, At, B0); PG8_MMA(0, 1, At, B1); PG8_BAR; PG8_SCHED;
;             PG8_LDA(At, 1, 1); PG8_STAGE(PG8_SB(1, 0), b3, voffB); PG8_STAGE(PG8_SB(1, 1), b3 + hstep, voffB); PG8_STAGE(PG8_SA(1, 0), a3, voffA);
;             PG8_WAIT_V(8); PG8_WAIT_L(0); PG8_BAR; PG8_MMA(1, 0, At, B0); PG8_MMA(1, 1, At, B1); PG8_BAR; PG8_SCHED;
	s_add_i32 s16, s33, s5
	v_lshl_add_u64 v[142:143], v[142:143], 0, s[34:35]
	s_mov_b32 m0, s16
	ds_read_b128 v[188:191], v146 offset:49152
	ds_read_b128 v[192:195], v146 offset:50176
	ds_read_b128 v[210:213], v146 offset:51200
	ds_read_b128 v[214:217], v146 offset:52224
	ds_read_b128 v[218:221], v146 offset:53248
	ds_read_b128 v[222:225], v146 offset:54272
	ds_read_b128 v[226:229], v146 offset:55296
	ds_read_b128 v[230:233], v146 offset:56320
	global_load_lds_dwordx4 v[142:143], off
	s_add_i32 m0, s16, 0x2000
	s_add_u32 s16, s46, 0x80080
	v_lshl_add_u64 v[142:143], v[152:153], 0, s[34:35]
	s_addc_u32 s17, s47, 0
	s_add_i32 s33, s70, s5
	global_load_lds_dwordx4 v[142:143], off
	s_mov_b32 m0, s33
	v_lshl_add_u64 v[142:143], s[16:17], 0, v[134:135]
	global_load_lds_dwordx4 v[142:143], off
	s_add_i32 m0, s33, 0x2000
	v_lshl_add_u64 v[142:143], s[16:17], 0, v[130:131]
	global_load_lds_dwordx4 v[142:143], off
	s_mov_b32 m0, s11
	v_lshl_add_u64 v[142:143], v[196:197], 0, s[34:35]
	global_load_lds_dwordx4 v[142:143], off
	s_mov_b32 m0, s18
	v_lshl_add_u64 v[142:143], v[234:235], 0, s[34:35]
	global_load_lds_dwordx4 v[142:143], off
	s_waitcnt vmcnt(8) lgkmcnt(0)
	s_barrier
	v_mfma_f32_16x16x32_bf16 v[62:65], v[148:151], v[188:191], v[62:65]
	v_mfma_f32_16x16x32_bf16 v[58:61], v[164:167], v[188:191], v[58:61]
	v_mfma_f32_16x16x32_bf16 v[54:57], v[148:151], v[210:213], v[54:57]
	v_mfma_f32_16x16x32_bf16 v[46:49], v[164:167], v[210:213], v[46:49]
	v_mfma_f32_16x16x32_bf16 v[38:41], v[148:151], v[218:221], v[38:41]
	v_mfma_f32_16x16x32_bf16 v[30:33], v[164:167], v[218:221], v[30:33]
	v_mfma_f32_16x16x32_bf16 v[22:25], v[148:151], v[226:229], v[22:25]
	v_mfma_f32_16x16x32_bf16 v[14:17], v[164:167], v[226:229], v[14:17]
	v_mfma_f32_16x16x32_bf16 v[62:65], v[160:163], v[192:195], v[62:65]
	v_mfma_f32_16x16x32_bf16 v[58:61], v[168:171], v[192:195], v[58:61]
	v_mfma_f32_16x16x32_bf16 v[54:57], v[160:163], v[214:217], v[54:57]
	v_mfma_f32_16x16x32_bf16 v[46:49], v[168:171], v[214:217], v[46:49]
	v_mfma_f32_16x16x32_bf16 v[38:41], v[160:163], v[222:225], v[38:41]
	v_mfma_f32_16x16x32_bf16 v[30:33], v[168:171], v[222:225], v[30:33]
	v_mfma_f32_16x16x32_bf16 v[22:25], v[160:163], v[230:233], v[22:25]
	v_mfma_f32_16x16x32_bf16 v[14:17], v[168:171], v[230:233], v[14:17]
	v_mfma_f32_16x16x32_bf16 v[50:53], v[172:175], v[188:191], v[50:53]
	v_mfma_f32_16x16x32_bf16 v[42:45], v[180:183], v[188:191], v[42:45]
	v_mfma_f32_16x16x32_bf16 v[34:37], v[172:175], v[210:213], v[34:37]
	v_mfma_f32_16x16x32_bf16 v[26:29], v[180:183], v[210:213], v[26:29]
	v_mfma_f32_16x16x32_bf16 v[18:21], v[172:175], v[218:221], v[18:21]
	v_mfma_f32_16x16x32_bf16 v[10:13], v[180:183], v[218:221], v[10:13]
	v_mfma_f32_16x16x32_bf16 v[6:9], v[172:175], v[226:229], v[6:9]
	v_mfma_f32_16x16x32_bf16 v[2:5], v[180:183], v[226:229], v[2:5]
	v_mfma_f32_16x16x32_bf16 v[50:53], v[176:179], v[192:195], v[50:53]
	v_mfma_f32_16x16x32_bf16 v[42:45], v[184:187], v[192:195], v[42:45]
	v_mfma_f32_16x16x32_bf16 v[34:37], v[176:179], v[214:217], v[34:37]
	v_mfma_f32_16x16x32_bf16 v[26:29], v[184:187], v[214:217], v[26:29]
	v_mfma_f32_16x16x32_bf16 v[18:21], v[176:179], v[222:225], v[18:21]
	v_mfma_f32_16x16x32_bf16 v[10:13], v[184:187], v[222:225], v[10:13]
	v_mfma_f32_16x16x32_bf16 v[6:9], v[176:179], v[230:233], v[6:9]
	v_mfma_f32_16x16x32_bf16 v[2:5], v[184:187], v[230:233], v[2:5]
	s_barrier
	s_add_i32 s49, s49, 2
	s_add_u32 s80, s80, 0x100
	s_addc_u32 s81, s81, 0
	s_add_u32 s37, s37, 0x100
	s_addc_u32 s43, s43, 0
	s_cmp_gt_u32 s49, 29
	s_cbranch_scc0 .LBB0_106
.LBB0_106:
	s_add_u32 s16, s80, 0xfff80080
	s_addc_u32 s17, s81, -1
	s_add_i32 s33, 0, 0x10000
	s_cmp_eq_u32 s49, 28
	s_cselect_b32 vcc_hi, s30, s17
	s_cselect_b32 vcc_lo, s31, s16
	v_add_u32_e32 v142, s33, v144
	s_cselect_b32 s47, s21, s43
	s_cselect_b32 s46, s36, s37
	s_add_i32 s70, 0, 0x14000
	ds_read_b128 v[148:151], v142
	ds_read_b128 v[160:163], v142 offset:1024
	ds_read_b128 v[164:167], v142 offset:2048
	ds_read_b128 v[168:171], v142 offset:3072
	v_add_u32_e32 v142, s70, v144
	ds_read_b128 v[172:175], v142
	ds_read_b128 v[176:179], v142 offset:1024
	ds_read_b128 v[180:183], v142 offset:2048
	ds_read_b128 v[184:187], v142 offset:3072
	v_lshl_add_u64 v[142:143], s[80:81], 0, v[138:139]
	s_add_i32 m0, s7, 0xc000
	ds_read_b128 v[188:191], v146
	ds_read_b128 v[192:195], v146 offset:1024
	ds_read_b128 v[210:213], v146 offset:2048
	ds_read_b128 v[214:217], v146 offset:3072
	ds_read_b128 v[218:221], v146 offset:4096
	ds_read_b128 v[222:225], v146 offset:5120
	ds_read_b128 v[226:229], v146 offset:6144
	ds_read_b128 v[230:233], v146 offset:7168
	global_load_lds_dwordx4 v[142:143], off
	s_add_i32 m0, s7, 0xe000
	v_lshl_add_u64 v[142:143], s[80:81], 0, v[140:141]
	global_load_lds_dwordx4 v[142:143], off
	s_waitcnt vmcnt(8) lgkmcnt(0)
	s_barrier
; #define PG8_STAGE(bufoff, gbase, voff) do { _Pragma("unroll") for (int _i = 0; _i < 2; ++_i) \
;         __builtin_amdgcn_global_load_lds((const unsigned*)((const char*)(gbase) + (voff)[_i]), (LAS unsigned*)(lds + (bufoff) + ldsw + _i * 8192), 16, 0, 0); } while (0)
; #define PG8_LDA(dst, b, h) do { _Pragma("unroll") for (int m = 0; m < 4; ++m) _Pragma("unroll") for (int k = 0; k < 2; ++k) dst[m][k] = *(const LAS bf16x8*)(lds + PG8_SA(b, h) + aoff + m * 2048 + k * 1024); } while (0)
; #define PG8_LDB(dst, b, h) do { _Pragma("unroll") for (int n = 0; n < 2; ++n) _Pragma("unroll") for (int k = 0; k < 2; ++k) dst[n][k] = *(const LAS bf16x8*)(lds + PG8_SB(b, h) + boff + n * 2048 + k * 1024); } while (0)
; #define PG8_MMA(ai, bj, At, Bt) do { __builtin_amdgcn_s_setprio(1); _Pragma("unroll") for (int m = 0; m < 4; ++m) _Pragma("unroll") for (int n = 0; n < 2; ++n) _Pragma("unroll") for (int k = 0; k < 2; ++k) \
;         acc[ai][bj][m][n] = __builtin_amdgcn_mfma_f32_16x16x32_bf16(Bt[n][k], At[m][k], acc[ai][bj][m][n], 0, 0, 0); __builtin_amdgcn_s_setprio(0); } while (0)
; #define PG8_WAIT_V(n) asm volatile("s_waitcnt vmcnt(" #n ")" ::: "memory")
; #define PG8_WAIT_L(n) asm volatile("s_waitcnt lgkmcnt(" #n ")" ::: "memory")
; #define PG8_BAR __builtin_amdgcn_s_barrier()
; #define PG8_SCHED __builtin_amdgcn_sched_barrier(0)
; template <class Epi, class Sched = StaticOrder, bool ALIGN_EPI = true>
; __device__ __forceinline__ void gemm_phase(LAS unsigned char* lds, const Gemm g, const Sched& S, const Epi& E) {
;     ...
;             PG8_LDB(B0, 0, 0); PG8_LDB(B1, 0, 1); PG8_SCHED; PG8_LDA(At, 0, 0); PG8_STAGE(PG8_SA(1, 1), a1 + hstep, voffA);
;             PG8_WAIT_V(8); PG8_WAIT_L(0); PG8_BAR; PG8_MMA(0, 0, At, B0); PG8_MMA(0, 1, At, B1); PG8_BAR; PG8_SCHED;
;             PG8_LDA(At, 0, 1); PG8_STAGE(PG8_SB(0, 0), b2, voffB); PG8_STAGE(PG8_SB(0, 1), b2 + hstep, voffB); PG8_STAGE(PG8_SA(0, 0), a2, voffA);
;             PG8_WAIT_V(8); PG8_WAIT_L(0); PG8_BAR; PG8_MMA(1, 0, At, B0); PG8_MMA(1, 1, At, B1); PG8_BAR; PG8_SCHED;
	v_mfma_f32_16x16x32_bf16 v[126:129], v[148:151], v[188:191], v[126:129]
	v_mfma_f32_16x16x32_bf16 v[122:125], v[164:167], v[188:191], v[122:125]
	v_mfma_f32_16x16x32_bf16 v[118:121], v[148:151], v[210:213], v[118:121]
	v_mfma_f32_16x16x32_bf16 v[110:113], v[164:167], v[210:213], v[110:113]
	v_mfma_f32_16x16x32_bf16 v[102:105], v[148:151], v[218:221], v[102:105]
	v_mfma_f32_16x16x32_bf16 v[94:97], v[164:167], v[218:221], v[94:97]
	v_mfma_f32_16x16x32_bf16 v[82:85], v[148:151], v[226:229], v[82:85]
	v_mfma_f32_16x16x32_bf16 v[74:77], v[164:167], v[226:229], v[74:77]
	v_mfma_f32_16x16x32_bf16 v[126:129], v[160:163], v[192:195], v[126:129]
	v_mfma_f32_16x16x32_bf16 v[122:125], v[168:171], v[192:195], v[122:125]
	v_mfma_f32_16x16x32_bf16 v[118:121], v[160:163], v[214:217], v[118:121]
	v_mfma_f32_16x16x32_bf16 v[110:113], v[168:171], v[214:217], v[110:113]
	v_mfma_f32_16x16x32_bf16 v[102:105], v[160:163], v[222:225], v[102:105]
	v_mfma_f32_16x16x32_bf16 v[94:97], v[168:171], v[222:225], v[94:97]
	v_mfma_f32_16x16x32_bf16 v[82:85], v[160:163], v[230:233], v[82:85]
	v_mfma_f32_16x16x32_bf16 v[74:77], v[168:171], v[230:233], v[74:77]
	v_mfma_f32_16x16x32_bf16 v[114:117], v[172:175], v[188:191], v[114:117]
	v_mfma_f32_16x16x32_bf16 v[106:109], v[180:183], v[188:191], v[106:109]
	v_mfma_f32_16x16x32_bf16 v[98:101], v[172:175], v[210:213], v[98:101]
	v_mfma_f32_16x16x32_bf16 v[90:93], v[180:183], v[210:213], v[90:93]
	v_mfma_f32_16x16x32_bf16 v[86:89], v[172:175], v[218:221], v[86:89]
	v_mfma_f32_16x16x32_bf16 v[78:81], v[180:183], v[218:221], v[78:81]
	v_mfma_f32_16x16x32_bf16 v[70:73], v[172:175], v[226:229], v[70:73]
	v_mfma_f32_16x16x32_bf16 v[66:69], v[180:183], v[226:229], v[66:69]
	v_mfma_f32_16x16x32_bf16 v[114:117], v[176:179], v[192:195], v[114:117]
	v_mfma_f32_16x16x32_bf16 v[106:109], v[184:187], v[192:195], v[106:109]
	v_mfma_f32_16x16x32_bf16 v[98:101], v[176:179], v[214:217], v[98:101]
	v_mfma_f32_16x16x32_bf16 v[90:93], v[184:187], v[214:217], v[90:93]
	v_mfma_f32_16x16x32_bf16 v[86:89], v[176:179], v[222:225], v[86:89]
	v_mfma_f32_16x16x32_bf16 v[78:81], v[184:187], v[222:225], v[78:81]
	v_mfma_f32_16x16x32_bf16 v[70:73], v[176:179], v[230:233], v[70:73]
	v_mfma_f32_16x16x32_bf16 v[66:69], v[184:187], v[230:233], v[66:69]
	s_barrier
	s_add_i32 s16, s33, s5
	v_lshl_add_u64 v[142:143], s[46:47], 0, v[134:135]
	s_mov_b32 m0, s16
	ds_read_b128 v[188:191], v146 offset:16384
	ds_read_b128 v[192:195], v146 offset:17408
	ds_read_b128 v[210:213], v146 offset:18432
	ds_read_b128 v[214:217], v146 offset:19456
	ds_read_b128 v[218:221], v146 offset:20480
	ds_read_b128 v[222:225], v146 offset:21504
	ds_read_b128 v[226:229], v146 offset:22528
	ds_read_b128 v[230:233], v146 offset:23552
	global_load_lds_dwordx4 v[142:143], off
	s_add_i32 m0, s16, 0x2000
	s_add_u32 s16, s46, 0x80000
	v_lshl_add_u64 v[152:153], s[46:47], 0, v[130:131]
	s_addc_u32 s17, s47, 0
	s_add_i32 s33, s70, s5
	global_load_lds_dwordx4 v[152:153], off
	v_lshl_add_u64 v[196:197], s[16:17], 0, v[134:135]
	s_mov_b32 m0, s33
	v_lshl_add_u64 v[234:235], vcc, 0, v[132:133]
	global_load_lds_dwordx4 v[196:197], off
	s_add_i32 m0, s33, 0x2000
	v_lshl_add_u64 v[196:197], s[16:17], 0, v[130:131]
	global_load_lds_dwordx4 v[196:197], off
	s_mov_b32 m0, s7
	v_lshl_add_u64 v[196:197], vcc, 0, v[136:137]
	global_load_lds_dwordx4 v[196:197], off
	s_mov_b32 m0, s8
	s_nop 0
	global_load_lds_dwordx4 v[234:235], off
	s_waitcnt vmcnt(8) lgkmcnt(0)
	s_barrier
	v_mfma_f32_16x16x32_bf16 v[62:65], v[148:151], v[188:191], v[62:65]
	v_mfma_f32_16x16x32_bf16 v[58:61], v[164:167], v[188:191], v[58:61]
	v_mfma_f32_16x16x32_bf16 v[54:57], v[148:151], v[210:213], v[54:57]
	v_mfma_f32_16x16x32_bf16 v[46:49], v[164:167], v[210:213], v[46:49]
	v_mfma_f32_16x16x32_bf16 v[38:41], v[148:151], v[218:221], v[38:41]
	v_mfma_f32_16x16x32_bf16 v[30:33], v[164:167], v[218:221], v[30:33]
	v_mfma_f32_16x16x32_bf16 v[22:25], v[148:151], v[226:229], v[22:25]
	v_mfma_f32_16x16x32_bf16 v[14:17], v[164:167], v[226:229], v[14:17]
	v_mfma_f32_16x16x32_bf16 v[62:65], v[160:163], v[192:195], v[62:65]
	v_mfma_f32_16x16x32_bf16 v[58:61], v[168:171], v[192:195], v[58:61]
	v_mfma_f32_16x16x32_bf16 v[54:57], v[160:163], v[214:217], v[54:57]
	v_mfma_f32_16x16x32_bf16 v[46:49], v[168:171], v[214:217], v[46:49]
	v_mfma_f32_16x16x32_bf16 v[38:41], v[160:163], v[222:225], v[38:41]
	v_mfma_f32_16x16x32_bf16 v[30:33], v[168:171], v[222:225], v[30:33]
	v_mfma_f32_16x16x32_bf16 v[22:25], v[160:163], v[230:233], v[22:25]
	v_mfma_f32_16x16x32_bf16 v[14:17], v[168:171], v[230:233], v[14:17]
	v_mfma_f32_16x16x32_bf16 v[50:53], v[172:175], v[188:191], v[50:53]
	v_mfma_f32_16x16x32_bf16 v[42:45], v[180:183], v[188:191], v[42:45]
	v_mfma_f32_16x16x32_bf16 v[34:37], v[172:175], v[210:213], v[34:37]
	v_mfma_f32_16x16x32_bf16 v[26:29], v[180:183], v[210:213], v[26:29]
	v_mfma_f32_16x16x32_bf16 v[18:21], v[172:175], v[218:221], v[18:21]
	v_mfma_f32_16x16x32_bf16 v[10:13], v[180:183], v[218:221], v[10:13]
	v_mfma_f32_16x16x32_bf16 v[6:9], v[172:175], v[226:229], v[6:9]
	v_mfma_f32_16x16x32_bf16 v[2:5], v[180:183], v[226:229], v[2:5]
	v_mfma_f32_16x16x32_bf16 v[50:53], v[176:179], v[192:195], v[50:53]
	v_mfma_f32_16x16x32_bf16 v[42:45], v[184:187], v[192:195], v[42:45]
	v_mfma_f32_16x16x32_bf16 v[34:37], v[176:179], v[214:217], v[34:37]
	v_mfma_f32_16x16x32_bf16 v[26:29], v[184:187], v[214:217], v[26:29]
	v_mfma_f32_16x16x32_bf16 v[18:21], v[176:179], v[222:225], v[18:21]
	v_mfma_f32_16x16x32_bf16 v[10:13], v[184:187], v[222:225], v[10:13]
	v_mfma_f32_16x16x32_bf16 v[6:9], v[176:179], v[230:233], v[6:9]
	v_mfma_f32_16x16x32_bf16 v[2:5], v[184:187], v[230:233], v[2:5]
	s_barrier
; #define PG8_STAGE(bufoff, gbase, voff) do { _Pragma("unroll") for (int _i = 0; _i < 2; ++_i) \
;         __builtin_amdgcn_global_load_lds((const unsigned*)((const char*)(gbase) + (voff)[_i]), (LAS unsigned*)(lds + (bufoff) + ldsw + _i * 8192), 16, 0, 0); } while (0)
; #define PG8_LDA(dst, b, h) do { _Pragma("unroll") for (int m = 0; m < 4; ++m) _Pragma("unroll") for (int k = 0; k < 2; ++k) dst[m][k] = *(const LAS bf16x8*)(lds + PG8_SA(b, h) + aoff + m * 2048 + k * 1024); } while (0)
; #define PG8_LDB(dst, b, h) do { _Pragma("unroll") for (int n = 0; n < 2; ++n) _Pragma("unroll") for (int k = 0; k < 2; ++k) dst[n][k] = *(const LAS bf16x8*)(lds + PG8_SB(b, h) + boff + n * 2048 + k * 1024); } while (0)
; #define PG8_MMA(ai, bj, At, Bt) do { __builtin_amdgcn_s_setprio(1); _Pragma("unroll") for (int m = 0; m < 4; ++m) _Pragma("unroll") for (int n = 0; n < 2; ++n) _Pragma("unroll") for (int k = 0; k < 2; ++k) \
;         acc[ai][bj][m][n] = __builtin_amdgcn_mfma_f32_16x16x32_bf16(Bt[n][k], At[m][k], acc[ai][bj][m][n], 0, 0, 0); __builtin_amdgcn_s_setprio(0); } while (0)
; #define PG8_WAIT_V(n) asm volatile("s_waitcnt vmcnt(" #n ")" ::: "memory")
; #define PG8_WAIT_L(n) asm volatile("s_waitcnt lgkmcnt(" #n ")" ::: "memory")
; #define PG8_BAR __builtin_amdgcn_s_barrier()
; #define PG8_SCHED __builtin_amdgcn_sched_barrier(0)
; template <class Epi, class Sched = StaticOrder, bool ALIGN_EPI = true>
; __device__ __forceinline__ void gemm_phase(LAS unsigned char* lds, const Gemm g, const Sched& S, const Epi& E) {
;     ...
;             PG8_LDB(B0, 1, 0); PG8_LDB(B1, 1, 1); PG8_SCHED; PG8_LDA(At, 1, 0); PG8_STAGE(PG8_SA(0, 1), a2 + hstep, voffA);
;             PG8_WAIT_V(8); PG8_WAIT_L(0); PG8_BAR; PG8_MMA(0, 0, At, B0); PG8_MMA(0, 1, At, B1); PG8_BAR; PG8_SCHED;
;             PG8_LDA(At, 1, 1); PG8_STAGE(PG8_SB(1, 0), b3, voffB); PG8_STAGE(PG8_SB(1, 1), b3 + hstep, voffB); PG8_STAGE(PG8_SA(1, 0), a3, voffA);
;             PG8_WAIT_V(8); PG8_WAIT_L(0); PG8_BAR; PG8_MMA(1, 0, At, B0); PG8_MMA(1, 1, At, B1); PG8_BAR; PG8_SCHED;
;         }
	s_add_i32 s33, 0, 0x18000
	v_add_u32_e32 v147, s33, v144
	s_add_i32 s70, 0, 0x1c000
	ds_read_b128 v[148:151], v147
	ds_read_b128 v[160:163], v147 offset:1024
	ds_read_b128 v[164:167], v147 offset:2048
	ds_read_b128 v[168:171], v147 offset:3072
	v_add_u32_e32 v147, s70, v144
	ds_read_b128 v[172:175], v147
	ds_read_b128 v[176:179], v147 offset:1024
	ds_read_b128 v[180:183], v147 offset:2048
	ds_read_b128 v[184:187], v147 offset:3072
	s_add_u32 s16, vcc_lo, 0x80000
	s_addc_u32 s17, vcc_hi, 0
	s_mov_b32 m0, s9
	v_lshl_add_u64 v[236:237], s[16:17], 0, v[136:137]
	ds_read_b128 v[188:191], v146 offset:32768
	ds_read_b128 v[192:195], v146 offset:33792
	ds_read_b128 v[210:213], v146 offset:34816
	ds_read_b128 v[214:217], v146 offset:35840
	ds_read_b128 v[218:221], v146 offset:36864
	ds_read_b128 v[222:225], v146 offset:37888
	ds_read_b128 v[226:229], v146 offset:38912
	ds_read_b128 v[230:233], v146 offset:39936
	global_load_lds_dwordx4 v[236:237], off
	s_mov_b32 m0, s10
	v_lshl_add_u64 v[236:237], s[16:17], 0, v[132:133]
	global_load_lds_dwordx4 v[236:237], off
	s_waitcnt vmcnt(8) lgkmcnt(0)
	s_barrier
	v_mfma_f32_16x16x32_bf16 v[126:129], v[148:151], v[188:191], v[126:129]
	v_mfma_f32_16x16x32_bf16 v[122:125], v[164:167], v[188:191], v[122:125]
	v_mfma_f32_16x16x32_bf16 v[118:121], v[148:151], v[210:213], v[118:121]
	v_mfma_f32_16x16x32_bf16 v[110:113], v[164:167], v[210:213], v[110:113]
	v_mfma_f32_16x16x32_bf16 v[102:105], v[148:151], v[218:221], v[102:105]
	v_mfma_f32_16x16x32_bf16 v[94:97], v[164:167], v[218:221], v[94:97]
	v_mfma_f32_16x16x32_bf16 v[82:85], v[148:151], v[226:229], v[82:85]
	v_mfma_f32_16x16x32_bf16 v[74:77], v[164:167], v[226:229], v[74:77]
	v_mfma_f32_16x16x32_bf16 v[126:129], v[160:163], v[192:195], v[126:129]
	v_mfma_f32_16x16x32_bf16 v[122:125], v[168:171], v[192:195], v[122:125]
	v_mfma_f32_16x16x32_bf16 v[118:121], v[160:163], v[214:217], v[118:121]
	v_mfma_f32_16x16x32_bf16 v[110:113], v[168:171], v[214:217], v[110:113]
	v_mfma_f32_16x16x32_bf16 v[102:105], v[160:163], v[222:225], v[102:105]
	v_mfma_f32_16x16x32_bf16 v[94:97], v[168:171], v[222:225], v[94:97]
	v_mfma_f32_16x16x32_bf16 v[82:85], v[160:163], v[230:233], v[82:85]
	v_mfma_f32_16x16x32_bf16 v[74:77], v[168:171], v[230:233], v[74:77]
	v_mfma_f32_16x16x32_bf16 v[114:117], v[172:175], v[188:191], v[114:117]
	v_mfma_f32_16x16x32_bf16 v[106:109], v[180:183], v[188:191], v[106:109]
	v_mfma_f32_16x16x32_bf16 v[98:101], v[172:175], v[210:213], v[98:101]
	v_mfma_f32_16x16x32_bf16 v[90:93], v[180:183], v[210:213], v[90:93]
	v_mfma_f32_16x16x32_bf16 v[86:89], v[172:175], v[218:221], v[86:89]
	v_mfma_f32_16x16x32_bf16 v[78:81], v[180:183], v[218:221], v[78:81]
	v_mfma_f32_16x16x32_bf16 v[70:73], v[172:175], v[226:229], v[70:73]
	v_mfma_f32_16x16x32_bf16 v[66:69], v[180:183], v[226:229], v[66:69]
	v_mfma_f32_16x16x32_bf16 v[114:117], v[176:179], v[192:195], v[114:117]
	v_mfma_f32_16x16x32_bf16 v[106:109], v[184:187], v[192:195], v[106:109]
	v_mfma_f32_16x16x32_bf16 v[98:101], v[176:179], v[214:217], v[98:101]
	v_mfma_f32_16x16x32_bf16 v[90:93], v[184:187], v[214:217], v[90:93]
	v_mfma_f32_16x16x32_bf16 v[86:89], v[176:179], v[222:225], v[86:89]
	v_mfma_f32_16x16x32_bf16 v[78:81], v[184:187], v[222:225], v[78:81]
	v_mfma_f32_16x16x32_bf16 v[70:73], v[176:179], v[230:233], v[70:73]
	v_mfma_f32_16x16x32_bf16 v[66:69], v[184:187], v[230:233], v[66:69]
	s_barrier
	s_add_i32 s16, s33, s5
	v_lshl_add_u64 v[142:143], v[142:143], 0, s[34:35]
	s_mov_b32 m0, s16
	ds_read_b128 v[188:191], v146 offset:49152
	ds_read_b128 v[192:195], v146 offset:50176
	ds_read_b128 v[210:213], v146 offset:51200
	ds_read_b128 v[214:217], v146 offset:52224
	ds_read_b128 v[218:221], v146 offset:53248
	ds_read_b128 v[222:225], v146 offset:54272
	ds_read_b128 v[226:229], v146 offset:55296
	ds_read_b128 v[230:233], v146 offset:56320
	global_load_lds_dwordx4 v[142:143], off
	s_add_i32 m0, s16, 0x2000
	s_add_u32 s16, s46, 0x80080
	v_lshl_add_u64 v[142:143], v[152:153], 0, s[34:35]
	s_addc_u32 s17, s47, 0
	s_add_i32 s33, s70, s5
	global_load_lds_dwordx4 v[142:143], off
	s_mov_b32 m0, s33
	v_lshl_add_u64 v[142:143], s[16:17], 0, v[134:135]
	global_load_lds_dwordx4 v[142:143], off
	s_add_i32 m0, s33, 0x2000
	v_lshl_add_u64 v[142:143], s[16:17], 0, v[130:131]
	global_load_lds_dwordx4 v[142:143], off
	s_mov_b32 m0, s11
	v_lshl_add_u64 v[142:143], v[196:197], 0, s[34:35]
	global_load_lds_dwordx4 v[142:143], off
	s_mov_b32 m0, s18
	v_lshl_add_u64 v[142:143], v[234:235], 0, s[34:35]
	global_load_lds_dwordx4 v[142:143], off
	s_waitcnt vmcnt(8) lgkmcnt(0)
	s_barrier
	v_mfma_f32_16x16x32_bf16 v[62:65], v[148:151], v[188:191], v[62:65]
	v_mfma_f32_16x16x32_bf16 v[58:61], v[164:167], v[188:191], v[58:61]
	v_mfma_f32_16x16x32_bf16 v[54:57], v[148:151], v[210:213], v[54:57]
	v_mfma_f32_16x16x32_bf16 v[46:49], v[164:167], v[210:213], v[46:49]
	v_mfma_f32_16x16x32_bf16 v[38:41], v[148:151], v[218:221], v[38:41]
	v_mfma_f32_16x16x32_bf16 v[30:33], v[164:167], v[218:221], v[30:33]
	v_mfma_f32_16x16x32_bf16 v[22:25], v[148:151], v[226:229], v[22:25]
	v_mfma_f32_16x16x32_bf16 v[14:17], v[164:167], v[226:229], v[14:17]
	v_mfma_f32_16x16x32_bf16 v[62:65], v[160:163], v[192:195], v[62:65]
	v_mfma_f32_16x16x32_bf16 v[58:61], v[168:171], v[192:195], v[58:61]
	v_mfma_f32_16x16x32_bf16 v[54:57], v[160:163], v[214:217], v[54:57]
	v_mfma_f32_16x16x32_bf16 v[46:49], v[168:171], v[214:217], v[46:49]
	v_mfma_f32_16x16x32_bf16 v[38:41], v[160:163], v[222:225], v[38:41]
	v_mfma_f32_16x16x32_bf16 v[30:33], v[168:171], v[222:225], v[30:33]
	v_mfma_f32_16x16x32_bf16 v[22:25], v[160:163], v[230:233], v[22:25]
	v_mfma_f32_16x16x32_bf16 v[14:17], v[168:171], v[230:233], v[14:17]
	v_mfma_f32_16x16x32_bf16 v[50:53], v[172:175], v[188:191], v[50:53]
	v_mfma_f32_16x16x32_bf16 v[42:45], v[180:183], v[188:191], v[42:45]
	v_mfma_f32_16x16x32_bf16 v[34:37], v[172:175], v[210:213], v[34:37]
	v_mfma_f32_16x16x32_bf16 v[26:29], v[180:183], v[210:213], v[26:29]
	v_mfma_f32_16x16x32_bf16 v[18:21], v[172:175], v[218:221], v[18:21]
	v_mfma_f32_16x16x32_bf16 v[10:13], v[180:183], v[218:221], v[10:13]
	v_mfma_f32_16x16x32_bf16 v[6:9], v[172:175], v[226:229], v[6:9]
	v_mfma_f32_16x16x32_bf16 v[2:5], v[180:183], v[226:229], v[2:5]
	v_mfma_f32_16x16x32_bf16 v[50:53], v[176:179], v[192:195], v[50:53]
	v_mfma_f32_16x16x32_bf16 v[42:45], v[184:187], v[192:195], v[42:45]
	v_mfma_f32_16x16x32_bf16 v[34:37], v[176:179], v[214:217], v[34:37]
	v_mfma_f32_16x16x32_bf16 v[26:29], v[184:187], v[214:217], v[26:29]
	v_mfma_f32_16x16x32_bf16 v[18:21], v[176:179], v[222:225], v[18:21]
	v_mfma_f32_16x16x32_bf16 v[10:13], v[184:187], v[222:225], v[10:13]
	v_mfma_f32_16x16x32_bf16 v[6:9], v[176:179], v[230:233], v[6:9]
	v_mfma_f32_16x16x32_bf16 v[2:5], v[184:187], v[230:233], v[2:5]
	s_barrier
	s_add_i32 s49, s49, 2
	s_add_u32 s80, s80, 0x100
	s_addc_u32 s81, s81, 0
	s_add_u32 s37, s37, 0x100
	s_addc_u32 s43, s43, 0
	s_cmp_gt_u32 s49, 29
	s_cbranch_scc0 .LBB0_106

; #define PG8_STAGE(bufoff, gbase, voff) do { _Pragma("unroll") for (int _i = 0; _i < 2; ++_i) \
;         __builtin_amdgcn_global_load_lds((const unsigned*)((const char*)(gbase) + (voff)[_i]), (LAS unsigned*)(lds + (bufoff) + ldsw + _i * 8192), 16, 0, 0); } while (0)
; #define PG8_LDA(dst, b, h) do { _Pragma("unroll") for (int m = 0; m < 4; ++m) _Pragma("unroll") for (int k = 0; k < 2; ++k) dst[m][k] = *(const LAS bf16x8*)(lds + PG8_SA(b, h) + aoff + m * 2048 + k * 1024); } while (0)
; #define PG8_LDB(dst, b, h) do { _Pragma("unroll") for (int n = 0; n < 2; ++n) _Pragma("unroll") for (int k = 0; k < 2; ++k) dst[n][k] = *(const LAS bf16x8*)(lds + PG8_SB(b, h) + boff + n * 2048 + k * 1024); } while (0)
; #define PG8_MMA(ai, bj, At, Bt) do { __builtin_amdgcn_s_setprio(1); _Pragma("unroll") for (int m = 0; m < 4; ++m) _Pragma("unroll") for (int n = 0; n < 2; ++n) _Pragma("unroll") for (int k = 0; k < 2; ++k) \
;         acc[ai][bj][m][n] = __builtin_amdgcn_mfma_f32_16x16x32_bf16(Bt[n][k], At[m][k], acc[ai][bj][m][n], 0, 0, 0); __builtin_amdgcn_s_setprio(0); } while (0)
; #define PG8_WAIT_V(n) asm volatile("s_waitcnt vmcnt(" #n ")" ::: "memory")
; #define PG8_WAIT_L(n) asm volatile("s_waitcnt lgkmcnt(" #n ")" ::: "memory")
; #define PG8_BAR __builtin_amdgcn_s_barrier()
; #define PG8_SCHED __builtin_amdgcn_sched_barrier(0)
; template <class Epi, class Sched = StaticOrder, bool ALIGN_EPI = true>
; __device__ __forceinline__ void gemm_phase(LAS unsigned char* lds, const Gemm g, const Sched& S, const Epi& E) {
;     ...
;             PG8_LDB(B0, 0, 0); PG8_LDB(B1, 0, 1); PG8_SCHED; PG8_LDA(At, 0, 0); PG8_STAGE(PG8_SA(1, 1), a1 + hstep, voffA);
;             PG8_WAIT_V(8); PG8_WAIT_L(0); PG8_BAR; PG8_MMA(0, 0, At, B0); PG8_MMA(0, 1, At, B1); PG8_BAR; PG8_SCHED;
;             PG8_LDA(At, 0, 1); PG8_STAGE(PG8_SB(0, 0), b2, voffB); PG8_STAGE(PG8_SB(0, 1), b2 + hstep, voffB); PG8_STAGE(PG8_SA(0, 0), a2, voffA);
;             PG8_WAIT_V(8); PG8_WAIT_L(0); PG8_BAR; PG8_MMA(1, 0, At, B0); PG8_MMA(1, 1, At, B1); PG8_BAR; PG8_SCHED;
;     ...
;         for (int a = 0; a < 2; ++a)
; #pragma unroll
;             for (int b = 0; b < 2; ++b)
; #pragma unroll
;                 for (int m = 0; m < 4; ++m)
; #pragma unroll
;                     for (int n = 0; n < 2; ++n) acc[a][b][m][n] = (f32x4){0.f, 0.f, 0.f, 0.f};
.Lmy_nb_336:
	s_add_u32 s0, s80, 0xfff80080
	s_addc_u32 s1, s81, -1
	s_add_i32 s16, 0, 0x10000
	s_cmp_eq_u32 s79, 28
	s_cselect_b32 s31, s36, s1
	s_cselect_b32 s30, s37, s0
	v_add_u32_e32 v142, s16, v144
	s_cselect_b32 s1, s21, s70
	s_cselect_b32 s0, s43, s49
	s_add_i32 s33, 0, 0x14000
	ds_read_b128 v[148:151], v142
	ds_read_b128 v[160:163], v142 offset:1024
	ds_read_b128 v[164:167], v142 offset:2048
	ds_read_b128 v[168:171], v142 offset:3072
	v_add_u32_e32 v142, s33, v144
	ds_read_b128 v[172:175], v142
	ds_read_b128 v[176:179], v142 offset:1024
	ds_read_b128 v[180:183], v142 offset:2048
	ds_read_b128 v[184:187], v142 offset:3072
	v_lshl_add_u64 v[142:143], s[80:81], 0, v[138:139]
	s_add_i32 m0, s7, 0xc000
	ds_read_b128 v[188:191], v146
	ds_read_b128 v[192:195], v146 offset:1024
	ds_read_b128 v[210:213], v146 offset:2048
	ds_read_b128 v[214:217], v146 offset:3072
	ds_read_b128 v[218:221], v146 offset:4096
	ds_read_b128 v[222:225], v146 offset:5120
	ds_read_b128 v[226:229], v146 offset:6144
	ds_read_b128 v[230:233], v146 offset:7168
	global_load_lds_dwordx4 v[142:143], off
	s_add_i32 m0, s7, 0xe000
	v_lshl_add_u64 v[142:143], s[80:81], 0, v[140:141]
	global_load_lds_dwordx4 v[142:143], off
	s_waitcnt vmcnt(8) lgkmcnt(0)
	s_barrier
	v_mfma_f32_16x16x32_bf16 v[126:129], v[148:151], v[188:191], 0
	v_mfma_f32_16x16x32_bf16 v[122:125], v[164:167], v[188:191], 0
	v_mfma_f32_16x16x32_bf16 v[118:121], v[148:151], v[210:213], 0
	v_mfma_f32_16x16x32_bf16 v[110:113], v[164:167], v[210:213], 0
	v_mfma_f32_16x16x32_bf16 v[102:105], v[148:151], v[218:221], 0
	v_mfma_f32_16x16x32_bf16 v[94:97], v[164:167], v[218:221], 0
	v_mfma_f32_16x16x32_bf16 v[86:89], v[148:151], v[226:229], 0
	v_mfma_f32_16x16x32_bf16 v[78:81], v[164:167], v[226:229], 0
	v_mfma_f32_16x16x32_bf16 v[126:129], v[160:163], v[192:195], v[126:129]
	v_mfma_f32_16x16x32_bf16 v[122:125], v[168:171], v[192:195], v[122:125]
	v_mfma_f32_16x16x32_bf16 v[118:121], v[160:163], v[214:217], v[118:121]
	v_mfma_f32_16x16x32_bf16 v[110:113], v[168:171], v[214:217], v[110:113]
	v_mfma_f32_16x16x32_bf16 v[102:105], v[160:163], v[222:225], v[102:105]
	v_mfma_f32_16x16x32_bf16 v[94:97], v[168:171], v[222:225], v[94:97]
	v_mfma_f32_16x16x32_bf16 v[86:89], v[160:163], v[230:233], v[86:89]
	v_mfma_f32_16x16x32_bf16 v[78:81], v[168:171], v[230:233], v[78:81]
	v_mfma_f32_16x16x32_bf16 v[114:117], v[172:175], v[188:191], 0
	v_mfma_f32_16x16x32_bf16 v[106:109], v[180:183], v[188:191], 0
	v_mfma_f32_16x16x32_bf16 v[98:101], v[172:175], v[210:213], 0
	v_mfma_f32_16x16x32_bf16 v[90:93], v[180:183], v[210:213], 0
	v_mfma_f32_16x16x32_bf16 v[82:85], v[172:175], v[218:221], 0
	v_mfma_f32_16x16x32_bf16 v[74:77], v[180:183], v[218:221], 0
	v_mfma_f32_16x16x32_bf16 v[70:73], v[172:175], v[226:229], 0
	v_mfma_f32_16x16x32_bf16 v[66:69], v[180:183], v[226:229], 0
	v_mfma_f32_16x16x32_bf16 v[114:117], v[176:179], v[192:195], v[114:117]
	v_mfma_f32_16x16x32_bf16 v[106:109], v[184:187], v[192:195], v[106:109]
	v_mfma_f32_16x16x32_bf16 v[98:101], v[176:179], v[214:217], v[98:101]
	v_mfma_f32_16x16x32_bf16 v[90:93], v[184:187], v[214:217], v[90:93]
	v_mfma_f32_16x16x32_bf16 v[82:85], v[176:179], v[222:225], v[82:85]
	v_mfma_f32_16x16x32_bf16 v[74:77], v[184:187], v[222:225], v[74:77]
	v_mfma_f32_16x16x32_bf16 v[70:73], v[176:179], v[230:233], v[70:73]
	v_mfma_f32_16x16x32_bf16 v[66:69], v[184:187], v[230:233], v[66:69]
	s_barrier
	s_add_i32 s16, s16, s5
	v_lshl_add_u64 v[142:143], s[0:1], 0, v[134:135]
	s_mov_b32 m0, s16
	ds_read_b128 v[188:191], v146 offset:16384
	ds_read_b128 v[192:195], v146 offset:17408
	ds_read_b128 v[210:213], v146 offset:18432
	ds_read_b128 v[214:217], v146 offset:19456
	ds_read_b128 v[218:221], v146 offset:20480
	ds_read_b128 v[222:225], v146 offset:21504
	ds_read_b128 v[226:229], v146 offset:22528
	ds_read_b128 v[230:233], v146 offset:23552
	global_load_lds_dwordx4 v[142:143], off
	s_add_i32 m0, s16, 0x2000
	s_add_u32 s16, s0, 0x80000
	v_lshl_add_u64 v[152:153], s[0:1], 0, v[130:131]
	s_addc_u32 s17, s1, 0
	s_add_i32 s33, s33, s5
	global_load_lds_dwordx4 v[152:153], off
	v_lshl_add_u64 v[196:197], s[16:17], 0, v[134:135]
	s_mov_b32 m0, s33
	v_lshl_add_u64 v[234:235], s[30:31], 0, v[132:133]
	global_load_lds_dwordx4 v[196:197], off
	s_add_i32 m0, s33, 0x2000
	v_lshl_add_u64 v[196:197], s[16:17], 0, v[130:131]
	global_load_lds_dwordx4 v[196:197], off
	s_mov_b32 m0, s7
	v_lshl_add_u64 v[196:197], s[30:31], 0, v[136:137]
	global_load_lds_dwordx4 v[196:197], off
	s_mov_b32 m0, s8
	s_nop 0
	global_load_lds_dwordx4 v[234:235], off
	s_waitcnt vmcnt(8) lgkmcnt(0)
	s_barrier
	v_mfma_f32_16x16x32_bf16 v[62:65], v[148:151], v[188:191], 0
	v_mfma_f32_16x16x32_bf16 v[58:61], v[164:167], v[188:191], 0
	v_mfma_f32_16x16x32_bf16 v[54:57], v[148:151], v[210:213], 0
	v_mfma_f32_16x16x32_bf16 v[46:49], v[164:167], v[210:213], 0
	v_mfma_f32_16x16x32_bf16 v[38:41], v[148:151], v[218:221], 0
	v_mfma_f32_16x16x32_bf16 v[30:33], v[164:167], v[218:221], 0
	v_mfma_f32_16x16x32_bf16 v[22:25], v[148:151], v[226:229], 0
	v_mfma_f32_16x16x32_bf16 v[14:17], v[164:167], v[226:229], 0
	v_mfma_f32_16x16x32_bf16 v[62:65], v[160:163], v[192:195], v[62:65]
	v_mfma_f32_16x16x32_bf16 v[58:61], v[168:171], v[192:195], v[58:61]
	v_mfma_f32_16x16x32_bf16 v[54:57], v[160:163], v[214:217], v[54:57]
	v_mfma_f32_16x16x32_bf16 v[46:49], v[168:171], v[214:217], v[46:49]
	v_mfma_f32_16x16x32_bf16 v[38:41], v[160:163], v[222:225], v[38:41]
	v_mfma_f32_16x16x32_bf16 v[30:33], v[168:171], v[222:225], v[30:33]
	v_mfma_f32_16x16x32_bf16 v[22:25], v[160:163], v[230:233], v[22:25]
	v_mfma_f32_16x16x32_bf16 v[14:17], v[168:171], v[230:233], v[14:17]
	v_mfma_f32_16x16x32_bf16 v[50:53], v[172:175], v[188:191], 0
	v_mfma_f32_16x16x32_bf16 v[42:45], v[180:183], v[188:191], 0
	v_mfma_f32_16x16x32_bf16 v[34:37], v[172:175], v[210:213], 0
	v_mfma_f32_16x16x32_bf16 v[26:29], v[180:183], v[210:213], 0
	v_mfma_f32_16x16x32_bf16 v[18:21], v[172:175], v[218:221], 0
	v_mfma_f32_16x16x32_bf16 v[10:13], v[180:183], v[218:221], 0
	v_mfma_f32_16x16x32_bf16 v[6:9], v[172:175], v[226:229], 0
	v_mfma_f32_16x16x32_bf16 v[2:5], v[180:183], v[226:229], 0
	v_mfma_f32_16x16x32_bf16 v[50:53], v[176:179], v[192:195], v[50:53]
	v_mfma_f32_16x16x32_bf16 v[42:45], v[184:187], v[192:195], v[42:45]
	v_mfma_f32_16x16x32_bf16 v[34:37], v[176:179], v[214:217], v[34:37]
	v_mfma_f32_16x16x32_bf16 v[26:29], v[184:187], v[214:217], v[26:29]
	v_mfma_f32_16x16x32_bf16 v[18:21], v[176:179], v[222:225], v[18:21]
	v_mfma_f32_16x16x32_bf16 v[10:13], v[184:187], v[222:225], v[10:13]
	v_mfma_f32_16x16x32_bf16 v[6:9], v[176:179], v[230:233], v[6:9]
	v_mfma_f32_16x16x32_bf16 v[2:5], v[184:187], v[230:233], v[2:5]
	s_barrier
; #define PG8_STAGE(bufoff, gbase, voff) do { _Pragma("unroll") for (int _i = 0; _i < 2; ++_i) \
;         __builtin_amdgcn_global_load_lds((const unsigned*)((const char*)(gbase) + (voff)[_i]), (LAS unsigned*)(lds + (bufoff) + ldsw + _i * 8192), 16, 0, 0); } while (0)
; #define PG8_LDA(dst, b, h) do { _Pragma("unroll") for (int m = 0; m < 4; ++m) _Pragma("unroll") for (int k = 0; k < 2; ++k) dst[m][k] = *(const LAS bf16x8*)(lds + PG8_SA(b, h) + aoff + m * 2048 + k * 1024); } while (0)
; #define PG8_LDB(dst, b, h) do { _Pragma("unroll") for (int n = 0; n < 2; ++n) _Pragma("unroll") for (int k = 0; k < 2; ++k) dst[n][k] = *(const LAS bf16x8*)(lds + PG8_SB(b, h) + boff + n * 2048 + k * 1024); } while (0)
; #define PG8_MMA(ai, bj, At, Bt) do { __builtin_amdgcn_s_setprio(1); _Pragma("unroll") for (int m = 0; m < 4; ++m) _Pragma("unroll") for (int n = 0; n < 2; ++n) _Pragma("unroll") for (int k = 0; k < 2; ++k) \
;         acc[ai][bj][m][n] = __builtin_amdgcn_mfma_f32_16x16x32_bf16(Bt[n][k], At[m][k], acc[ai][bj][m][n], 0, 0, 0); __builtin_amdgcn_s_setprio(0); } while (0)
; #define PG8_WAIT_V(n) asm volatile("s_waitcnt vmcnt(" #n ")" ::: "memory")
; #define PG8_WAIT_L(n) asm volatile("s_waitcnt lgkmcnt(" #n ")" ::: "memory")
; #define PG8_BAR __builtin_amdgcn_s_barrier()
; #define PG8_SCHED __builtin_amdgcn_sched_barrier(0)
; template <class Epi, class Sched = StaticOrder, bool ALIGN_EPI = true>
; __device__ __forceinline__ void gemm_phase(LAS unsigned char* lds, const Gemm g, const Sched& S, const Epi& E) {
;     ...
;             PG8_LDB(B0, 1, 0); PG8_LDB(B1, 1, 1); PG8_SCHED; PG8_LDA(At, 1, 0); PG8_STAGE(PG8_SA(0, 1), a2 + hstep, voffA);
;             PG8_WAIT_V(8); PG8_WAIT_L(0); PG8_BAR; PG8_MMA(0, 0, At, B0); PG8_MMA(0, 1, At, B1); PG8_BAR; PG8_SCHED;
;             PG8_LDA(At, 1, 1); PG8_STAGE(PG8_SB(1, 0), b3, voffB); PG8_STAGE(PG8_SB(1, 1), b3 + hstep, voffB); PG8_STAGE(PG8_SA(1, 0), a3, voffA);
;             PG8_WAIT_V(8); PG8_WAIT_L(0); PG8_BAR; PG8_MMA(1, 0, At, B0); PG8_MMA(1, 1, At, B1); PG8_BAR; PG8_SCHED;
;         }
	s_add_i32 s33, 0, 0x18000
	v_add_u32_e32 v147, s33, v144
	s_add_i32 s82, 0, 0x1c000
	ds_read_b128 v[148:151], v147
	ds_read_b128 v[160:163], v147 offset:1024
	ds_read_b128 v[164:167], v147 offset:2048
	ds_read_b128 v[168:171], v147 offset:3072
	v_add_u32_e32 v147, s82, v144
	ds_read_b128 v[172:175], v147
	ds_read_b128 v[176:179], v147 offset:1024
	ds_read_b128 v[180:183], v147 offset:2048
	ds_read_b128 v[184:187], v147 offset:3072
	s_add_u32 s16, s30, 0x80000
	s_addc_u32 s17, s31, 0
	s_mov_b32 m0, s9
	v_lshl_add_u64 v[236:237], s[16:17], 0, v[136:137]
	ds_read_b128 v[188:191], v146 offset:32768
	ds_read_b128 v[192:195], v146 offset:33792
	ds_read_b128 v[210:213], v146 offset:34816
	ds_read_b128 v[214:217], v146 offset:35840
	ds_read_b128 v[218:221], v146 offset:36864
	ds_read_b128 v[222:225], v146 offset:37888
	ds_read_b128 v[226:229], v146 offset:38912
	ds_read_b128 v[230:233], v146 offset:39936
	global_load_lds_dwordx4 v[236:237], off
	s_mov_b32 m0, s10
	v_lshl_add_u64 v[236:237], s[16:17], 0, v[132:133]
	global_load_lds_dwordx4 v[236:237], off
	s_waitcnt vmcnt(8) lgkmcnt(0)
	s_barrier
	v_mfma_f32_16x16x32_bf16 v[126:129], v[148:151], v[188:191], v[126:129]
	v_mfma_f32_16x16x32_bf16 v[122:125], v[164:167], v[188:191], v[122:125]
	v_mfma_f32_16x16x32_bf16 v[118:121], v[148:151], v[210:213], v[118:121]
	v_mfma_f32_16x16x32_bf16 v[110:113], v[164:167], v[210:213], v[110:113]
	v_mfma_f32_16x16x32_bf16 v[102:105], v[148:151], v[218:221], v[102:105]
	v_mfma_f32_16x16x32_bf16 v[94:97], v[164:167], v[218:221], v[94:97]
	v_mfma_f32_16x16x32_bf16 v[86:89], v[148:151], v[226:229], v[86:89]
	v_mfma_f32_16x16x32_bf16 v[78:81], v[164:167], v[226:229], v[78:81]
	v_mfma_f32_16x16x32_bf16 v[126:129], v[160:163], v[192:195], v[126:129]
	v_mfma_f32_16x16x32_bf16 v[122:125], v[168:171], v[192:195], v[122:125]
	v_mfma_f32_16x16x32_bf16 v[118:121], v[160:163], v[214:217], v[118:121]
	v_mfma_f32_16x16x32_bf16 v[110:113], v[168:171], v[214:217], v[110:113]
	v_mfma_f32_16x16x32_bf16 v[102:105], v[160:163], v[222:225], v[102:105]
	v_mfma_f32_16x16x32_bf16 v[94:97], v[168:171], v[222:225], v[94:97]
	v_mfma_f32_16x16x32_bf16 v[86:89], v[160:163], v[230:233], v[86:89]
	v_mfma_f32_16x16x32_bf16 v[78:81], v[168:171], v[230:233], v[78:81]
	v_mfma_f32_16x16x32_bf16 v[114:117], v[172:175], v[188:191], v[114:117]
	v_mfma_f32_16x16x32_bf16 v[106:109], v[180:183], v[188:191], v[106:109]
	v_mfma_f32_16x16x32_bf16 v[98:101], v[172:175], v[210:213], v[98:101]
	v_mfma_f32_16x16x32_bf16 v[90:93], v[180:183], v[210:213], v[90:93]
	v_mfma_f32_16x16x32_bf16 v[82:85], v[172:175], v[218:221], v[82:85]
	v_mfma_f32_16x16x32_bf16 v[74:77], v[180:183], v[218:221], v[74:77]
	v_mfma_f32_16x16x32_bf16 v[70:73], v[172:175], v[226:229], v[70:73]
	v_mfma_f32_16x16x32_bf16 v[66:69], v[180:183], v[226:229], v[66:69]
	v_mfma_f32_16x16x32_bf16 v[114:117], v[176:179], v[192:195], v[114:117]
	v_mfma_f32_16x16x32_bf16 v[106:109], v[184:187], v[192:195], v[106:109]
	v_mfma_f32_16x16x32_bf16 v[98:101], v[176:179], v[214:217], v[98:101]
	v_mfma_f32_16x16x32_bf16 v[90:93], v[184:187], v[214:217], v[90:93]
	v_mfma_f32_16x16x32_bf16 v[82:85], v[176:179], v[222:225], v[82:85]
	v_mfma_f32_16x16x32_bf16 v[74:77], v[184:187], v[222:225], v[74:77]
	v_mfma_f32_16x16x32_bf16 v[70:73], v[176:179], v[230:233], v[70:73]
	v_mfma_f32_16x16x32_bf16 v[66:69], v[184:187], v[230:233], v[66:69]
	s_barrier
	s_add_i32 s16, s33, s5
	v_lshl_add_u64 v[142:143], v[142:143], 0, s[34:35]
	s_mov_b32 m0, s16
	ds_read_b128 v[188:191], v146 offset:49152
	ds_read_b128 v[192:195], v146 offset:50176
	ds_read_b128 v[210:213], v146 offset:51200
	ds_read_b128 v[214:217], v146 offset:52224
	ds_read_b128 v[218:221], v146 offset:53248
	ds_read_b128 v[222:225], v146 offset:54272
	ds_read_b128 v[226:229], v146 offset:55296
	ds_read_b128 v[230:233], v146 offset:56320
	global_load_lds_dwordx4 v[142:143], off
	s_add_i32 m0, s16, 0x2000
	s_add_u32 s0, s0, 0x80080
	v_lshl_add_u64 v[142:143], v[152:153], 0, s[34:35]
	s_addc_u32 s1, s1, 0
	s_add_i32 s16, s82, s5
	global_load_lds_dwordx4 v[142:143], off
	s_mov_b32 m0, s16
	v_lshl_add_u64 v[142:143], s[0:1], 0, v[134:135]
	global_load_lds_dwordx4 v[142:143], off
	s_add_i32 m0, s16, 0x2000
	v_lshl_add_u64 v[142:143], s[0:1], 0, v[130:131]
	global_load_lds_dwordx4 v[142:143], off
	s_mov_b32 m0, s11
	v_lshl_add_u64 v[142:143], v[196:197], 0, s[34:35]
	global_load_lds_dwordx4 v[142:143], off
	s_mov_b32 m0, s18
	v_lshl_add_u64 v[142:143], v[234:235], 0, s[34:35]
	global_load_lds_dwordx4 v[142:143], off
	s_waitcnt vmcnt(8) lgkmcnt(0)
	s_barrier
	v_mfma_f32_16x16x32_bf16 v[62:65], v[148:151], v[188:191], v[62:65]
	v_mfma_f32_16x16x32_bf16 v[58:61], v[164:167], v[188:191], v[58:61]
	v_mfma_f32_16x16x32_bf16 v[54:57], v[148:151], v[210:213], v[54:57]
	v_mfma_f32_16x16x32_bf16 v[46:49], v[164:167], v[210:213], v[46:49]
	v_mfma_f32_16x16x32_bf16 v[38:41], v[148:151], v[218:221], v[38:41]
	v_mfma_f32_16x16x32_bf16 v[30:33], v[164:167], v[218:221], v[30:33]
	v_mfma_f32_16x16x32_bf16 v[22:25], v[148:151], v[226:229], v[22:25]
	v_mfma_f32_16x16x32_bf16 v[14:17], v[164:167], v[226:229], v[14:17]
	v_mfma_f32_16x16x32_bf16 v[62:65], v[160:163], v[192:195], v[62:65]
	v_mfma_f32_16x16x32_bf16 v[58:61], v[168:171], v[192:195], v[58:61]
	v_mfma_f32_16x16x32_bf16 v[54:57], v[160:163], v[214:217], v[54:57]
	v_mfma_f32_16x16x32_bf16 v[46:49], v[168:171], v[214:217], v[46:49]
	v_mfma_f32_16x16x32_bf16 v[38:41], v[160:163], v[222:225], v[38:41]
	v_mfma_f32_16x16x32_bf16 v[30:33], v[168:171], v[222:225], v[30:33]
	v_mfma_f32_16x16x32_bf16 v[22:25], v[160:163], v[230:233], v[22:25]
	v_mfma_f32_16x16x32_bf16 v[14:17], v[168:171], v[230:233], v[14:17]
	v_mfma_f32_16x16x32_bf16 v[50:53], v[172:175], v[188:191], v[50:53]
	v_mfma_f32_16x16x32_bf16 v[42:45], v[180:183], v[188:191], v[42:45]
	v_mfma_f32_16x16x32_bf16 v[34:37], v[172:175], v[210:213], v[34:37]
	v_mfma_f32_16x16x32_bf16 v[26:29], v[180:183], v[210:213], v[26:29]
	v_mfma_f32_16x16x32_bf16 v[18:21], v[172:175], v[218:221], v[18:21]
	v_mfma_f32_16x16x32_bf16 v[10:13], v[180:183], v[218:221], v[10:13]
	v_mfma_f32_16x16x32_bf16 v[6:9], v[172:175], v[226:229], v[6:9]
	v_mfma_f32_16x16x32_bf16 v[2:5], v[180:183], v[226:229], v[2:5]
	v_mfma_f32_16x16x32_bf16 v[50:53], v[176:179], v[192:195], v[50:53]
	v_mfma_f32_16x16x32_bf16 v[42:45], v[184:187], v[192:195], v[42:45]
	v_mfma_f32_16x16x32_bf16 v[34:37], v[176:179], v[214:217], v[34:37]
	v_mfma_f32_16x16x32_bf16 v[26:29], v[184:187], v[214:217], v[26:29]
	v_mfma_f32_16x16x32_bf16 v[18:21], v[176:179], v[222:225], v[18:21]
	v_mfma_f32_16x16x32_bf16 v[10:13], v[184:187], v[222:225], v[10:13]
	v_mfma_f32_16x16x32_bf16 v[6:9], v[176:179], v[230:233], v[6:9]
	v_mfma_f32_16x16x32_bf16 v[2:5], v[184:187], v[230:233], v[2:5]
	s_barrier
	s_add_i32 s79, s79, 2
	s_add_u32 s80, s80, 0x100
	s_addc_u32 s81, s81, 0
	s_add_u32 s49, s49, 0x100
	s_addc_u32 s70, s70, 0
	s_cmp_gt_u32 s79, 29
	s_cbranch_scc0 .LBB0_336
;     __device__ bool next(int i, Unit& u) const { const int idx = i * G + c; if (idx >= 64) return false; u.kp = idx & 3; u.pn = (idx >> 2) & 7; u.pm = 192 + (idx >> 5); return true; }
; #define PG8_STAGE(bufoff, gbase, voff) do { _Pragma("unroll") for (int _i = 0; _i < 2; ++_i) \
;         __builtin_amdgcn_global_load_lds((const unsigned*)((const char*)(gbase) + (voff)[_i]), (LAS unsigned*)(lds + (bufoff) + ldsw + _i * 8192), 16, 0, 0); } while (0)
; #define PG8_LDA(dst, b, h) do { _Pragma("unroll") for (int m = 0; m < 4; ++m) _Pragma("unroll") for (int k = 0; k < 2; ++k) dst[m][k] = *(const LAS bf16x8*)(lds + PG8_SA(b, h) + aoff + m * 2048 + k * 1024); } while (0)
; #define PG8_LDB(dst, b, h) do { _Pragma("unroll") for (int n = 0; n < 2; ++n) _Pragma("unroll") for (int k = 0; k < 2; ++k) dst[n][k] = *(const LAS bf16x8*)(lds + PG8_SB(b, h) + boff + n * 2048 + k * 1024); } while (0)
; #define PG8_WAIT_V(n) asm volatile("s_waitcnt vmcnt(" #n ")" ::: "memory")
; #define PG8_WAIT_L(n) asm volatile("s_waitcnt lgkmcnt(" #n ")" ::: "memory")
; template <class Epi, class Sched = StaticOrder, bool ALIGN_EPI = true>
; __device__ __forceinline__ void gemm_phase(LAS unsigned char* lds, const Gemm g, const Sched& S, const Epi& E) {
;     ...
;         const bool has_next = S.next(ui + 1, nxt);
;         const char* nA = has_next ? (const char*)g.A + (size_t)nxt.pm * tstep + (size_t)nxt.kp * K * 2 : cA; const char* nB = has_next ? (const char*)g.Bt + (size_t)nxt.pn * tstep + (size_t)nxt.kp * K * 2 : cB;
;         for (int t = 0; t < nt; t += 2) {
;             const bool last = (t == nt - 2);
;             const char* a1 = cA + (size_t)(t + 1) * kstep;
;             const char* a2 = last ? nA : cA + (size_t)(t + 2) * kstep; const char* b2 = last ? nB : cB + (size_t)(t + 2) * kstep;
;             const char* a3 = a2 + kstep; const char* b3 = b2 + kstep;
;             PG8_LDB(B0, 0, 0); PG8_LDB(B1, 0, 1); PG8_SCHED; PG8_LDA(At, 0, 0); PG8_STAGE(PG8_SA(1, 1), a1 + hstep, voffA);
;             PG8_WAIT_V(8); PG8_WAIT_L(0); PG8_BAR; PG8_MMA(0, 0, At, B0); PG8_MMA(0, 1, At, B1); PG8_BAR; PG8_SCHED;
;             PG8_LDA(At, 0, 1); PG8_STAGE(PG8_SB(0, 0), b2, voffB); PG8_STAGE(PG8_SB(0, 1), b2 + hstep, voffB); PG8_STAGE(PG8_SA(0, 0), a2, voffA);
;             PG8_WAIT_V(8); PG8_WAIT_L(0); PG8_BAR; PG8_MMA(1, 0, At, B0); PG8_MMA(1, 1, At, B1); PG8_BAR; PG8_SCHED;
.LBB0_336:
	s_add_u32 s0, s80, 0xfff80080
	s_addc_u32 s1, s81, -1
	s_add_i32 s16, 0, 0x10000
	s_cmp_eq_u32 s79, 28
	s_cselect_b32 s31, s36, s1
	s_cselect_b32 s30, s37, s0
	v_add_u32_e32 v142, s16, v144
	s_cselect_b32 s1, s21, s70
	s_cselect_b32 s0, s43, s49
	s_add_i32 s33, 0, 0x14000
	ds_read_b128 v[148:151], v142
	ds_read_b128 v[160:163], v142 offset:1024
	ds_read_b128 v[164:167], v142 offset:2048
	ds_read_b128 v[168:171], v142 offset:3072
	v_add_u32_e32 v142, s33, v144
	ds_read_b128 v[172:175], v142
	ds_read_b128 v[176:179], v142 offset:1024
	ds_read_b128 v[180:183], v142 offset:2048
	ds_read_b128 v[184:187], v142 offset:3072
	v_lshl_add_u64 v[142:143], s[80:81], 0, v[138:139]
	s_add_i32 m0, s7, 0xc000
	ds_read_b128 v[188:191], v146
	ds_read_b128 v[192:195], v146 offset:1024
	ds_read_b128 v[210:213], v146 offset:2048
	ds_read_b128 v[214:217], v146 offset:3072
	ds_read_b128 v[218:221], v146 offset:4096
	ds_read_b128 v[222:225], v146 offset:5120
	ds_read_b128 v[226:229], v146 offset:6144
	ds_read_b128 v[230:233], v146 offset:7168
	global_load_lds_dwordx4 v[142:143], off
	s_add_i32 m0, s7, 0xe000
	v_lshl_add_u64 v[142:143], s[80:81], 0, v[140:141]
	global_load_lds_dwordx4 v[142:143], off
	s_waitcnt vmcnt(8) lgkmcnt(0)
	s_barrier
	v_mfma_f32_16x16x32_bf16 v[126:129], v[148:151], v[188:191], v[126:129]
	v_mfma_f32_16x16x32_bf16 v[122:125], v[164:167], v[188:191], v[122:125]
	v_mfma_f32_16x16x32_bf16 v[118:121], v[148:151], v[210:213], v[118:121]
	v_mfma_f32_16x16x32_bf16 v[110:113], v[164:167], v[210:213], v[110:113]
	v_mfma_f32_16x16x32_bf16 v[102:105], v[148:151], v[218:221], v[102:105]
	v_mfma_f32_16x16x32_bf16 v[94:97], v[164:167], v[218:221], v[94:97]
	v_mfma_f32_16x16x32_bf16 v[86:89], v[148:151], v[226:229], v[86:89]
	v_mfma_f32_16x16x32_bf16 v[78:81], v[164:167], v[226:229], v[78:81]
	v_mfma_f32_16x16x32_bf16 v[126:129], v[160:163], v[192:195], v[126:129]
	v_mfma_f32_16x16x32_bf16 v[122:125], v[168:171], v[192:195], v[122:125]
	v_mfma_f32_16x16x32_bf16 v[118:121], v[160:163], v[214:217], v[118:121]
	v_mfma_f32_16x16x32_bf16 v[110:113], v[168:171], v[214:217], v[110:113]
	v_mfma_f32_16x16x32_bf16 v[102:105], v[160:163], v[222:225], v[102:105]
	v_mfma_f32_16x16x32_bf16 v[94:97], v[168:171], v[222:225], v[94:97]
	v_mfma_f32_16x16x32_bf16 v[86:89], v[160:163], v[230:233], v[86:89]
	v_mfma_f32_16x16x32_bf16 v[78:81], v[168:171], v[230:233], v[78:81]
	v_mfma_f32_16x16x32_bf16 v[114:117], v[172:175], v[188:191], v[114:117]
	v_mfma_f32_16x16x32_bf16 v[106:109], v[180:183], v[188:191], v[106:109]
	v_mfma_f32_16x16x32_bf16 v[98:101], v[172:175], v[210:213], v[98:101]
	v_mfma_f32_16x16x32_bf16 v[90:93], v[180:183], v[210:213], v[90:93]
	v_mfma_f32_16x16x32_bf16 v[82:85], v[172:175], v[218:221], v[82:85]
	v_mfma_f32_16x16x32_bf16 v[74:77], v[180:183], v[218:221], v[74:77]
	v_mfma_f32_16x16x32_bf16 v[70:73], v[172:175], v[226:229], v[70:73]
	v_mfma_f32_16x16x32_bf16 v[66:69], v[180:183], v[226:229], v[66:69]
	v_mfma_f32_16x16x32_bf16 v[114:117], v[176:179], v[192:195], v[114:117]
	v_mfma_f32_16x16x32_bf16 v[106:109], v[184:187], v[192:195], v[106:109]
	v_mfma_f32_16x16x32_bf16 v[98:101], v[176:179], v[214:217], v[98:101]
	v_mfma_f32_16x16x32_bf16 v[90:93], v[184:187], v[214:217], v[90:93]
	v_mfma_f32_16x16x32_bf16 v[82:85], v[176:179], v[222:225], v[82:85]
	v_mfma_f32_16x16x32_bf16 v[74:77], v[184:187], v[222:225], v[74:77]
	v_mfma_f32_16x16x32_bf16 v[70:73], v[176:179], v[230:233], v[70:73]
	v_mfma_f32_16x16x32_bf16 v[66:69], v[184:187], v[230:233], v[66:69]
	s_barrier
	s_add_i32 s16, s16, s5
	v_lshl_add_u64 v[142:143], s[0:1], 0, v[134:135]
	s_mov_b32 m0, s16
	ds_read_b128 v[188:191], v146 offset:16384
	ds_read_b128 v[192:195], v146 offset:17408
	ds_read_b128 v[210:213], v146 offset:18432
	ds_read_b128 v[214:217], v146 offset:19456
	ds_read_b128 v[218:221], v146 offset:20480
	ds_read_b128 v[222:225], v146 offset:21504
	ds_read_b128 v[226:229], v146 offset:22528
	ds_read_b128 v[230:233], v146 offset:23552
	global_load_lds_dwordx4 v[142:143], off
	s_add_i32 m0, s16, 0x2000
	s_add_u32 s16, s0, 0x80000
	v_lshl_add_u64 v[152:153], s[0:1], 0, v[130:131]
	s_addc_u32 s17, s1, 0
	s_add_i32 s33, s33, s5
	global_load_lds_dwordx4 v[152:153], off
	v_lshl_add_u64 v[196:197], s[16:17], 0, v[134:135]
	s_mov_b32 m0, s33
	v_lshl_add_u64 v[234:235], s[30:31], 0, v[132:133]
	global_load_lds_dwordx4 v[196:197], off
	s_add_i32 m0, s33, 0x2000
	v_lshl_add_u64 v[196:197], s[16:17], 0, v[130:131]
	global_load_lds_dwordx4 v[196:197], off
	s_mov_b32 m0, s7
	v_lshl_add_u64 v[196:197], s[30:31], 0, v[136:137]
	global_load_lds_dwordx4 v[196:197], off
	s_mov_b32 m0, s8
	s_nop 0
	global_load_lds_dwordx4 v[234:235], off
	s_waitcnt vmcnt(8) lgkmcnt(0)
	s_barrier
; #define PG8_STAGE(bufoff, gbase, voff) do { _Pragma("unroll") for (int _i = 0; _i < 2; ++_i) \
;         __builtin_amdgcn_global_load_lds((const unsigned*)((const char*)(gbase) + (voff)[_i]), (LAS unsigned*)(lds + (bufoff) + ldsw + _i * 8192), 16, 0, 0); } while (0)
; #define PG8_LDA(dst, b, h) do { _Pragma("unroll") for (int m = 0; m < 4; ++m) _Pragma("unroll") for (int k = 0; k < 2; ++k) dst[m][k] = *(const LAS bf16x8*)(lds + PG8_SA(b, h) + aoff + m * 2048 + k * 1024); } while (0)
; #define PG8_LDB(dst, b, h) do { _Pragma("unroll") for (int n = 0; n < 2; ++n) _Pragma("unroll") for (int k = 0; k < 2; ++k) dst[n][k] = *(const LAS bf16x8*)(lds + PG8_SB(b, h) + boff + n * 2048 + k * 1024); } while (0)
; #define PG8_MMA(ai, bj, At, Bt) do { __builtin_amdgcn_s_setprio(1); _Pragma("unroll") for (int m = 0; m < 4; ++m) _Pragma("unroll") for (int n = 0; n < 2; ++n) _Pragma("unroll") for (int k = 0; k < 2; ++k) \
;         acc[ai][bj][m][n] = __builtin_amdgcn_mfma_f32_16x16x32_bf16(Bt[n][k], At[m][k], acc[ai][bj][m][n], 0, 0, 0); __builtin_amdgcn_s_setprio(0); } while (0)
; #define PG8_WAIT_V(n) asm volatile("s_waitcnt vmcnt(" #n ")" ::: "memory")
; #define PG8_WAIT_L(n) asm volatile("s_waitcnt lgkmcnt(" #n ")" ::: "memory")
; #define PG8_BAR __builtin_amdgcn_s_barrier()
; #define PG8_SCHED __builtin_amdgcn_sched_barrier(0)
; template <class Epi, class Sched = StaticOrder, bool ALIGN_EPI = true>
; __device__ __forceinline__ void gemm_phase(LAS unsigned char* lds, const Gemm g, const Sched& S, const Epi& E) {
;     ...
;             PG8_WAIT_V(8); PG8_WAIT_L(0); PG8_BAR; PG8_MMA(1, 0, At, B0); PG8_MMA(1, 1, At, B1); PG8_BAR; PG8_SCHED;
;             PG8_LDB(B0, 1, 0); PG8_LDB(B1, 1, 1); PG8_SCHED; PG8_LDA(At, 1, 0); PG8_STAGE(PG8_SA(0, 1), a2 + hstep, voffA);
;             PG8_WAIT_V(8); PG8_WAIT_L(0); PG8_BAR; PG8_MMA(0, 0, At, B0); PG8_MMA(0, 1, At, B1); PG8_BAR; PG8_SCHED;
	v_mfma_f32_16x16x32_bf16 v[62:65], v[148:151], v[188:191], v[62:65]
	v_mfma_f32_16x16x32_bf16 v[58:61], v[164:167], v[188:191], v[58:61]
	v_mfma_f32_16x16x32_bf16 v[54:57], v[148:151], v[210:213], v[54:57]
	v_mfma_f32_16x16x32_bf16 v[46:49], v[164:167], v[210:213], v[46:49]
	v_mfma_f32_16x16x32_bf16 v[38:41], v[148:151], v[218:221], v[38:41]
	v_mfma_f32_16x16x32_bf16 v[30:33], v[164:167], v[218:221], v[30:33]
	v_mfma_f32_16x16x32_bf16 v[22:25], v[148:151], v[226:229], v[22:25]
	v_mfma_f32_16x16x32_bf16 v[14:17], v[164:167], v[226:229], v[14:17]
	v_mfma_f32_16x16x32_bf16 v[62:65], v[160:163], v[192:195], v[62:65]
	v_mfma_f32_16x16x32_bf16 v[58:61], v[168:171], v[192:195], v[58:61]
	v_mfma_f32_16x16x32_bf16 v[54:57], v[160:163], v[214:217], v[54:57]
	v_mfma_f32_16x16x32_bf16 v[46:49], v[168:171], v[214:217], v[46:49]
	v_mfma_f32_16x16x32_bf16 v[38:41], v[160:163], v[222:225], v[38:41]
	v_mfma_f32_16x16x32_bf16 v[30:33], v[168:171], v[222:225], v[30:33]
	v_mfma_f32_16x16x32_bf16 v[22:25], v[160:163], v[230:233], v[22:25]
	v_mfma_f32_16x16x32_bf16 v[14:17], v[168:171], v[230:233], v[14:17]
	v_mfma_f32_16x16x32_bf16 v[50:53], v[172:175], v[188:191], v[50:53]
	v_mfma_f32_16x16x32_bf16 v[42:45], v[180:183], v[188:191], v[42:45]
	v_mfma_f32_16x16x32_bf16 v[34:37], v[172:175], v[210:213], v[34:37]
	v_mfma_f32_16x16x32_bf16 v[26:29], v[180:183], v[210:213], v[26:29]
	v_mfma_f32_16x16x32_bf16 v[18:21], v[172:175], v[218:221], v[18:21]
	v_mfma_f32_16x16x32_bf16 v[10:13], v[180:183], v[218:221], v[10:13]
	v_mfma_f32_16x16x32_bf16 v[6:9], v[172:175], v[226:229], v[6:9]
	v_mfma_f32_16x16x32_bf16 v[2:5], v[180:183], v[226:229], v[2:5]
	v_mfma_f32_16x16x32_bf16 v[50:53], v[176:179], v[192:195], v[50:53]
	v_mfma_f32_16x16x32_bf16 v[42:45], v[184:187], v[192:195], v[42:45]
	v_mfma_f32_16x16x32_bf16 v[34:37], v[176:179], v[214:217], v[34:37]
	v_mfma_f32_16x16x32_bf16 v[26:29], v[184:187], v[214:217], v[26:29]
	v_mfma_f32_16x16x32_bf16 v[18:21], v[176:179], v[222:225], v[18:21]
	v_mfma_f32_16x16x32_bf16 v[10:13], v[184:187], v[222:225], v[10:13]
	v_mfma_f32_16x16x32_bf16 v[6:9], v[176:179], v[230:233], v[6:9]
	v_mfma_f32_16x16x32_bf16 v[2:5], v[184:187], v[230:233], v[2:5]
	s_barrier
	s_add_i32 s33, 0, 0x18000
	v_add_u32_e32 v147, s33, v144
	s_add_i32 s82, 0, 0x1c000
	ds_read_b128 v[148:151], v147
	ds_read_b128 v[160:163], v147 offset:1024
	ds_read_b128 v[164:167], v147 offset:2048
	ds_read_b128 v[168:171], v147 offset:3072
	v_add_u32_e32 v147, s82, v144
	ds_read_b128 v[172:175], v147
	ds_read_b128 v[176:179], v147 offset:1024
	ds_read_b128 v[180:183], v147 offset:2048
	ds_read_b128 v[184:187], v147 offset:3072
	s_add_u32 s16, s30, 0x80000
	s_addc_u32 s17, s31, 0
	s_mov_b32 m0, s9
	v_lshl_add_u64 v[236:237], s[16:17], 0, v[136:137]
	ds_read_b128 v[188:191], v146 offset:32768
	ds_read_b128 v[192:195], v146 offset:33792
	ds_read_b128 v[210:213], v146 offset:34816
	ds_read_b128 v[214:217], v146 offset:35840
	ds_read_b128 v[218:221], v146 offset:36864
	ds_read_b128 v[222:225], v146 offset:37888
	ds_read_b128 v[226:229], v146 offset:38912
	ds_read_b128 v[230:233], v146 offset:39936
	global_load_lds_dwordx4 v[236:237], off
	s_mov_b32 m0, s10
	v_lshl_add_u64 v[236:237], s[16:17], 0, v[132:133]
	global_load_lds_dwordx4 v[236:237], off
	s_waitcnt vmcnt(8) lgkmcnt(0)
	s_barrier
	v_mfma_f32_16x16x32_bf16 v[126:129], v[148:151], v[188:191], v[126:129]
	v_mfma_f32_16x16x32_bf16 v[122:125], v[164:167], v[188:191], v[122:125]
	v_mfma_f32_16x16x32_bf16 v[118:121], v[148:151], v[210:213], v[118:121]
	v_mfma_f32_16x16x32_bf16 v[110:113], v[164:167], v[210:213], v[110:113]
	v_mfma_f32_16x16x32_bf16 v[102:105], v[148:151], v[218:221], v[102:105]
	v_mfma_f32_16x16x32_bf16 v[94:97], v[164:167], v[218:221], v[94:97]
	v_mfma_f32_16x16x32_bf16 v[86:89], v[148:151], v[226:229], v[86:89]
	v_mfma_f32_16x16x32_bf16 v[78:81], v[164:167], v[226:229], v[78:81]
	v_mfma_f32_16x16x32_bf16 v[126:129], v[160:163], v[192:195], v[126:129]
	v_mfma_f32_16x16x32_bf16 v[122:125], v[168:171], v[192:195], v[122:125]
	v_mfma_f32_16x16x32_bf16 v[118:121], v[160:163], v[214:217], v[118:121]
	v_mfma_f32_16x16x32_bf16 v[110:113], v[168:171], v[214:217], v[110:113]
	v_mfma_f32_16x16x32_bf16 v[102:105], v[160:163], v[222:225], v[102:105]
	v_mfma_f32_16x16x32_bf16 v[94:97], v[168:171], v[222:225], v[94:97]
	v_mfma_f32_16x16x32_bf16 v[86:89], v[160:163], v[230:233], v[86:89]
	v_mfma_f32_16x16x32_bf16 v[78:81], v[168:171], v[230:233], v[78:81]
	v_mfma_f32_16x16x32_bf16 v[114:117], v[172:175], v[188:191], v[114:117]
	v_mfma_f32_16x16x32_bf16 v[106:109], v[180:183], v[188:191], v[106:109]
	v_mfma_f32_16x16x32_bf16 v[98:101], v[172:175], v[210:213], v[98:101]
	v_mfma_f32_16x16x32_bf16 v[90:93], v[180:183], v[210:213], v[90:93]
	v_mfma_f32_16x16x32_bf16 v[82:85], v[172:175], v[218:221], v[82:85]
	v_mfma_f32_16x16x32_bf16 v[74:77], v[180:183], v[218:221], v[74:77]
	v_mfma_f32_16x16x32_bf16 v[70:73], v[172:175], v[226:229], v[70:73]
	v_mfma_f32_16x16x32_bf16 v[66:69], v[180:183], v[226:229], v[66:69]
	v_mfma_f32_16x16x32_bf16 v[114:117], v[176:179], v[192:195], v[114:117]
	v_mfma_f32_16x16x32_bf16 v[106:109], v[184:187], v[192:195], v[106:109]
	v_mfma_f32_16x16x32_bf16 v[98:101], v[176:179], v[214:217], v[98:101]
	v_mfma_f32_16x16x32_bf16 v[90:93], v[184:187], v[214:217], v[90:93]
	v_mfma_f32_16x16x32_bf16 v[82:85], v[176:179], v[222:225], v[82:85]
	v_mfma_f32_16x16x32_bf16 v[74:77], v[184:187], v[222:225], v[74:77]
	v_mfma_f32_16x16x32_bf16 v[70:73], v[176:179], v[230:233], v[70:73]
	v_mfma_f32_16x16x32_bf16 v[66:69], v[184:187], v[230:233], v[66:69]
	s_barrier
; #define PG8_STAGE(bufoff, gbase, voff) do { _Pragma("unroll") for (int _i = 0; _i < 2; ++_i) \
;         __builtin_amdgcn_global_load_lds((const unsigned*)((const char*)(gbase) + (voff)[_i]), (LAS unsigned*)(lds + (bufoff) + ldsw + _i * 8192), 16, 0, 0); } while (0)
; #define PG8_LDA(dst, b, h) do { _Pragma("unroll") for (int m = 0; m < 4; ++m) _Pragma("unroll") for (int k = 0; k < 2; ++k) dst[m][k] = *(const LAS bf16x8*)(lds + PG8_SA(b, h) + aoff + m * 2048 + k * 1024); } while (0)
; #define PG8_MMA(ai, bj, At, Bt) do { __builtin_amdgcn_s_setprio(1); _Pragma("unroll") for (int m = 0; m < 4; ++m) _Pragma("unroll") for (int n = 0; n < 2; ++n) _Pragma("unroll") for (int k = 0; k < 2; ++k) \
;         acc[ai][bj][m][n] = __builtin_amdgcn_mfma_f32_16x16x32_bf16(Bt[n][k], At[m][k], acc[ai][bj][m][n], 0, 0, 0); __builtin_amdgcn_s_setprio(0); } while (0)
; #define PG8_WAIT_V(n) asm volatile("s_waitcnt vmcnt(" #n ")" ::: "memory")
; #define PG8_WAIT_L(n) asm volatile("s_waitcnt lgkmcnt(" #n ")" ::: "memory")
; #define PG8_BAR __builtin_amdgcn_s_barrier()
; #define PG8_SCHED __builtin_amdgcn_sched_barrier(0)
; template <class Epi, class Sched = StaticOrder, bool ALIGN_EPI = true>
; __device__ __forceinline__ void gemm_phase(LAS unsigned char* lds, const Gemm g, const Sched& S, const Epi& E) {
;     ...
;             PG8_LDA(At, 1, 1); PG8_STAGE(PG8_SB(1, 0), b3, voffB); PG8_STAGE(PG8_SB(1, 1), b3 + hstep, voffB); PG8_STAGE(PG8_SA(1, 0), a3, voffA);
;             PG8_WAIT_V(8); PG8_WAIT_L(0); PG8_BAR; PG8_MMA(1, 0, At, B0); PG8_MMA(1, 1, At, B1); PG8_BAR; PG8_SCHED;
;         }
	s_add_i32 s16, s33, s5
	v_lshl_add_u64 v[142:143], v[142:143], 0, s[34:35]
	s_mov_b32 m0, s16
	ds_read_b128 v[188:191], v146 offset:49152
	ds_read_b128 v[192:195], v146 offset:50176
	ds_read_b128 v[210:213], v146 offset:51200
	ds_read_b128 v[214:217], v146 offset:52224
	ds_read_b128 v[218:221], v146 offset:53248
	ds_read_b128 v[222:225], v146 offset:54272
	ds_read_b128 v[226:229], v146 offset:55296
	ds_read_b128 v[230:233], v146 offset:56320
	global_load_lds_dwordx4 v[142:143], off
	s_add_i32 m0, s16, 0x2000
	s_add_u32 s0, s0, 0x80080
	v_lshl_add_u64 v[142:143], v[152:153], 0, s[34:35]
	s_addc_u32 s1, s1, 0
	s_add_i32 s16, s82, s5
	global_load_lds_dwordx4 v[142:143], off
	s_mov_b32 m0, s16
	v_lshl_add_u64 v[142:143], s[0:1], 0, v[134:135]
	global_load_lds_dwordx4 v[142:143], off
	s_add_i32 m0, s16, 0x2000
	v_lshl_add_u64 v[142:143], s[0:1], 0, v[130:131]
	global_load_lds_dwordx4 v[142:143], off
	s_mov_b32 m0, s11
	v_lshl_add_u64 v[142:143], v[196:197], 0, s[34:35]
	global_load_lds_dwordx4 v[142:143], off
	s_mov_b32 m0, s18
	v_lshl_add_u64 v[142:143], v[234:235], 0, s[34:35]
	global_load_lds_dwordx4 v[142:143], off
	s_waitcnt vmcnt(8) lgkmcnt(0)
	s_barrier
	v_mfma_f32_16x16x32_bf16 v[62:65], v[148:151], v[188:191], v[62:65]
	v_mfma_f32_16x16x32_bf16 v[58:61], v[164:167], v[188:191], v[58:61]
	v_mfma_f32_16x16x32_bf16 v[54:57], v[148:151], v[210:213], v[54:57]
	v_mfma_f32_16x16x32_bf16 v[46:49], v[164:167], v[210:213], v[46:49]
	v_mfma_f32_16x16x32_bf16 v[38:41], v[148:151], v[218:221], v[38:41]
	v_mfma_f32_16x16x32_bf16 v[30:33], v[164:167], v[218:221], v[30:33]
	v_mfma_f32_16x16x32_bf16 v[22:25], v[148:151], v[226:229], v[22:25]
	v_mfma_f32_16x16x32_bf16 v[14:17], v[164:167], v[226:229], v[14:17]
	v_mfma_f32_16x16x32_bf16 v[62:65], v[160:163], v[192:195], v[62:65]
	v_mfma_f32_16x16x32_bf16 v[58:61], v[168:171], v[192:195], v[58:61]
	v_mfma_f32_16x16x32_bf16 v[54:57], v[160:163], v[214:217], v[54:57]
	v_mfma_f32_16x16x32_bf16 v[46:49], v[168:171], v[214:217], v[46:49]
	v_mfma_f32_16x16x32_bf16 v[38:41], v[160:163], v[222:225], v[38:41]
	v_mfma_f32_16x16x32_bf16 v[30:33], v[168:171], v[222:225], v[30:33]
	v_mfma_f32_16x16x32_bf16 v[22:25], v[160:163], v[230:233], v[22:25]
	v_mfma_f32_16x16x32_bf16 v[14:17], v[168:171], v[230:233], v[14:17]
	v_mfma_f32_16x16x32_bf16 v[50:53], v[172:175], v[188:191], v[50:53]
	v_mfma_f32_16x16x32_bf16 v[42:45], v[180:183], v[188:191], v[42:45]
	v_mfma_f32_16x16x32_bf16 v[34:37], v[172:175], v[210:213], v[34:37]
	v_mfma_f32_16x16x32_bf16 v[26:29], v[180:183], v[210:213], v[26:29]
	v_mfma_f32_16x16x32_bf16 v[18:21], v[172:175], v[218:221], v[18:21]
	v_mfma_f32_16x16x32_bf16 v[10:13], v[180:183], v[218:221], v[10:13]
	v_mfma_f32_16x16x32_bf16 v[6:9], v[172:175], v[226:229], v[6:9]
	v_mfma_f32_16x16x32_bf16 v[2:5], v[180:183], v[226:229], v[2:5]
	v_mfma_f32_16x16x32_bf16 v[50:53], v[176:179], v[192:195], v[50:53]
	v_mfma_f32_16x16x32_bf16 v[42:45], v[184:187], v[192:195], v[42:45]
	v_mfma_f32_16x16x32_bf16 v[34:37], v[176:179], v[214:217], v[34:37]
	v_mfma_f32_16x16x32_bf16 v[26:29], v[184:187], v[214:217], v[26:29]
	v_mfma_f32_16x16x32_bf16 v[18:21], v[176:179], v[222:225], v[18:21]
	v_mfma_f32_16x16x32_bf16 v[10:13], v[184:187], v[222:225], v[10:13]
	v_mfma_f32_16x16x32_bf16 v[6:9], v[176:179], v[230:233], v[6:9]
	v_mfma_f32_16x16x32_bf16 v[2:5], v[184:187], v[230:233], v[2:5]
	s_barrier
	s_add_i32 s79, s79, 2
	s_add_u32 s80, s80, 0x100
	s_addc_u32 s81, s81, 0
	s_add_u32 s49, s49, 0x100
	s_addc_u32 s70, s70, 0
	s_cmp_gt_u32 s79, 29
	s_cbranch_scc0 .LBB0_336

; #define PG8_STAGE(bufoff, gbase, voff) do { _Pragma("unroll") for (int _i = 0; _i < 2; ++_i) \
;         __builtin_amdgcn_global_load_lds((const unsigned*)((const char*)(gbase) + (voff)[_i]), (LAS unsigned*)(lds + (bufoff) + ldsw + _i * 8192), 16, 0, 0); } while (0)
; #define PG8_LDA(dst, b, h) do { _Pragma("unroll") for (int m = 0; m < 4; ++m) _Pragma("unroll") for (int k = 0; k < 2; ++k) dst[m][k] = *(const LAS bf16x8*)(lds + PG8_SA(b, h) + aoff + m * 2048 + k * 1024); } while (0)
; #define PG8_LDB(dst, b, h) do { _Pragma("unroll") for (int n = 0; n < 2; ++n) _Pragma("unroll") for (int k = 0; k < 2; ++k) dst[n][k] = *(const LAS bf16x8*)(lds + PG8_SB(b, h) + boff + n * 2048 + k * 1024); } while (0)
; #define PG8_MMA(ai, bj, At, Bt) do { __builtin_amdgcn_s_setprio(1); _Pragma("unroll") for (int m = 0; m < 4; ++m) _Pragma("unroll") for (int n = 0; n < 2; ++n) _Pragma("unroll") for (int k = 0; k < 2; ++k) \
;         acc[ai][bj][m][n] = __builtin_amdgcn_mfma_f32_16x16x32_bf16(Bt[n][k], At[m][k], acc[ai][bj][m][n], 0, 0, 0); __builtin_amdgcn_s_setprio(0); } while (0)
; #define PG8_WAIT_V(n) asm volatile("s_waitcnt vmcnt(" #n ")" ::: "memory")
; #define PG8_WAIT_L(n) asm volatile("s_waitcnt lgkmcnt(" #n ")" ::: "memory")
; #define PG8_BAR __builtin_amdgcn_s_barrier()
; #define PG8_SCHED __builtin_amdgcn_sched_barrier(0)
; template <class Epi, class Sched = StaticOrder, bool ALIGN_EPI = true>
; __device__ __forceinline__ void gemm_phase(LAS unsigned char* lds, const Gemm g, const Sched& S, const Epi& E) {
;     ...
;             PG8_LDB(B0, 0, 0); PG8_LDB(B1, 0, 1); PG8_SCHED; PG8_LDA(At, 0, 0); PG8_STAGE(PG8_SA(1, 1), a1 + hstep, voffA);
;             PG8_WAIT_V(8); PG8_WAIT_L(0); PG8_BAR; PG8_MMA(0, 0, At, B0); PG8_MMA(0, 1, At, B1); PG8_BAR; PG8_SCHED;
;             PG8_LDA(At, 0, 1); PG8_STAGE(PG8_SB(0, 0), b2, voffB); PG8_STAGE(PG8_SB(0, 1), b2 + hstep, voffB); PG8_STAGE(PG8_SA(0, 0), a2, voffA);
;             PG8_WAIT_V(8); PG8_WAIT_L(0); PG8_BAR; PG8_MMA(1, 0, At, B0); PG8_MMA(1, 1, At, B1); PG8_BAR; PG8_SCHED;
;     ...
;         for (int a = 0; a < 2; ++a)
; #pragma unroll
;             for (int b = 0; b < 2; ++b)
; #pragma unroll
;                 for (int m = 0; m < 4; ++m)
; #pragma unroll
;                     for (int n = 0; n < 2; ++n) acc[a][b][m][n] = (f32x4){0.f, 0.f, 0.f, 0.f};
.Lmy_nb_370:
	s_add_u32 s46, s44, 0x100
	s_addc_u32 s47, s45, 0
	s_add_i32 s16, 0, 0x10000
	s_cmpk_eq_i32 s82, 0x54
	s_cselect_b32 s31, s37, s47
	s_cselect_b32 s30, s36, s46
	v_add_u32_e32 v142, s16, v144
	s_cselect_b32 s1, s43, s92
	s_cselect_b32 s0, s42, s79
	s_add_i32 s33, 0, 0x14000
	ds_read_b128 v[148:151], v142
	ds_read_b128 v[160:163], v142 offset:1024
	ds_read_b128 v[164:167], v142 offset:2048
	ds_read_b128 v[168:171], v142 offset:3072
	v_add_u32_e32 v142, s33, v144
	ds_read_b128 v[172:175], v142
	ds_read_b128 v[176:179], v142 offset:1024
	ds_read_b128 v[180:183], v142 offset:2048
	ds_read_b128 v[184:187], v142 offset:3072
	v_lshl_add_u64 v[142:143], s[44:45], 0, v[138:139]
	s_add_i32 m0, s6, 0xc000
	ds_read_b128 v[188:191], v146
	ds_read_b128 v[192:195], v146 offset:1024
	ds_read_b128 v[210:213], v146 offset:2048
	ds_read_b128 v[214:217], v146 offset:3072
	ds_read_b128 v[218:221], v146 offset:4096
	ds_read_b128 v[222:225], v146 offset:5120
	ds_read_b128 v[226:229], v146 offset:6144
	ds_read_b128 v[230:233], v146 offset:7168
	global_load_lds_dwordx4 v[142:143], off
	s_add_i32 m0, s6, 0xe000
	v_lshl_add_u64 v[142:143], s[44:45], 0, v[140:141]
	global_load_lds_dwordx4 v[142:143], off
	s_waitcnt vmcnt(8) lgkmcnt(0)
	s_barrier
	v_mfma_f32_16x16x32_bf16 v[126:129], v[148:151], v[188:191], 0
	v_mfma_f32_16x16x32_bf16 v[122:125], v[164:167], v[188:191], 0
	v_mfma_f32_16x16x32_bf16 v[118:121], v[148:151], v[210:213], 0
	v_mfma_f32_16x16x32_bf16 v[110:113], v[164:167], v[210:213], 0
	v_mfma_f32_16x16x32_bf16 v[102:105], v[148:151], v[218:221], 0
	v_mfma_f32_16x16x32_bf16 v[94:97], v[164:167], v[218:221], 0
	v_mfma_f32_16x16x32_bf16 v[82:85], v[148:151], v[226:229], 0
	v_mfma_f32_16x16x32_bf16 v[74:77], v[164:167], v[226:229], 0
	v_mfma_f32_16x16x32_bf16 v[126:129], v[160:163], v[192:195], v[126:129]
	v_mfma_f32_16x16x32_bf16 v[122:125], v[168:171], v[192:195], v[122:125]
	v_mfma_f32_16x16x32_bf16 v[118:121], v[160:163], v[214:217], v[118:121]
	v_mfma_f32_16x16x32_bf16 v[110:113], v[168:171], v[214:217], v[110:113]
	v_mfma_f32_16x16x32_bf16 v[102:105], v[160:163], v[222:225], v[102:105]
	v_mfma_f32_16x16x32_bf16 v[94:97], v[168:171], v[222:225], v[94:97]
	v_mfma_f32_16x16x32_bf16 v[82:85], v[160:163], v[230:233], v[82:85]
	v_mfma_f32_16x16x32_bf16 v[74:77], v[168:171], v[230:233], v[74:77]
	v_mfma_f32_16x16x32_bf16 v[114:117], v[172:175], v[188:191], 0
	v_mfma_f32_16x16x32_bf16 v[106:109], v[180:183], v[188:191], 0
	v_mfma_f32_16x16x32_bf16 v[98:101], v[172:175], v[210:213], 0
	v_mfma_f32_16x16x32_bf16 v[90:93], v[180:183], v[210:213], 0
	v_mfma_f32_16x16x32_bf16 v[86:89], v[172:175], v[218:221], 0
	v_mfma_f32_16x16x32_bf16 v[78:81], v[180:183], v[218:221], 0
	v_mfma_f32_16x16x32_bf16 v[70:73], v[172:175], v[226:229], 0
	v_mfma_f32_16x16x32_bf16 v[66:69], v[180:183], v[226:229], 0
	v_mfma_f32_16x16x32_bf16 v[114:117], v[176:179], v[192:195], v[114:117]
	v_mfma_f32_16x16x32_bf16 v[106:109], v[184:187], v[192:195], v[106:109]
	v_mfma_f32_16x16x32_bf16 v[98:101], v[176:179], v[214:217], v[98:101]
	v_mfma_f32_16x16x32_bf16 v[90:93], v[184:187], v[214:217], v[90:93]
	v_mfma_f32_16x16x32_bf16 v[86:89], v[176:179], v[222:225], v[86:89]
	v_mfma_f32_16x16x32_bf16 v[78:81], v[184:187], v[222:225], v[78:81]
	v_mfma_f32_16x16x32_bf16 v[70:73], v[176:179], v[230:233], v[70:73]
	v_mfma_f32_16x16x32_bf16 v[66:69], v[184:187], v[230:233], v[66:69]
	s_barrier
	s_add_i32 s16, s16, s4
	v_lshl_add_u64 v[142:143], s[0:1], 0, v[134:135]
	s_mov_b32 m0, s16
	ds_read_b128 v[188:191], v146 offset:16384
	ds_read_b128 v[192:195], v146 offset:17408
	ds_read_b128 v[210:213], v146 offset:18432
	ds_read_b128 v[214:217], v146 offset:19456
	ds_read_b128 v[218:221], v146 offset:20480
	ds_read_b128 v[222:225], v146 offset:21504
	ds_read_b128 v[226:229], v146 offset:22528
	ds_read_b128 v[230:233], v146 offset:23552
	global_load_lds_dwordx4 v[142:143], off
	s_add_i32 m0, s16, 0x2000
	s_add_u32 s16, s0, 0x160000
	v_lshl_add_u64 v[152:153], s[0:1], 0, v[130:131]
	s_addc_u32 s17, s1, 0
	s_add_i32 s33, s33, s4
	global_load_lds_dwordx4 v[152:153], off
	v_lshl_add_u64 v[196:197], s[16:17], 0, v[134:135]
	s_mov_b32 m0, s33
	v_lshl_add_u64 v[234:235], s[30:31], 0, v[132:133]
	global_load_lds_dwordx4 v[196:197], off
	s_add_i32 m0, s33, 0x2000
	v_lshl_add_u64 v[196:197], s[16:17], 0, v[130:131]
	global_load_lds_dwordx4 v[196:197], off
	s_mov_b32 m0, s6
	v_lshl_add_u64 v[196:197], s[30:31], 0, v[136:137]
	global_load_lds_dwordx4 v[196:197], off
	s_mov_b32 m0, s7
	s_nop 0
	global_load_lds_dwordx4 v[234:235], off
	s_waitcnt vmcnt(8) lgkmcnt(0)
	s_barrier
	v_mfma_f32_16x16x32_bf16 v[62:65], v[148:151], v[188:191], 0
	v_mfma_f32_16x16x32_bf16 v[58:61], v[164:167], v[188:191], 0
	v_mfma_f32_16x16x32_bf16 v[54:57], v[148:151], v[210:213], 0
	v_mfma_f32_16x16x32_bf16 v[46:49], v[164:167], v[210:213], 0
	v_mfma_f32_16x16x32_bf16 v[38:41], v[148:151], v[218:221], 0
	v_mfma_f32_16x16x32_bf16 v[30:33], v[164:167], v[218:221], 0
	v_mfma_f32_16x16x32_bf16 v[22:25], v[148:151], v[226:229], 0
	v_mfma_f32_16x16x32_bf16 v[14:17], v[164:167], v[226:229], 0
	v_mfma_f32_16x16x32_bf16 v[62:65], v[160:163], v[192:195], v[62:65]
	v_mfma_f32_16x16x32_bf16 v[58:61], v[168:171], v[192:195], v[58:61]
	v_mfma_f32_16x16x32_bf16 v[54:57], v[160:163], v[214:217], v[54:57]
	v_mfma_f32_16x16x32_bf16 v[46:49], v[168:171], v[214:217], v[46:49]
	v_mfma_f32_16x16x32_bf16 v[38:41], v[160:163], v[222:225], v[38:41]
	v_mfma_f32_16x16x32_bf16 v[30:33], v[168:171], v[222:225], v[30:33]
	v_mfma_f32_16x16x32_bf16 v[22:25], v[160:163], v[230:233], v[22:25]
	v_mfma_f32_16x16x32_bf16 v[14:17], v[168:171], v[230:233], v[14:17]
	v_mfma_f32_16x16x32_bf16 v[50:53], v[172:175], v[188:191], 0
	v_mfma_f32_16x16x32_bf16 v[42:45], v[180:183], v[188:191], 0
	v_mfma_f32_16x16x32_bf16 v[34:37], v[172:175], v[210:213], 0
	v_mfma_f32_16x16x32_bf16 v[26:29], v[180:183], v[210:213], 0
	v_mfma_f32_16x16x32_bf16 v[18:21], v[172:175], v[218:221], 0
	v_mfma_f32_16x16x32_bf16 v[10:13], v[180:183], v[218:221], 0
	v_mfma_f32_16x16x32_bf16 v[6:9], v[172:175], v[226:229], 0
	v_mfma_f32_16x16x32_bf16 v[2:5], v[180:183], v[226:229], 0
	v_mfma_f32_16x16x32_bf16 v[50:53], v[176:179], v[192:195], v[50:53]
	v_mfma_f32_16x16x32_bf16 v[42:45], v[184:187], v[192:195], v[42:45]
	v_mfma_f32_16x16x32_bf16 v[34:37], v[176:179], v[214:217], v[34:37]
	v_mfma_f32_16x16x32_bf16 v[26:29], v[184:187], v[214:217], v[26:29]
	v_mfma_f32_16x16x32_bf16 v[18:21], v[176:179], v[222:225], v[18:21]
	v_mfma_f32_16x16x32_bf16 v[10:13], v[184:187], v[222:225], v[10:13]
	v_mfma_f32_16x16x32_bf16 v[6:9], v[176:179], v[230:233], v[6:9]
	v_mfma_f32_16x16x32_bf16 v[2:5], v[184:187], v[230:233], v[2:5]
	s_barrier
; #define PG8_STAGE(bufoff, gbase, voff) do { _Pragma("unroll") for (int _i = 0; _i < 2; ++_i) \
;         __builtin_amdgcn_global_load_lds((const unsigned*)((const char*)(gbase) + (voff)[_i]), (LAS unsigned*)(lds + (bufoff) + ldsw + _i * 8192), 16, 0, 0); } while (0)
; #define PG8_LDA(dst, b, h) do { _Pragma("unroll") for (int m = 0; m < 4; ++m) _Pragma("unroll") for (int k = 0; k < 2; ++k) dst[m][k] = *(const LAS bf16x8*)(lds + PG8_SA(b, h) + aoff + m * 2048 + k * 1024); } while (0)
; #define PG8_LDB(dst, b, h) do { _Pragma("unroll") for (int n = 0; n < 2; ++n) _Pragma("unroll") for (int k = 0; k < 2; ++k) dst[n][k] = *(const LAS bf16x8*)(lds + PG8_SB(b, h) + boff + n * 2048 + k * 1024); } while (0)
; #define PG8_MMA(ai, bj, At, Bt) do { __builtin_amdgcn_s_setprio(1); _Pragma("unroll") for (int m = 0; m < 4; ++m) _Pragma("unroll") for (int n = 0; n < 2; ++n) _Pragma("unroll") for (int k = 0; k < 2; ++k) \
;         acc[ai][bj][m][n] = __builtin_amdgcn_mfma_f32_16x16x32_bf16(Bt[n][k], At[m][k], acc[ai][bj][m][n], 0, 0, 0); __builtin_amdgcn_s_setprio(0); } while (0)
; #define PG8_WAIT_V(n) asm volatile("s_waitcnt vmcnt(" #n ")" ::: "memory")
; #define PG8_WAIT_L(n) asm volatile("s_waitcnt lgkmcnt(" #n ")" ::: "memory")
; #define PG8_BAR __builtin_amdgcn_s_barrier()
; #define PG8_SCHED __builtin_amdgcn_sched_barrier(0)
; template <class Epi, class Sched = StaticOrder, bool ALIGN_EPI = true>
; __device__ __forceinline__ void gemm_phase(LAS unsigned char* lds, const Gemm g, const Sched& S, const Epi& E) {
;     ...
;             PG8_LDB(B0, 1, 0); PG8_LDB(B1, 1, 1); PG8_SCHED; PG8_LDA(At, 1, 0); PG8_STAGE(PG8_SA(0, 1), a2 + hstep, voffA);
;             PG8_WAIT_V(8); PG8_WAIT_L(0); PG8_BAR; PG8_MMA(0, 0, At, B0); PG8_MMA(0, 1, At, B1); PG8_BAR; PG8_SCHED;
;             PG8_LDA(At, 1, 1); PG8_STAGE(PG8_SB(1, 0), b3, voffB); PG8_STAGE(PG8_SB(1, 1), b3 + hstep, voffB); PG8_STAGE(PG8_SA(1, 0), a3, voffA);
;             PG8_WAIT_V(8); PG8_WAIT_L(0); PG8_BAR; PG8_MMA(1, 0, At, B0); PG8_MMA(1, 1, At, B1); PG8_BAR; PG8_SCHED;
;         }
	s_add_i32 s33, 0, 0x18000
	v_add_u32_e32 v147, s33, v144
	s_add_i32 s44, 0, 0x1c000
	ds_read_b128 v[148:151], v147
	ds_read_b128 v[160:163], v147 offset:1024
	ds_read_b128 v[164:167], v147 offset:2048
	ds_read_b128 v[168:171], v147 offset:3072
	v_add_u32_e32 v147, s44, v144
	ds_read_b128 v[172:175], v147
	ds_read_b128 v[176:179], v147 offset:1024
	ds_read_b128 v[180:183], v147 offset:2048
	ds_read_b128 v[184:187], v147 offset:3072
	s_add_u32 s16, s30, 0x160000
	s_addc_u32 s17, s31, 0
	s_mov_b32 m0, s8
	v_lshl_add_u64 v[236:237], s[16:17], 0, v[136:137]
	ds_read_b128 v[188:191], v146 offset:32768
	ds_read_b128 v[192:195], v146 offset:33792
	ds_read_b128 v[210:213], v146 offset:34816
	ds_read_b128 v[214:217], v146 offset:35840
	ds_read_b128 v[218:221], v146 offset:36864
	ds_read_b128 v[222:225], v146 offset:37888
	ds_read_b128 v[226:229], v146 offset:38912
	ds_read_b128 v[230:233], v146 offset:39936
	global_load_lds_dwordx4 v[236:237], off
	s_mov_b32 m0, s9
	v_lshl_add_u64 v[236:237], s[16:17], 0, v[132:133]
	global_load_lds_dwordx4 v[236:237], off
	s_waitcnt vmcnt(8) lgkmcnt(0)
	s_barrier
	v_mfma_f32_16x16x32_bf16 v[126:129], v[148:151], v[188:191], v[126:129]
	v_mfma_f32_16x16x32_bf16 v[122:125], v[164:167], v[188:191], v[122:125]
	v_mfma_f32_16x16x32_bf16 v[118:121], v[148:151], v[210:213], v[118:121]
	v_mfma_f32_16x16x32_bf16 v[110:113], v[164:167], v[210:213], v[110:113]
	v_mfma_f32_16x16x32_bf16 v[102:105], v[148:151], v[218:221], v[102:105]
	v_mfma_f32_16x16x32_bf16 v[94:97], v[164:167], v[218:221], v[94:97]
	v_mfma_f32_16x16x32_bf16 v[82:85], v[148:151], v[226:229], v[82:85]
	v_mfma_f32_16x16x32_bf16 v[74:77], v[164:167], v[226:229], v[74:77]
	v_mfma_f32_16x16x32_bf16 v[126:129], v[160:163], v[192:195], v[126:129]
	v_mfma_f32_16x16x32_bf16 v[122:125], v[168:171], v[192:195], v[122:125]
	v_mfma_f32_16x16x32_bf16 v[118:121], v[160:163], v[214:217], v[118:121]
	v_mfma_f32_16x16x32_bf16 v[110:113], v[168:171], v[214:217], v[110:113]
	v_mfma_f32_16x16x32_bf16 v[102:105], v[160:163], v[222:225], v[102:105]
	v_mfma_f32_16x16x32_bf16 v[94:97], v[168:171], v[222:225], v[94:97]
	v_mfma_f32_16x16x32_bf16 v[82:85], v[160:163], v[230:233], v[82:85]
	v_mfma_f32_16x16x32_bf16 v[74:77], v[168:171], v[230:233], v[74:77]
	v_mfma_f32_16x16x32_bf16 v[114:117], v[172:175], v[188:191], v[114:117]
	v_mfma_f32_16x16x32_bf16 v[106:109], v[180:183], v[188:191], v[106:109]
	v_mfma_f32_16x16x32_bf16 v[98:101], v[172:175], v[210:213], v[98:101]
	v_mfma_f32_16x16x32_bf16 v[90:93], v[180:183], v[210:213], v[90:93]
	v_mfma_f32_16x16x32_bf16 v[86:89], v[172:175], v[218:221], v[86:89]
	v_mfma_f32_16x16x32_bf16 v[78:81], v[180:183], v[218:221], v[78:81]
	v_mfma_f32_16x16x32_bf16 v[70:73], v[172:175], v[226:229], v[70:73]
	v_mfma_f32_16x16x32_bf16 v[66:69], v[180:183], v[226:229], v[66:69]
	v_mfma_f32_16x16x32_bf16 v[114:117], v[176:179], v[192:195], v[114:117]
	v_mfma_f32_16x16x32_bf16 v[106:109], v[184:187], v[192:195], v[106:109]
	v_mfma_f32_16x16x32_bf16 v[98:101], v[176:179], v[214:217], v[98:101]
	v_mfma_f32_16x16x32_bf16 v[90:93], v[184:187], v[214:217], v[90:93]
	v_mfma_f32_16x16x32_bf16 v[86:89], v[176:179], v[222:225], v[86:89]
	v_mfma_f32_16x16x32_bf16 v[78:81], v[184:187], v[222:225], v[78:81]
	v_mfma_f32_16x16x32_bf16 v[70:73], v[176:179], v[230:233], v[70:73]
	v_mfma_f32_16x16x32_bf16 v[66:69], v[184:187], v[230:233], v[66:69]
	s_barrier
	s_add_i32 s16, s33, s4
	v_lshl_add_u64 v[142:143], v[142:143], 0, s[34:35]
	s_mov_b32 m0, s16
	ds_read_b128 v[188:191], v146 offset:49152
	ds_read_b128 v[192:195], v146 offset:50176
	ds_read_b128 v[210:213], v146 offset:51200
	ds_read_b128 v[214:217], v146 offset:52224
	ds_read_b128 v[218:221], v146 offset:53248
	ds_read_b128 v[222:225], v146 offset:54272
	ds_read_b128 v[226:229], v146 offset:55296
	ds_read_b128 v[230:233], v146 offset:56320
	global_load_lds_dwordx4 v[142:143], off
	s_add_i32 m0, s16, 0x2000
	s_add_u32 s0, s0, 0x160080
	v_lshl_add_u64 v[142:143], v[152:153], 0, s[34:35]
	s_addc_u32 s1, s1, 0
	s_add_i32 s16, s44, s4
	global_load_lds_dwordx4 v[142:143], off
	s_mov_b32 m0, s16
	v_lshl_add_u64 v[142:143], s[0:1], 0, v[134:135]
	global_load_lds_dwordx4 v[142:143], off
	s_add_i32 m0, s16, 0x2000
	v_lshl_add_u64 v[142:143], s[0:1], 0, v[130:131]
	global_load_lds_dwordx4 v[142:143], off
	s_mov_b32 m0, s10
	v_lshl_add_u64 v[142:143], v[196:197], 0, s[34:35]
	global_load_lds_dwordx4 v[142:143], off
	s_mov_b32 m0, s11
	v_lshl_add_u64 v[142:143], v[234:235], 0, s[34:35]
	global_load_lds_dwordx4 v[142:143], off
	s_waitcnt vmcnt(8) lgkmcnt(0)
	s_barrier
	v_mfma_f32_16x16x32_bf16 v[62:65], v[148:151], v[188:191], v[62:65]
	v_mfma_f32_16x16x32_bf16 v[58:61], v[164:167], v[188:191], v[58:61]
	v_mfma_f32_16x16x32_bf16 v[54:57], v[148:151], v[210:213], v[54:57]
	v_mfma_f32_16x16x32_bf16 v[46:49], v[164:167], v[210:213], v[46:49]
	v_mfma_f32_16x16x32_bf16 v[38:41], v[148:151], v[218:221], v[38:41]
	v_mfma_f32_16x16x32_bf16 v[30:33], v[164:167], v[218:221], v[30:33]
	v_mfma_f32_16x16x32_bf16 v[22:25], v[148:151], v[226:229], v[22:25]
	v_mfma_f32_16x16x32_bf16 v[14:17], v[164:167], v[226:229], v[14:17]
	v_mfma_f32_16x16x32_bf16 v[62:65], v[160:163], v[192:195], v[62:65]
	v_mfma_f32_16x16x32_bf16 v[58:61], v[168:171], v[192:195], v[58:61]
	v_mfma_f32_16x16x32_bf16 v[54:57], v[160:163], v[214:217], v[54:57]
	v_mfma_f32_16x16x32_bf16 v[46:49], v[168:171], v[214:217], v[46:49]
	v_mfma_f32_16x16x32_bf16 v[38:41], v[160:163], v[222:225], v[38:41]
	v_mfma_f32_16x16x32_bf16 v[30:33], v[168:171], v[222:225], v[30:33]
	v_mfma_f32_16x16x32_bf16 v[22:25], v[160:163], v[230:233], v[22:25]
	v_mfma_f32_16x16x32_bf16 v[14:17], v[168:171], v[230:233], v[14:17]
	v_mfma_f32_16x16x32_bf16 v[50:53], v[172:175], v[188:191], v[50:53]
	v_mfma_f32_16x16x32_bf16 v[42:45], v[180:183], v[188:191], v[42:45]
	v_mfma_f32_16x16x32_bf16 v[34:37], v[172:175], v[210:213], v[34:37]
	v_mfma_f32_16x16x32_bf16 v[26:29], v[180:183], v[210:213], v[26:29]
	v_mfma_f32_16x16x32_bf16 v[18:21], v[172:175], v[218:221], v[18:21]
	v_mfma_f32_16x16x32_bf16 v[10:13], v[180:183], v[218:221], v[10:13]
	v_mfma_f32_16x16x32_bf16 v[6:9], v[172:175], v[226:229], v[6:9]
	v_mfma_f32_16x16x32_bf16 v[2:5], v[180:183], v[226:229], v[2:5]
	v_mfma_f32_16x16x32_bf16 v[50:53], v[176:179], v[192:195], v[50:53]
	v_mfma_f32_16x16x32_bf16 v[42:45], v[184:187], v[192:195], v[42:45]
	v_mfma_f32_16x16x32_bf16 v[34:37], v[176:179], v[214:217], v[34:37]
	v_mfma_f32_16x16x32_bf16 v[26:29], v[184:187], v[214:217], v[26:29]
	v_mfma_f32_16x16x32_bf16 v[18:21], v[176:179], v[222:225], v[18:21]
	v_mfma_f32_16x16x32_bf16 v[10:13], v[184:187], v[222:225], v[10:13]
	v_mfma_f32_16x16x32_bf16 v[6:9], v[176:179], v[230:233], v[6:9]
	v_mfma_f32_16x16x32_bf16 v[2:5], v[184:187], v[230:233], v[2:5]
	s_barrier
	s_add_i32 s82, s82, 2
	s_add_u32 s79, s79, 0x100
	s_addc_u32 s92, s92, 0
	s_cmpk_gt_u32 s82, 0x55
	s_mov_b64 s[44:45], s[46:47]
	s_cbranch_scc0 .LBB0_370
;     __device__ bool next(int i, Unit& u) const { const int idx = i * G + c; if (idx >= 64) return false; u.kp = idx & 3; u.pn = (idx >> 2) & 7; u.pm = 192 + (idx >> 5); return true; }
; #define PG8_STAGE(bufoff, gbase, voff) do { _Pragma("unroll") for (int _i = 0; _i < 2; ++_i) \
;         __builtin_amdgcn_global_load_lds((const unsigned*)((const char*)(gbase) + (voff)[_i]), (LAS unsigned*)(lds + (bufoff) + ldsw + _i * 8192), 16, 0, 0); } while (0)
; #define PG8_LDA(dst, b, h) do { _Pragma("unroll") for (int m = 0; m < 4; ++m) _Pragma("unroll") for (int k = 0; k < 2; ++k) dst[m][k] = *(const LAS bf16x8*)(lds + PG8_SA(b, h) + aoff + m * 2048 + k * 1024); } while (0)
; #define PG8_LDB(dst, b, h) do { _Pragma("unroll") for (int n = 0; n < 2; ++n) _Pragma("unroll") for (int k = 0; k < 2; ++k) dst[n][k] = *(const LAS bf16x8*)(lds + PG8_SB(b, h) + boff + n * 2048 + k * 1024); } while (0)
; #define PG8_WAIT_V(n) asm volatile("s_waitcnt vmcnt(" #n ")" ::: "memory")
; #define PG8_WAIT_L(n) asm volatile("s_waitcnt lgkmcnt(" #n ")" ::: "memory")
; template <class Epi, class Sched = StaticOrder, bool ALIGN_EPI = true>
; __device__ __forceinline__ void gemm_phase(LAS unsigned char* lds, const Gemm g, const Sched& S, const Epi& E) {
;     ...
;         const bool has_next = S.next(ui + 1, nxt);
;         const char* nA = has_next ? (const char*)g.A + (size_t)nxt.pm * tstep + (size_t)nxt.kp * K * 2 : cA; const char* nB = has_next ? (const char*)g.Bt + (size_t)nxt.pn * tstep + (size_t)nxt.kp * K * 2 : cB;
;         for (int t = 0; t < nt; t += 2) {
;             const bool last = (t == nt - 2);
;             const char* a1 = cA + (size_t)(t + 1) * kstep;
;             const char* a2 = last ? nA : cA + (size_t)(t + 2) * kstep; const char* b2 = last ? nB : cB + (size_t)(t + 2) * kstep;
;             const char* a3 = a2 + kstep; const char* b3 = b2 + kstep;
;             PG8_LDB(B0, 0, 0); PG8_LDB(B1, 0, 1); PG8_SCHED; PG8_LDA(At, 0, 0); PG8_STAGE(PG8_SA(1, 1), a1 + hstep, voffA);
;             PG8_WAIT_V(8); PG8_WAIT_L(0); PG8_BAR; PG8_MMA(0, 0, At, B0); PG8_MMA(0, 1, At, B1); PG8_BAR; PG8_SCHED;
;             PG8_LDA(At, 0, 1); PG8_STAGE(PG8_SB(0, 0), b2, voffB); PG8_STAGE(PG8_SB(0, 1), b2 + hstep, voffB); PG8_STAGE(PG8_SA(0, 0), a2, voffA);
;             PG8_WAIT_V(8); PG8_WAIT_L(0); PG8_BAR; PG8_MMA(1, 0, At, B0); PG8_MMA(1, 1, At, B1); PG8_BAR; PG8_SCHED;
.LBB0_370:
	s_add_u32 s46, s44, 0x100
	s_addc_u32 s47, s45, 0
	s_add_i32 s16, 0, 0x10000
	s_cmpk_eq_i32 s82, 0x54
	s_cselect_b32 s31, s37, s47
	s_cselect_b32 s30, s36, s46
	v_add_u32_e32 v142, s16, v144
	s_cselect_b32 s1, s43, s92
	s_cselect_b32 s0, s42, s79
	s_add_i32 s33, 0, 0x14000
	ds_read_b128 v[148:151], v142
	ds_read_b128 v[160:163], v142 offset:1024
	ds_read_b128 v[164:167], v142 offset:2048
	ds_read_b128 v[168:171], v142 offset:3072
	v_add_u32_e32 v142, s33, v144
	ds_read_b128 v[172:175], v142
	ds_read_b128 v[176:179], v142 offset:1024
	ds_read_b128 v[180:183], v142 offset:2048
	ds_read_b128 v[184:187], v142 offset:3072
	v_lshl_add_u64 v[142:143], s[44:45], 0, v[138:139]
	s_add_i32 m0, s6, 0xc000
	ds_read_b128 v[188:191], v146
	ds_read_b128 v[192:195], v146 offset:1024
	ds_read_b128 v[210:213], v146 offset:2048
	ds_read_b128 v[214:217], v146 offset:3072
	ds_read_b128 v[218:221], v146 offset:4096
	ds_read_b128 v[222:225], v146 offset:5120
	ds_read_b128 v[226:229], v146 offset:6144
	ds_read_b128 v[230:233], v146 offset:7168
	global_load_lds_dwordx4 v[142:143], off
	s_add_i32 m0, s6, 0xe000
	v_lshl_add_u64 v[142:143], s[44:45], 0, v[140:141]
	global_load_lds_dwordx4 v[142:143], off
	s_waitcnt vmcnt(8) lgkmcnt(0)
	s_barrier
	v_mfma_f32_16x16x32_bf16 v[126:129], v[148:151], v[188:191], v[126:129]
	v_mfma_f32_16x16x32_bf16 v[122:125], v[164:167], v[188:191], v[122:125]
	v_mfma_f32_16x16x32_bf16 v[118:121], v[148:151], v[210:213], v[118:121]
	v_mfma_f32_16x16x32_bf16 v[110:113], v[164:167], v[210:213], v[110:113]
	v_mfma_f32_16x16x32_bf16 v[102:105], v[148:151], v[218:221], v[102:105]
	v_mfma_f32_16x16x32_bf16 v[94:97], v[164:167], v[218:221], v[94:97]
	v_mfma_f32_16x16x32_bf16 v[82:85], v[148:151], v[226:229], v[82:85]
	v_mfma_f32_16x16x32_bf16 v[74:77], v[164:167], v[226:229], v[74:77]
	v_mfma_f32_16x16x32_bf16 v[126:129], v[160:163], v[192:195], v[126:129]
	v_mfma_f32_16x16x32_bf16 v[122:125], v[168:171], v[192:195], v[122:125]
	v_mfma_f32_16x16x32_bf16 v[118:121], v[160:163], v[214:217], v[118:121]
	v_mfma_f32_16x16x32_bf16 v[110:113], v[168:171], v[214:217], v[110:113]
	v_mfma_f32_16x16x32_bf16 v[102:105], v[160:163], v[222:225], v[102:105]
	v_mfma_f32_16x16x32_bf16 v[94:97], v[168:171], v[222:225], v[94:97]
	v_mfma_f32_16x16x32_bf16 v[82:85], v[160:163], v[230:233], v[82:85]
	v_mfma_f32_16x16x32_bf16 v[74:77], v[168:171], v[230:233], v[74:77]
	v_mfma_f32_16x16x32_bf16 v[114:117], v[172:175], v[188:191], v[114:117]
	v_mfma_f32_16x16x32_bf16 v[106:109], v[180:183], v[188:191], v[106:109]
	v_mfma_f32_16x16x32_bf16 v[98:101], v[172:175], v[210:213], v[98:101]
	v_mfma_f32_16x16x32_bf16 v[90:93], v[180:183], v[210:213], v[90:93]
	v_mfma_f32_16x16x32_bf16 v[86:89], v[172:175], v[218:221], v[86:89]
	v_mfma_f32_16x16x32_bf16 v[78:81], v[180:183], v[218:221], v[78:81]
	v_mfma_f32_16x16x32_bf16 v[70:73], v[172:175], v[226:229], v[70:73]
	v_mfma_f32_16x16x32_bf16 v[66:69], v[180:183], v[226:229], v[66:69]
	v_mfma_f32_16x16x32_bf16 v[114:117], v[176:179], v[192:195], v[114:117]
	v_mfma_f32_16x16x32_bf16 v[106:109], v[184:187], v[192:195], v[106:109]
	v_mfma_f32_16x16x32_bf16 v[98:101], v[176:179], v[214:217], v[98:101]
	v_mfma_f32_16x16x32_bf16 v[90:93], v[184:187], v[214:217], v[90:93]
	v_mfma_f32_16x16x32_bf16 v[86:89], v[176:179], v[222:225], v[86:89]
	v_mfma_f32_16x16x32_bf16 v[78:81], v[184:187], v[222:225], v[78:81]
	v_mfma_f32_16x16x32_bf16 v[70:73], v[176:179], v[230:233], v[70:73]
	v_mfma_f32_16x16x32_bf16 v[66:69], v[184:187], v[230:233], v[66:69]
	s_barrier
	s_add_i32 s16, s16, s4
	v_lshl_add_u64 v[142:143], s[0:1], 0, v[134:135]
	s_mov_b32 m0, s16
	ds_read_b128 v[188:191], v146 offset:16384
	ds_read_b128 v[192:195], v146 offset:17408
	ds_read_b128 v[210:213], v146 offset:18432
	ds_read_b128 v[214:217], v146 offset:19456
	ds_read_b128 v[218:221], v146 offset:20480
	ds_read_b128 v[222:225], v146 offset:21504
	ds_read_b128 v[226:229], v146 offset:22528
	ds_read_b128 v[230:233], v146 offset:23552
	global_load_lds_dwordx4 v[142:143], off
	s_add_i32 m0, s16, 0x2000
	s_add_u32 s16, s0, 0x160000
	v_lshl_add_u64 v[152:153], s[0:1], 0, v[130:131]
	s_addc_u32 s17, s1, 0
	s_add_i32 s33, s33, s4
	global_load_lds_dwordx4 v[152:153], off
	v_lshl_add_u64 v[196:197], s[16:17], 0, v[134:135]
	s_mov_b32 m0, s33
	v_lshl_add_u64 v[234:235], s[30:31], 0, v[132:133]
	global_load_lds_dwordx4 v[196:197], off
	s_add_i32 m0, s33, 0x2000
	v_lshl_add_u64 v[196:197], s[16:17], 0, v[130:131]
	global_load_lds_dwordx4 v[196:197], off
	s_mov_b32 m0, s6
	v_lshl_add_u64 v[196:197], s[30:31], 0, v[136:137]
	global_load_lds_dwordx4 v[196:197], off
	s_mov_b32 m0, s7
	s_nop 0
	global_load_lds_dwordx4 v[234:235], off
	s_waitcnt vmcnt(8) lgkmcnt(0)
	s_barrier
; #define PG8_STAGE(bufoff, gbase, voff) do { _Pragma("unroll") for (int _i = 0; _i < 2; ++_i) \
;         __builtin_amdgcn_global_load_lds((const unsigned*)((const char*)(gbase) + (voff)[_i]), (LAS unsigned*)(lds + (bufoff) + ldsw + _i * 8192), 16, 0, 0); } while (0)
; #define PG8_LDA(dst, b, h) do { _Pragma("unroll") for (int m = 0; m < 4; ++m) _Pragma("unroll") for (int k = 0; k < 2; ++k) dst[m][k] = *(const LAS bf16x8*)(lds + PG8_SA(b, h) + aoff + m * 2048 + k * 1024); } while (0)
; #define PG8_LDB(dst, b, h) do { _Pragma("unroll") for (int n = 0; n < 2; ++n) _Pragma("unroll") for (int k = 0; k < 2; ++k) dst[n][k] = *(const LAS bf16x8*)(lds + PG8_SB(b, h) + boff + n * 2048 + k * 1024); } while (0)
; #define PG8_MMA(ai, bj, At, Bt) do { __builtin_amdgcn_s_setprio(1); _Pragma("unroll") for (int m = 0; m < 4; ++m) _Pragma("unroll") for (int n = 0; n < 2; ++n) _Pragma("unroll") for (int k = 0; k < 2; ++k) \
;         acc[ai][bj][m][n] = __builtin_amdgcn_mfma_f32_16x16x32_bf16(Bt[n][k], At[m][k], acc[ai][bj][m][n], 0, 0, 0); __builtin_amdgcn_s_setprio(0); } while (0)
; #define PG8_WAIT_V(n) asm volatile("s_waitcnt vmcnt(" #n ")" ::: "memory")
; #define PG8_WAIT_L(n) asm volatile("s_waitcnt lgkmcnt(" #n ")" ::: "memory")
; #define PG8_BAR __builtin_amdgcn_s_barrier()
; #define PG8_SCHED __builtin_amdgcn_sched_barrier(0)
; template <class Epi, class Sched = StaticOrder, bool ALIGN_EPI = true>
; __device__ __forceinline__ void gemm_phase(LAS unsigned char* lds, const Gemm g, const Sched& S, const Epi& E) {
;     ...
;             PG8_WAIT_V(8); PG8_WAIT_L(0); PG8_BAR; PG8_MMA(1, 0, At, B0); PG8_MMA(1, 1, At, B1); PG8_BAR; PG8_SCHED;
;             PG8_LDB(B0, 1, 0); PG8_LDB(B1, 1, 1); PG8_SCHED; PG8_LDA(At, 1, 0); PG8_STAGE(PG8_SA(0, 1), a2 + hstep, voffA);
;             PG8_WAIT_V(8); PG8_WAIT_L(0); PG8_BAR; PG8_MMA(0, 0, At, B0); PG8_MMA(0, 1, At, B1); PG8_BAR; PG8_SCHED;
	v_mfma_f32_16x16x32_bf16 v[62:65], v[148:151], v[188:191], v[62:65]
	v_mfma_f32_16x16x32_bf16 v[58:61], v[164:167], v[188:191], v[58:61]
	v_mfma_f32_16x16x32_bf16 v[54:57], v[148:151], v[210:213], v[54:57]
	v_mfma_f32_16x16x32_bf16 v[46:49], v[164:167], v[210:213], v[46:49]
	v_mfma_f32_16x16x32_bf16 v[38:41], v[148:151], v[218:221], v[38:41]
	v_mfma_f32_16x16x32_bf16 v[30:33], v[164:167], v[218:221], v[30:33]
	v_mfma_f32_16x16x32_bf16 v[22:25], v[148:151], v[226:229], v[22:25]
	v_mfma_f32_16x16x32_bf16 v[14:17], v[164:167], v[226:229], v[14:17]
	v_mfma_f32_16x16x32_bf16 v[62:65], v[160:163], v[192:195], v[62:65]
	v_mfma_f32_16x16x32_bf16 v[58:61], v[168:171], v[192:195], v[58:61]
	v_mfma_f32_16x16x32_bf16 v[54:57], v[160:163], v[214:217], v[54:57]
	v_mfma_f32_16x16x32_bf16 v[46:49], v[168:171], v[214:217], v[46:49]
	v_mfma_f32_16x16x32_bf16 v[38:41], v[160:163], v[222:225], v[38:41]
	v_mfma_f32_16x16x32_bf16 v[30:33], v[168:171], v[222:225], v[30:33]
	v_mfma_f32_16x16x32_bf16 v[22:25], v[160:163], v[230:233], v[22:25]
	v_mfma_f32_16x16x32_bf16 v[14:17], v[168:171], v[230:233], v[14:17]
	v_mfma_f32_16x16x32_bf16 v[50:53], v[172:175], v[188:191], v[50:53]
	v_mfma_f32_16x16x32_bf16 v[42:45], v[180:183], v[188:191], v[42:45]
	v_mfma_f32_16x16x32_bf16 v[34:37], v[172:175], v[210:213], v[34:37]
	v_mfma_f32_16x16x32_bf16 v[26:29], v[180:183], v[210:213], v[26:29]
	v_mfma_f32_16x16x32_bf16 v[18:21], v[172:175], v[218:221], v[18:21]
	v_mfma_f32_16x16x32_bf16 v[10:13], v[180:183], v[218:221], v[10:13]
	v_mfma_f32_16x16x32_bf16 v[6:9], v[172:175], v[226:229], v[6:9]
	v_mfma_f32_16x16x32_bf16 v[2:5], v[180:183], v[226:229], v[2:5]
	v_mfma_f32_16x16x32_bf16 v[50:53], v[176:179], v[192:195], v[50:53]
	v_mfma_f32_16x16x32_bf16 v[42:45], v[184:187], v[192:195], v[42:45]
	v_mfma_f32_16x16x32_bf16 v[34:37], v[176:179], v[214:217], v[34:37]
	v_mfma_f32_16x16x32_bf16 v[26:29], v[184:187], v[214:217], v[26:29]
	v_mfma_f32_16x16x32_bf16 v[18:21], v[176:179], v[222:225], v[18:21]
	v_mfma_f32_16x16x32_bf16 v[10:13], v[184:187], v[222:225], v[10:13]
	v_mfma_f32_16x16x32_bf16 v[6:9], v[176:179], v[230:233], v[6:9]
	v_mfma_f32_16x16x32_bf16 v[2:5], v[184:187], v[230:233], v[2:5]
	s_barrier
	s_add_i32 s33, 0, 0x18000
	v_add_u32_e32 v147, s33, v144
	s_add_i32 s44, 0, 0x1c000
	ds_read_b128 v[148:151], v147
	ds_read_b128 v[160:163], v147 offset:1024
	ds_read_b128 v[164:167], v147 offset:2048
	ds_read_b128 v[168:171], v147 offset:3072
	v_add_u32_e32 v147, s44, v144
	ds_read_b128 v[172:175], v147
	ds_read_b128 v[176:179], v147 offset:1024
	ds_read_b128 v[180:183], v147 offset:2048
	ds_read_b128 v[184:187], v147 offset:3072
	s_add_u32 s16, s30, 0x160000
	s_addc_u32 s17, s31, 0
	s_mov_b32 m0, s8
	v_lshl_add_u64 v[236:237], s[16:17], 0, v[136:137]
	ds_read_b128 v[188:191], v146 offset:32768
	ds_read_b128 v[192:195], v146 offset:33792
	ds_read_b128 v[210:213], v146 offset:34816
	ds_read_b128 v[214:217], v146 offset:35840
	ds_read_b128 v[218:221], v146 offset:36864
	ds_read_b128 v[222:225], v146 offset:37888
	ds_read_b128 v[226:229], v146 offset:38912
	ds_read_b128 v[230:233], v146 offset:39936
	global_load_lds_dwordx4 v[236:237], off
	s_mov_b32 m0, s9
	v_lshl_add_u64 v[236:237], s[16:17], 0, v[132:133]
	global_load_lds_dwordx4 v[236:237], off
	s_waitcnt vmcnt(8) lgkmcnt(0)
	s_barrier
	v_mfma_f32_16x16x32_bf16 v[126:129], v[148:151], v[188:191], v[126:129]
	v_mfma_f32_16x16x32_bf16 v[122:125], v[164:167], v[188:191], v[122:125]
	v_mfma_f32_16x16x32_bf16 v[118:121], v[148:151], v[210:213], v[118:121]
	v_mfma_f32_16x16x32_bf16 v[110:113], v[164:167], v[210:213], v[110:113]
	v_mfma_f32_16x16x32_bf16 v[102:105], v[148:151], v[218:221], v[102:105]
	v_mfma_f32_16x16x32_bf16 v[94:97], v[164:167], v[218:221], v[94:97]
	v_mfma_f32_16x16x32_bf16 v[82:85], v[148:151], v[226:229], v[82:85]
	v_mfma_f32_16x16x32_bf16 v[74:77], v[164:167], v[226:229], v[74:77]
	v_mfma_f32_16x16x32_bf16 v[126:129], v[160:163], v[192:195], v[126:129]
	v_mfma_f32_16x16x32_bf16 v[122:125], v[168:171], v[192:195], v[122:125]
	v_mfma_f32_16x16x32_bf16 v[118:121], v[160:163], v[214:217], v[118:121]
	v_mfma_f32_16x16x32_bf16 v[110:113], v[168:171], v[214:217], v[110:113]
	v_mfma_f32_16x16x32_bf16 v[102:105], v[160:163], v[222:225], v[102:105]
	v_mfma_f32_16x16x32_bf16 v[94:97], v[168:171], v[222:225], v[94:97]
	v_mfma_f32_16x16x32_bf16 v[82:85], v[160:163], v[230:233], v[82:85]
	v_mfma_f32_16x16x32_bf16 v[74:77], v[168:171], v[230:233], v[74:77]
	v_mfma_f32_16x16x32_bf16 v[114:117], v[172:175], v[188:191], v[114:117]
	v_mfma_f32_16x16x32_bf16 v[106:109], v[180:183], v[188:191], v[106:109]
	v_mfma_f32_16x16x32_bf16 v[98:101], v[172:175], v[210:213], v[98:101]
	v_mfma_f32_16x16x32_bf16 v[90:93], v[180:183], v[210:213], v[90:93]
	v_mfma_f32_16x16x32_bf16 v[86:89], v[172:175], v[218:221], v[86:89]
	v_mfma_f32_16x16x32_bf16 v[78:81], v[180:183], v[218:221], v[78:81]
	v_mfma_f32_16x16x32_bf16 v[70:73], v[172:175], v[226:229], v[70:73]
	v_mfma_f32_16x16x32_bf16 v[66:69], v[180:183], v[226:229], v[66:69]
	v_mfma_f32_16x16x32_bf16 v[114:117], v[176:179], v[192:195], v[114:117]
	v_mfma_f32_16x16x32_bf16 v[106:109], v[184:187], v[192:195], v[106:109]
	v_mfma_f32_16x16x32_bf16 v[98:101], v[176:179], v[214:217], v[98:101]
	v_mfma_f32_16x16x32_bf16 v[90:93], v[184:187], v[214:217], v[90:93]
	v_mfma_f32_16x16x32_bf16 v[86:89], v[176:179], v[222:225], v[86:89]
	v_mfma_f32_16x16x32_bf16 v[78:81], v[184:187], v[222:225], v[78:81]
	v_mfma_f32_16x16x32_bf16 v[70:73], v[176:179], v[230:233], v[70:73]
	v_mfma_f32_16x16x32_bf16 v[66:69], v[184:187], v[230:233], v[66:69]
	s_barrier
; #define PG8_STAGE(bufoff, gbase, voff) do { _Pragma("unroll") for (int _i = 0; _i < 2; ++_i) \
;         __builtin_amdgcn_global_load_lds((const unsigned*)((const char*)(gbase) + (voff)[_i]), (LAS unsigned*)(lds + (bufoff) + ldsw + _i * 8192), 16, 0, 0); } while (0)
; #define PG8_LDA(dst, b, h) do { _Pragma("unroll") for (int m = 0; m < 4; ++m) _Pragma("unroll") for (int k = 0; k < 2; ++k) dst[m][k] = *(const LAS bf16x8*)(lds + PG8_SA(b, h) + aoff + m * 2048 + k * 1024); } while (0)
; #define PG8_MMA(ai, bj, At, Bt) do { __builtin_amdgcn_s_setprio(1); _Pragma("unroll") for (int m = 0; m < 4; ++m) _Pragma("unroll") for (int n = 0; n < 2; ++n) _Pragma("unroll") for (int k = 0; k < 2; ++k) \
;         acc[ai][bj][m][n] = __builtin_amdgcn_mfma_f32_16x16x32_bf16(Bt[n][k], At[m][k], acc[ai][bj][m][n], 0, 0, 0); __builtin_amdgcn_s_setprio(0); } while (0)
; #define PG8_WAIT_V(n) asm volatile("s_waitcnt vmcnt(" #n ")" ::: "memory")
; #define PG8_WAIT_L(n) asm volatile("s_waitcnt lgkmcnt(" #n ")" ::: "memory")
; #define PG8_BAR __builtin_amdgcn_s_barrier()
; #define PG8_SCHED __builtin_amdgcn_sched_barrier(0)
; template <class Epi, class Sched = StaticOrder, bool ALIGN_EPI = true>
; __device__ __forceinline__ void gemm_phase(LAS unsigned char* lds, const Gemm g, const Sched& S, const Epi& E) {
;     ...
;             PG8_LDA(At, 1, 1); PG8_STAGE(PG8_SB(1, 0), b3, voffB); PG8_STAGE(PG8_SB(1, 1), b3 + hstep, voffB); PG8_STAGE(PG8_SA(1, 0), a3, voffA);
;             PG8_WAIT_V(8); PG8_WAIT_L(0); PG8_BAR; PG8_MMA(1, 0, At, B0); PG8_MMA(1, 1, At, B1); PG8_BAR; PG8_SCHED;
;         }
	s_add_i32 s16, s33, s4
	v_lshl_add_u64 v[142:143], v[142:143], 0, s[34:35]
	s_mov_b32 m0, s16
	ds_read_b128 v[188:191], v146 offset:49152
	ds_read_b128 v[192:195], v146 offset:50176
	ds_read_b128 v[210:213], v146 offset:51200
	ds_read_b128 v[214:217], v146 offset:52224
	ds_read_b128 v[218:221], v146 offset:53248
	ds_read_b128 v[222:225], v146 offset:54272
	ds_read_b128 v[226:229], v146 offset:55296
	ds_read_b128 v[230:233], v146 offset:56320
	global_load_lds_dwordx4 v[142:143], off
	s_add_i32 m0, s16, 0x2000
	s_add_u32 s0, s0, 0x160080
	v_lshl_add_u64 v[142:143], v[152:153], 0, s[34:35]
	s_addc_u32 s1, s1, 0
	s_add_i32 s16, s44, s4
	global_load_lds_dwordx4 v[142:143], off
	s_mov_b32 m0, s16
	v_lshl_add_u64 v[142:143], s[0:1], 0, v[134:135]
	global_load_lds_dwordx4 v[142:143], off
	s_add_i32 m0, s16, 0x2000
	v_lshl_add_u64 v[142:143], s[0:1], 0, v[130:131]
	global_load_lds_dwordx4 v[142:143], off
	s_mov_b32 m0, s10
	v_lshl_add_u64 v[142:143], v[196:197], 0, s[34:35]
	global_load_lds_dwordx4 v[142:143], off
	s_mov_b32 m0, s11
	v_lshl_add_u64 v[142:143], v[234:235], 0, s[34:35]
	global_load_lds_dwordx4 v[142:143], off
	s_waitcnt vmcnt(8) lgkmcnt(0)
	s_barrier
	v_mfma_f32_16x16x32_bf16 v[62:65], v[148:151], v[188:191], v[62:65]
	v_mfma_f32_16x16x32_bf16 v[58:61], v[164:167], v[188:191], v[58:61]
	v_mfma_f32_16x16x32_bf16 v[54:57], v[148:151], v[210:213], v[54:57]
	v_mfma_f32_16x16x32_bf16 v[46:49], v[164:167], v[210:213], v[46:49]
	v_mfma_f32_16x16x32_bf16 v[38:41], v[148:151], v[218:221], v[38:41]
	v_mfma_f32_16x16x32_bf16 v[30:33], v[164:167], v[218:221], v[30:33]
	v_mfma_f32_16x16x32_bf16 v[22:25], v[148:151], v[226:229], v[22:25]
	v_mfma_f32_16x16x32_bf16 v[14:17], v[164:167], v[226:229], v[14:17]
	v_mfma_f32_16x16x32_bf16 v[62:65], v[160:163], v[192:195], v[62:65]
	v_mfma_f32_16x16x32_bf16 v[58:61], v[168:171], v[192:195], v[58:61]
	v_mfma_f32_16x16x32_bf16 v[54:57], v[160:163], v[214:217], v[54:57]
	v_mfma_f32_16x16x32_bf16 v[46:49], v[168:171], v[214:217], v[46:49]
	v_mfma_f32_16x16x32_bf16 v[38:41], v[160:163], v[222:225], v[38:41]
	v_mfma_f32_16x16x32_bf16 v[30:33], v[168:171], v[222:225], v[30:33]
	v_mfma_f32_16x16x32_bf16 v[22:25], v[160:163], v[230:233], v[22:25]
	v_mfma_f32_16x16x32_bf16 v[14:17], v[168:171], v[230:233], v[14:17]
	v_mfma_f32_16x16x32_bf16 v[50:53], v[172:175], v[188:191], v[50:53]
	v_mfma_f32_16x16x32_bf16 v[42:45], v[180:183], v[188:191], v[42:45]
	v_mfma_f32_16x16x32_bf16 v[34:37], v[172:175], v[210:213], v[34:37]
	v_mfma_f32_16x16x32_bf16 v[26:29], v[180:183], v[210:213], v[26:29]
	v_mfma_f32_16x16x32_bf16 v[18:21], v[172:175], v[218:221], v[18:21]
	v_mfma_f32_16x16x32_bf16 v[10:13], v[180:183], v[218:221], v[10:13]
	v_mfma_f32_16x16x32_bf16 v[6:9], v[172:175], v[226:229], v[6:9]
	v_mfma_f32_16x16x32_bf16 v[2:5], v[180:183], v[226:229], v[2:5]
	v_mfma_f32_16x16x32_bf16 v[50:53], v[176:179], v[192:195], v[50:53]
	v_mfma_f32_16x16x32_bf16 v[42:45], v[184:187], v[192:195], v[42:45]
	v_mfma_f32_16x16x32_bf16 v[34:37], v[176:179], v[214:217], v[34:37]
	v_mfma_f32_16x16x32_bf16 v[26:29], v[184:187], v[214:217], v[26:29]
	v_mfma_f32_16x16x32_bf16 v[18:21], v[176:179], v[222:225], v[18:21]
	v_mfma_f32_16x16x32_bf16 v[10:13], v[184:187], v[222:225], v[10:13]
	v_mfma_f32_16x16x32_bf16 v[6:9], v[176:179], v[230:233], v[6:9]
	v_mfma_f32_16x16x32_bf16 v[2:5], v[184:187], v[230:233], v[2:5]
	s_barrier
	s_add_i32 s82, s82, 2
	s_add_u32 s79, s79, 0x100
	s_addc_u32 s92, s92, 0
	s_cmpk_gt_u32 s82, 0x55
	s_mov_b64 s[44:45], s[46:47]
	s_cbranch_scc0 .LBB0_370

; #define PG8_STAGE(bufoff, gbase, voff) do { _Pragma("unroll") for (int _i = 0; _i < 2; ++_i) \
;         __builtin_amdgcn_global_load_lds((const unsigned*)((const char*)(gbase) + (voff)[_i]), (LAS unsigned*)(lds + (bufoff) + ldsw + _i * 8192), 16, 0, 0); } while (0)
; #define PG8_LDA(dst, b, h) do { _Pragma("unroll") for (int m = 0; m < 4; ++m) _Pragma("unroll") for (int k = 0; k < 2; ++k) dst[m][k] = *(const LAS bf16x8*)(lds + PG8_SA(b, h) + aoff + m * 2048 + k * 1024); } while (0)
; #define PG8_LDB(dst, b, h) do { _Pragma("unroll") for (int n = 0; n < 2; ++n) _Pragma("unroll") for (int k = 0; k < 2; ++k) dst[n][k] = *(const LAS bf16x8*)(lds + PG8_SB(b, h) + boff + n * 2048 + k * 1024); } while (0)
; #define PG8_MMA(ai, bj, At, Bt) do { __builtin_amdgcn_s_setprio(1); _Pragma("unroll") for (int m = 0; m < 4; ++m) _Pragma("unroll") for (int n = 0; n < 2; ++n) _Pragma("unroll") for (int k = 0; k < 2; ++k) \
;         acc[ai][bj][m][n] = __builtin_amdgcn_mfma_f32_16x16x32_bf16(Bt[n][k], At[m][k], acc[ai][bj][m][n], 0, 0, 0); __builtin_amdgcn_s_setprio(0); } while (0)
; #define PG8_WAIT_V(n) asm volatile("s_waitcnt vmcnt(" #n ")" ::: "memory")
; #define PG8_WAIT_L(n) asm volatile("s_waitcnt lgkmcnt(" #n ")" ::: "memory")
; #define PG8_BAR __builtin_amdgcn_s_barrier()
; #define PG8_SCHED __builtin_amdgcn_sched_barrier(0)
; template <class Epi, class Sched = StaticOrder, bool ALIGN_EPI = true>
; __device__ __forceinline__ void gemm_phase(LAS unsigned char* lds, const Gemm g, const Sched& S, const Epi& E) {
;     ...
;             PG8_LDB(B0, 0, 0); PG8_LDB(B1, 0, 1); PG8_SCHED; PG8_LDA(At, 0, 0); PG8_STAGE(PG8_SA(1, 1), a1 + hstep, voffA);
;             PG8_WAIT_V(8); PG8_WAIT_L(0); PG8_BAR; PG8_MMA(0, 0, At, B0); PG8_MMA(0, 1, At, B1); PG8_BAR; PG8_SCHED;
;             PG8_LDA(At, 0, 1); PG8_STAGE(PG8_SB(0, 0), b2, voffB); PG8_STAGE(PG8_SB(0, 1), b2 + hstep, voffB); PG8_STAGE(PG8_SA(0, 0), a2, voffA);
;             PG8_WAIT_V(8); PG8_WAIT_L(0); PG8_BAR; PG8_MMA(1, 0, At, B0); PG8_MMA(1, 1, At, B1); PG8_BAR; PG8_SCHED;
;     ...
;         for (int a = 0; a < 2; ++a)
; #pragma unroll
;             for (int b = 0; b < 2; ++b)
; #pragma unroll
;                 for (int m = 0; m < 4; ++m)
; #pragma unroll
;                     for (int n = 0; n < 2; ++n) acc[a][b][m][n] = (f32x4){0.f, 0.f, 0.f, 0.f};
.Lmy_nb_392:
	s_add_u32 s46, s44, 0x100
	s_addc_u32 s47, s45, 0
	s_add_i32 s16, 0, 0x10000
	s_cmpk_eq_i32 s82, 0x54
	s_cselect_b32 s31, s37, s47
	s_cselect_b32 s30, s36, s46
	v_add_u32_e32 v152, s16, v135
	s_cselect_b32 s1, s43, s92
	s_cselect_b32 s0, s42, s79
	s_add_i32 s33, 0, 0x14000
	ds_read_b128 v[140:143], v152
	ds_read_b128 v[144:147], v152 offset:1024
	ds_read_b128 v[148:151], v152 offset:2048
	ds_read_b128 v[160:163], v152 offset:3072
	v_add_u32_e32 v152, s33, v135
	ds_read_b128 v[164:167], v152
	ds_read_b128 v[172:175], v152 offset:1024
	ds_read_b128 v[176:179], v152 offset:2048
	ds_read_b128 v[180:183], v152 offset:3072
	v_lshl_add_u64 v[152:153], s[44:45], 0, v[136:137]
	s_add_i32 m0, s6, 0xc000
	ds_read_b128 v[184:187], v170
	ds_read_b128 v[188:191], v170 offset:1024
	ds_read_b128 v[192:195], v170 offset:2048
	ds_read_b128 v[210:213], v170 offset:3072
	ds_read_b128 v[214:217], v170 offset:4096
	ds_read_b128 v[218:221], v170 offset:5120
	ds_read_b128 v[222:225], v170 offset:6144
	ds_read_b128 v[226:229], v170 offset:7168
	global_load_lds_dwordx4 v[152:153], off
	s_add_i32 m0, s6, 0xe000
	v_lshl_add_u64 v[152:153], s[44:45], 0, v[138:139]
	global_load_lds_dwordx4 v[152:153], off
	s_waitcnt vmcnt(8) lgkmcnt(0)
	s_barrier
	v_mfma_f32_16x16x32_bf16 v[126:129], v[140:143], v[184:187], 0
	v_mfma_f32_16x16x32_bf16 v[122:125], v[148:151], v[184:187], 0
	v_mfma_f32_16x16x32_bf16 v[118:121], v[140:143], v[192:195], 0
	v_mfma_f32_16x16x32_bf16 v[106:109], v[148:151], v[192:195], 0
	v_mfma_f32_16x16x32_bf16 v[98:101], v[140:143], v[214:217], 0
	v_mfma_f32_16x16x32_bf16 v[90:93], v[148:151], v[214:217], 0
	v_mfma_f32_16x16x32_bf16 v[82:85], v[140:143], v[222:225], 0
	v_mfma_f32_16x16x32_bf16 v[74:77], v[148:151], v[222:225], 0
	v_mfma_f32_16x16x32_bf16 v[126:129], v[144:147], v[188:191], v[126:129]
	v_mfma_f32_16x16x32_bf16 v[122:125], v[160:163], v[188:191], v[122:125]
	v_mfma_f32_16x16x32_bf16 v[118:121], v[144:147], v[210:213], v[118:121]
	v_mfma_f32_16x16x32_bf16 v[106:109], v[160:163], v[210:213], v[106:109]
	v_mfma_f32_16x16x32_bf16 v[98:101], v[144:147], v[218:221], v[98:101]
	v_mfma_f32_16x16x32_bf16 v[90:93], v[160:163], v[218:221], v[90:93]
	v_mfma_f32_16x16x32_bf16 v[82:85], v[144:147], v[226:229], v[82:85]
	v_mfma_f32_16x16x32_bf16 v[74:77], v[160:163], v[226:229], v[74:77]
	v_mfma_f32_16x16x32_bf16 v[114:117], v[164:167], v[184:187], 0
	v_mfma_f32_16x16x32_bf16 v[110:113], v[176:179], v[184:187], 0
	v_mfma_f32_16x16x32_bf16 v[102:105], v[164:167], v[192:195], 0
	v_mfma_f32_16x16x32_bf16 v[94:97], v[176:179], v[192:195], 0
	v_mfma_f32_16x16x32_bf16 v[86:89], v[164:167], v[214:217], 0
	v_mfma_f32_16x16x32_bf16 v[78:81], v[176:179], v[214:217], 0
	v_mfma_f32_16x16x32_bf16 v[70:73], v[164:167], v[222:225], 0
	v_mfma_f32_16x16x32_bf16 v[66:69], v[176:179], v[222:225], 0
	v_mfma_f32_16x16x32_bf16 v[114:117], v[172:175], v[188:191], v[114:117]
	v_mfma_f32_16x16x32_bf16 v[110:113], v[180:183], v[188:191], v[110:113]
	v_mfma_f32_16x16x32_bf16 v[102:105], v[172:175], v[210:213], v[102:105]
	v_mfma_f32_16x16x32_bf16 v[94:97], v[180:183], v[210:213], v[94:97]
	v_mfma_f32_16x16x32_bf16 v[86:89], v[172:175], v[218:221], v[86:89]
	v_mfma_f32_16x16x32_bf16 v[78:81], v[180:183], v[218:221], v[78:81]
	v_mfma_f32_16x16x32_bf16 v[70:73], v[172:175], v[226:229], v[70:73]
	v_mfma_f32_16x16x32_bf16 v[66:69], v[180:183], v[226:229], v[66:69]
	s_barrier
	s_add_i32 s16, s16, s4
	v_lshl_add_u64 v[152:153], s[0:1], 0, v[132:133]
	s_mov_b32 m0, s16
	ds_read_b128 v[184:187], v170 offset:16384
	ds_read_b128 v[188:191], v170 offset:17408
	ds_read_b128 v[192:195], v170 offset:18432
	ds_read_b128 v[210:213], v170 offset:19456
	ds_read_b128 v[214:217], v170 offset:20480
	ds_read_b128 v[218:221], v170 offset:21504
	ds_read_b128 v[222:225], v170 offset:22528
	ds_read_b128 v[226:229], v170 offset:23552
	global_load_lds_dwordx4 v[152:153], off
	s_add_i32 m0, s16, 0x2000
	s_add_u32 s16, s0, 0x160000
	v_lshl_add_u64 v[168:169], s[0:1], 0, v[130:131]
	s_addc_u32 s17, s1, 0
	s_add_i32 s33, s33, s4
	global_load_lds_dwordx4 v[168:169], off
	v_lshl_add_u64 v[196:197], s[16:17], 0, v[132:133]
	s_mov_b32 m0, s33
	v_lshl_add_u64 v[230:231], s[30:31], 0, v[130:131]
	global_load_lds_dwordx4 v[196:197], off
	s_add_i32 m0, s33, 0x2000
	v_lshl_add_u64 v[196:197], s[16:17], 0, v[130:131]
	global_load_lds_dwordx4 v[196:197], off
	s_mov_b32 m0, s6
	v_lshl_add_u64 v[196:197], s[30:31], 0, v[132:133]
	global_load_lds_dwordx4 v[196:197], off
	s_mov_b32 m0, s7
	s_nop 0
	global_load_lds_dwordx4 v[230:231], off
	s_waitcnt vmcnt(8) lgkmcnt(0)
	s_barrier
	v_mfma_f32_16x16x32_bf16 v[62:65], v[140:143], v[184:187], 0
	v_mfma_f32_16x16x32_bf16 v[58:61], v[148:151], v[184:187], 0
	v_mfma_f32_16x16x32_bf16 v[50:53], v[140:143], v[192:195], 0
	v_mfma_f32_16x16x32_bf16 v[42:45], v[148:151], v[192:195], 0
	v_mfma_f32_16x16x32_bf16 v[34:37], v[140:143], v[214:217], 0
	v_mfma_f32_16x16x32_bf16 v[26:29], v[148:151], v[214:217], 0
	v_mfma_f32_16x16x32_bf16 v[18:21], v[140:143], v[222:225], 0
	v_mfma_f32_16x16x32_bf16 v[10:13], v[148:151], v[222:225], 0
	v_mfma_f32_16x16x32_bf16 v[62:65], v[144:147], v[188:191], v[62:65]
	v_mfma_f32_16x16x32_bf16 v[58:61], v[160:163], v[188:191], v[58:61]
	v_mfma_f32_16x16x32_bf16 v[50:53], v[144:147], v[210:213], v[50:53]
	v_mfma_f32_16x16x32_bf16 v[42:45], v[160:163], v[210:213], v[42:45]
	v_mfma_f32_16x16x32_bf16 v[34:37], v[144:147], v[218:221], v[34:37]
	v_mfma_f32_16x16x32_bf16 v[26:29], v[160:163], v[218:221], v[26:29]
	v_mfma_f32_16x16x32_bf16 v[18:21], v[144:147], v[226:229], v[18:21]
	v_mfma_f32_16x16x32_bf16 v[10:13], v[160:163], v[226:229], v[10:13]
	v_mfma_f32_16x16x32_bf16 v[54:57], v[164:167], v[184:187], 0
	v_mfma_f32_16x16x32_bf16 v[46:49], v[176:179], v[184:187], 0
	v_mfma_f32_16x16x32_bf16 v[38:41], v[164:167], v[192:195], 0
	v_mfma_f32_16x16x32_bf16 v[30:33], v[176:179], v[192:195], 0
	v_mfma_f32_16x16x32_bf16 v[22:25], v[164:167], v[214:217], 0
	v_mfma_f32_16x16x32_bf16 v[14:17], v[176:179], v[214:217], 0
	v_mfma_f32_16x16x32_bf16 v[6:9], v[164:167], v[222:225], 0
	v_mfma_f32_16x16x32_bf16 v[2:5], v[176:179], v[222:225], 0
	v_mfma_f32_16x16x32_bf16 v[54:57], v[172:175], v[188:191], v[54:57]
	v_mfma_f32_16x16x32_bf16 v[46:49], v[180:183], v[188:191], v[46:49]
	v_mfma_f32_16x16x32_bf16 v[38:41], v[172:175], v[210:213], v[38:41]
	v_mfma_f32_16x16x32_bf16 v[30:33], v[180:183], v[210:213], v[30:33]
	v_mfma_f32_16x16x32_bf16 v[22:25], v[172:175], v[218:221], v[22:25]
	v_mfma_f32_16x16x32_bf16 v[14:17], v[180:183], v[218:221], v[14:17]
	v_mfma_f32_16x16x32_bf16 v[6:9], v[172:175], v[226:229], v[6:9]
	v_mfma_f32_16x16x32_bf16 v[2:5], v[180:183], v[226:229], v[2:5]
	s_barrier
; #define PG8_STAGE(bufoff, gbase, voff) do { _Pragma("unroll") for (int _i = 0; _i < 2; ++_i) \
;         __builtin_amdgcn_global_load_lds((const unsigned*)((const char*)(gbase) + (voff)[_i]), (LAS unsigned*)(lds + (bufoff) + ldsw + _i * 8192), 16, 0, 0); } while (0)
; #define PG8_LDA(dst, b, h) do { _Pragma("unroll") for (int m = 0; m < 4; ++m) _Pragma("unroll") for (int k = 0; k < 2; ++k) dst[m][k] = *(const LAS bf16x8*)(lds + PG8_SA(b, h) + aoff + m * 2048 + k * 1024); } while (0)
; #define PG8_LDB(dst, b, h) do { _Pragma("unroll") for (int n = 0; n < 2; ++n) _Pragma("unroll") for (int k = 0; k < 2; ++k) dst[n][k] = *(const LAS bf16x8*)(lds + PG8_SB(b, h) + boff + n * 2048 + k * 1024); } while (0)
; #define PG8_MMA(ai, bj, At, Bt) do { __builtin_amdgcn_s_setprio(1); _Pragma("unroll") for (int m = 0; m < 4; ++m) _Pragma("unroll") for (int n = 0; n < 2; ++n) _Pragma("unroll") for (int k = 0; k < 2; ++k) \
;         acc[ai][bj][m][n] = __builtin_amdgcn_mfma_f32_16x16x32_bf16(Bt[n][k], At[m][k], acc[ai][bj][m][n], 0, 0, 0); __builtin_amdgcn_s_setprio(0); } while (0)
; #define PG8_WAIT_V(n) asm volatile("s_waitcnt vmcnt(" #n ")" ::: "memory")
; #define PG8_WAIT_L(n) asm volatile("s_waitcnt lgkmcnt(" #n ")" ::: "memory")
; #define PG8_BAR __builtin_amdgcn_s_barrier()
; #define PG8_SCHED __builtin_amdgcn_sched_barrier(0)
; template <class Epi, class Sched = StaticOrder, bool ALIGN_EPI = true>
; __device__ __forceinline__ void gemm_phase(LAS unsigned char* lds, const Gemm g, const Sched& S, const Epi& E) {
;     ...
;             PG8_LDB(B0, 1, 0); PG8_LDB(B1, 1, 1); PG8_SCHED; PG8_LDA(At, 1, 0); PG8_STAGE(PG8_SA(0, 1), a2 + hstep, voffA);
;             PG8_WAIT_V(8); PG8_WAIT_L(0); PG8_BAR; PG8_MMA(0, 0, At, B0); PG8_MMA(0, 1, At, B1); PG8_BAR; PG8_SCHED;
;             PG8_LDA(At, 1, 1); PG8_STAGE(PG8_SB(1, 0), b3, voffB); PG8_STAGE(PG8_SB(1, 1), b3 + hstep, voffB); PG8_STAGE(PG8_SA(1, 0), a3, voffA);
;             PG8_WAIT_V(8); PG8_WAIT_L(0); PG8_BAR; PG8_MMA(1, 0, At, B0); PG8_MMA(1, 1, At, B1); PG8_BAR; PG8_SCHED;
;         }
	s_add_i32 s33, 0, 0x18000
	s_add_i32 s44, 0, 0x1c000
	v_add_u32_e32 v160, s33, v135
	v_add_u32_e32 v171, s44, v135
	ds_read_b128 v[140:143], v160
	ds_read_b128 v[144:147], v160 offset:1024
	ds_read_b128 v[148:151], v160 offset:2048
	ds_read_b128 v[160:163], v160 offset:3072
	ds_read_b128 v[164:167], v171
	ds_read_b128 v[172:175], v171 offset:1024
	ds_read_b128 v[176:179], v171 offset:2048
	ds_read_b128 v[180:183], v171 offset:3072
	s_add_u32 s16, s30, 0x160000
	s_addc_u32 s17, s31, 0
	s_mov_b32 m0, s8
	v_lshl_add_u64 v[232:233], s[16:17], 0, v[132:133]
	ds_read_b128 v[184:187], v170 offset:32768
	ds_read_b128 v[188:191], v170 offset:33792
	ds_read_b128 v[192:195], v170 offset:34816
	ds_read_b128 v[210:213], v170 offset:35840
	ds_read_b128 v[214:217], v170 offset:36864
	ds_read_b128 v[218:221], v170 offset:37888
	ds_read_b128 v[222:225], v170 offset:38912
	ds_read_b128 v[226:229], v170 offset:39936
	global_load_lds_dwordx4 v[232:233], off
	s_mov_b32 m0, s9
	v_lshl_add_u64 v[232:233], s[16:17], 0, v[130:131]
	global_load_lds_dwordx4 v[232:233], off
	s_waitcnt vmcnt(8) lgkmcnt(0)
	s_barrier
	v_mfma_f32_16x16x32_bf16 v[126:129], v[140:143], v[184:187], v[126:129]
	v_mfma_f32_16x16x32_bf16 v[122:125], v[148:151], v[184:187], v[122:125]
	v_mfma_f32_16x16x32_bf16 v[118:121], v[140:143], v[192:195], v[118:121]
	v_mfma_f32_16x16x32_bf16 v[106:109], v[148:151], v[192:195], v[106:109]
	v_mfma_f32_16x16x32_bf16 v[98:101], v[140:143], v[214:217], v[98:101]
	v_mfma_f32_16x16x32_bf16 v[90:93], v[148:151], v[214:217], v[90:93]
	v_mfma_f32_16x16x32_bf16 v[82:85], v[140:143], v[222:225], v[82:85]
	v_mfma_f32_16x16x32_bf16 v[74:77], v[148:151], v[222:225], v[74:77]
	v_mfma_f32_16x16x32_bf16 v[126:129], v[144:147], v[188:191], v[126:129]
	v_mfma_f32_16x16x32_bf16 v[122:125], v[160:163], v[188:191], v[122:125]
	v_mfma_f32_16x16x32_bf16 v[118:121], v[144:147], v[210:213], v[118:121]
	v_mfma_f32_16x16x32_bf16 v[106:109], v[160:163], v[210:213], v[106:109]
	v_mfma_f32_16x16x32_bf16 v[98:101], v[144:147], v[218:221], v[98:101]
	v_mfma_f32_16x16x32_bf16 v[90:93], v[160:163], v[218:221], v[90:93]
	v_mfma_f32_16x16x32_bf16 v[82:85], v[144:147], v[226:229], v[82:85]
	v_mfma_f32_16x16x32_bf16 v[74:77], v[160:163], v[226:229], v[74:77]
	v_mfma_f32_16x16x32_bf16 v[114:117], v[164:167], v[184:187], v[114:117]
	v_mfma_f32_16x16x32_bf16 v[110:113], v[176:179], v[184:187], v[110:113]
	v_mfma_f32_16x16x32_bf16 v[102:105], v[164:167], v[192:195], v[102:105]
	v_mfma_f32_16x16x32_bf16 v[94:97], v[176:179], v[192:195], v[94:97]
	v_mfma_f32_16x16x32_bf16 v[86:89], v[164:167], v[214:217], v[86:89]
	v_mfma_f32_16x16x32_bf16 v[78:81], v[176:179], v[214:217], v[78:81]
	v_mfma_f32_16x16x32_bf16 v[70:73], v[164:167], v[222:225], v[70:73]
	v_mfma_f32_16x16x32_bf16 v[66:69], v[176:179], v[222:225], v[66:69]
	v_mfma_f32_16x16x32_bf16 v[114:117], v[172:175], v[188:191], v[114:117]
	v_mfma_f32_16x16x32_bf16 v[110:113], v[180:183], v[188:191], v[110:113]
	v_mfma_f32_16x16x32_bf16 v[102:105], v[172:175], v[210:213], v[102:105]
	v_mfma_f32_16x16x32_bf16 v[94:97], v[180:183], v[210:213], v[94:97]
	v_mfma_f32_16x16x32_bf16 v[86:89], v[172:175], v[218:221], v[86:89]
	v_mfma_f32_16x16x32_bf16 v[78:81], v[180:183], v[218:221], v[78:81]
	v_mfma_f32_16x16x32_bf16 v[70:73], v[172:175], v[226:229], v[70:73]
	v_mfma_f32_16x16x32_bf16 v[66:69], v[180:183], v[226:229], v[66:69]
	s_barrier
	s_add_i32 s16, s33, s4
	v_lshl_add_u64 v[152:153], v[152:153], 0, s[34:35]
	s_mov_b32 m0, s16
	ds_read_b128 v[184:187], v170 offset:49152
	ds_read_b128 v[188:191], v170 offset:50176
	ds_read_b128 v[192:195], v170 offset:51200
	ds_read_b128 v[210:213], v170 offset:52224
	ds_read_b128 v[214:217], v170 offset:53248
	ds_read_b128 v[218:221], v170 offset:54272
	ds_read_b128 v[222:225], v170 offset:55296
	ds_read_b128 v[226:229], v170 offset:56320
	global_load_lds_dwordx4 v[152:153], off
	s_add_i32 m0, s16, 0x2000
	s_add_u32 s0, s0, 0x160080
	v_lshl_add_u64 v[152:153], v[168:169], 0, s[34:35]
	s_addc_u32 s1, s1, 0
	s_add_i32 s16, s44, s4
	global_load_lds_dwordx4 v[152:153], off
	s_mov_b32 m0, s16
	v_lshl_add_u64 v[152:153], s[0:1], 0, v[132:133]
	global_load_lds_dwordx4 v[152:153], off
	s_add_i32 m0, s16, 0x2000
	v_lshl_add_u64 v[152:153], s[0:1], 0, v[130:131]
	global_load_lds_dwordx4 v[152:153], off
	s_mov_b32 m0, s10
	v_lshl_add_u64 v[152:153], v[196:197], 0, s[34:35]
	global_load_lds_dwordx4 v[152:153], off
	s_mov_b32 m0, s11
	v_lshl_add_u64 v[152:153], v[230:231], 0, s[34:35]
	global_load_lds_dwordx4 v[152:153], off
	s_waitcnt vmcnt(8) lgkmcnt(0)
	s_barrier
	v_mfma_f32_16x16x32_bf16 v[62:65], v[140:143], v[184:187], v[62:65]
	v_mfma_f32_16x16x32_bf16 v[58:61], v[148:151], v[184:187], v[58:61]
	v_mfma_f32_16x16x32_bf16 v[50:53], v[140:143], v[192:195], v[50:53]
	v_mfma_f32_16x16x32_bf16 v[42:45], v[148:151], v[192:195], v[42:45]
	v_mfma_f32_16x16x32_bf16 v[34:37], v[140:143], v[214:217], v[34:37]
	v_mfma_f32_16x16x32_bf16 v[26:29], v[148:151], v[214:217], v[26:29]
	v_mfma_f32_16x16x32_bf16 v[18:21], v[140:143], v[222:225], v[18:21]
	v_mfma_f32_16x16x32_bf16 v[10:13], v[148:151], v[222:225], v[10:13]
	v_mfma_f32_16x16x32_bf16 v[62:65], v[144:147], v[188:191], v[62:65]
	v_mfma_f32_16x16x32_bf16 v[58:61], v[160:163], v[188:191], v[58:61]
	v_mfma_f32_16x16x32_bf16 v[50:53], v[144:147], v[210:213], v[50:53]
	v_mfma_f32_16x16x32_bf16 v[42:45], v[160:163], v[210:213], v[42:45]
	v_mfma_f32_16x16x32_bf16 v[34:37], v[144:147], v[218:221], v[34:37]
	v_mfma_f32_16x16x32_bf16 v[26:29], v[160:163], v[218:221], v[26:29]
	v_mfma_f32_16x16x32_bf16 v[18:21], v[144:147], v[226:229], v[18:21]
	v_mfma_f32_16x16x32_bf16 v[10:13], v[160:163], v[226:229], v[10:13]
	v_mfma_f32_16x16x32_bf16 v[54:57], v[164:167], v[184:187], v[54:57]
	v_mfma_f32_16x16x32_bf16 v[46:49], v[176:179], v[184:187], v[46:49]
	v_mfma_f32_16x16x32_bf16 v[38:41], v[164:167], v[192:195], v[38:41]
	v_mfma_f32_16x16x32_bf16 v[30:33], v[176:179], v[192:195], v[30:33]
	v_mfma_f32_16x16x32_bf16 v[22:25], v[164:167], v[214:217], v[22:25]
	v_mfma_f32_16x16x32_bf16 v[14:17], v[176:179], v[214:217], v[14:17]
	v_mfma_f32_16x16x32_bf16 v[6:9], v[164:167], v[222:225], v[6:9]
	v_mfma_f32_16x16x32_bf16 v[2:5], v[176:179], v[222:225], v[2:5]
	v_mfma_f32_16x16x32_bf16 v[54:57], v[172:175], v[188:191], v[54:57]
	v_mfma_f32_16x16x32_bf16 v[46:49], v[180:183], v[188:191], v[46:49]
	v_mfma_f32_16x16x32_bf16 v[38:41], v[172:175], v[210:213], v[38:41]
	v_mfma_f32_16x16x32_bf16 v[30:33], v[180:183], v[210:213], v[30:33]
	v_mfma_f32_16x16x32_bf16 v[22:25], v[172:175], v[218:221], v[22:25]
	v_mfma_f32_16x16x32_bf16 v[14:17], v[180:183], v[218:221], v[14:17]
	v_mfma_f32_16x16x32_bf16 v[6:9], v[172:175], v[226:229], v[6:9]
	v_mfma_f32_16x16x32_bf16 v[2:5], v[180:183], v[226:229], v[2:5]
	s_barrier
	s_add_i32 s82, s82, 2
	s_add_u32 s79, s79, 0x100
	s_addc_u32 s92, s92, 0
	s_cmpk_gt_u32 s82, 0x55
	s_mov_b64 s[44:45], s[46:47]
	s_cbranch_scc0 .LBB0_392
;     __device__ bool next(int i, Unit& u) const { const int idx = i * G + c; if (idx >= 64) return false; u.kp = idx & 3; u.pn = (idx >> 2) & 7; u.pm = 192 + (idx >> 5); return true; }
; #define PG8_STAGE(bufoff, gbase, voff) do { _Pragma("unroll") for (int _i = 0; _i < 2; ++_i) \
;         __builtin_amdgcn_global_load_lds((const unsigned*)((const char*)(gbase) + (voff)[_i]), (LAS unsigned*)(lds + (bufoff) + ldsw + _i * 8192), 16, 0, 0); } while (0)
; #define PG8_LDA(dst, b, h) do { _Pragma("unroll") for (int m = 0; m < 4; ++m) _Pragma("unroll") for (int k = 0; k < 2; ++k) dst[m][k] = *(const LAS bf16x8*)(lds + PG8_SA(b, h) + aoff + m * 2048 + k * 1024); } while (0)
; #define PG8_LDB(dst, b, h) do { _Pragma("unroll") for (int n = 0; n < 2; ++n) _Pragma("unroll") for (int k = 0; k < 2; ++k) dst[n][k] = *(const LAS bf16x8*)(lds + PG8_SB(b, h) + boff + n * 2048 + k * 1024); } while (0)
; #define PG8_WAIT_V(n) asm volatile("s_waitcnt vmcnt(" #n ")" ::: "memory")
; #define PG8_WAIT_L(n) asm volatile("s_waitcnt lgkmcnt(" #n ")" ::: "memory")
; template <class Epi, class Sched = StaticOrder, bool ALIGN_EPI = true>
; __device__ __forceinline__ void gemm_phase(LAS unsigned char* lds, const Gemm g, const Sched& S, const Epi& E) {
;     ...
;         const bool has_next = S.next(ui + 1, nxt);
;         const char* nA = has_next ? (const char*)g.A + (size_t)nxt.pm * tstep + (size_t)nxt.kp * K * 2 : cA; const char* nB = has_next ? (const char*)g.Bt + (size_t)nxt.pn * tstep + (size_t)nxt.kp * K * 2 : cB;
;         for (int t = 0; t < nt; t += 2) {
;             const bool last = (t == nt - 2);
;             const char* a1 = cA + (size_t)(t + 1) * kstep;
;             const char* a2 = last ? nA : cA + (size_t)(t + 2) * kstep; const char* b2 = last ? nB : cB + (size_t)(t + 2) * kstep;
;             const char* a3 = a2 + kstep; const char* b3 = b2 + kstep;
;             PG8_LDB(B0, 0, 0); PG8_LDB(B1, 0, 1); PG8_SCHED; PG8_LDA(At, 0, 0); PG8_STAGE(PG8_SA(1, 1), a1 + hstep, voffA);
;             PG8_WAIT_V(8); PG8_WAIT_L(0); PG8_BAR; PG8_MMA(0, 0, At, B0); PG8_MMA(0, 1, At, B1); PG8_BAR; PG8_SCHED;
;             PG8_LDA(At, 0, 1); PG8_STAGE(PG8_SB(0, 0), b2, voffB); PG8_STAGE(PG8_SB(0, 1), b2 + hstep, voffB); PG8_STAGE(PG8_SA(0, 0), a2, voffA);
;             PG8_WAIT_V(8); PG8_WAIT_L(0); PG8_BAR; PG8_MMA(1, 0, At, B0); PG8_MMA(1, 1, At, B1); PG8_BAR; PG8_SCHED;
.LBB0_392:
	s_add_u32 s46, s44, 0x100
	s_addc_u32 s47, s45, 0
	s_add_i32 s16, 0, 0x10000
	s_cmpk_eq_i32 s82, 0x54
	s_cselect_b32 s31, s37, s47
	s_cselect_b32 s30, s36, s46
	v_add_u32_e32 v152, s16, v135
	s_cselect_b32 s1, s43, s92
	s_cselect_b32 s0, s42, s79
	s_add_i32 s33, 0, 0x14000
	ds_read_b128 v[140:143], v152
	ds_read_b128 v[144:147], v152 offset:1024
	ds_read_b128 v[148:151], v152 offset:2048
	ds_read_b128 v[160:163], v152 offset:3072
	v_add_u32_e32 v152, s33, v135
	ds_read_b128 v[164:167], v152
	ds_read_b128 v[172:175], v152 offset:1024
	ds_read_b128 v[176:179], v152 offset:2048
	ds_read_b128 v[180:183], v152 offset:3072
	v_lshl_add_u64 v[152:153], s[44:45], 0, v[136:137]
	s_add_i32 m0, s6, 0xc000
	ds_read_b128 v[184:187], v170
	ds_read_b128 v[188:191], v170 offset:1024
	ds_read_b128 v[192:195], v170 offset:2048
	ds_read_b128 v[210:213], v170 offset:3072
	ds_read_b128 v[214:217], v170 offset:4096
	ds_read_b128 v[218:221], v170 offset:5120
	ds_read_b128 v[222:225], v170 offset:6144
	ds_read_b128 v[226:229], v170 offset:7168
	global_load_lds_dwordx4 v[152:153], off
	s_add_i32 m0, s6, 0xe000
	v_lshl_add_u64 v[152:153], s[44:45], 0, v[138:139]
	global_load_lds_dwordx4 v[152:153], off
	s_waitcnt vmcnt(8) lgkmcnt(0)
	s_barrier
	v_mfma_f32_16x16x32_bf16 v[126:129], v[140:143], v[184:187], v[126:129]
	v_mfma_f32_16x16x32_bf16 v[122:125], v[148:151], v[184:187], v[122:125]
	v_mfma_f32_16x16x32_bf16 v[118:121], v[140:143], v[192:195], v[118:121]
	v_mfma_f32_16x16x32_bf16 v[106:109], v[148:151], v[192:195], v[106:109]
	v_mfma_f32_16x16x32_bf16 v[98:101], v[140:143], v[214:217], v[98:101]
	v_mfma_f32_16x16x32_bf16 v[90:93], v[148:151], v[214:217], v[90:93]
	v_mfma_f32_16x16x32_bf16 v[82:85], v[140:143], v[222:225], v[82:85]
	v_mfma_f32_16x16x32_bf16 v[74:77], v[148:151], v[222:225], v[74:77]
	v_mfma_f32_16x16x32_bf16 v[126:129], v[144:147], v[188:191], v[126:129]
	v_mfma_f32_16x16x32_bf16 v[122:125], v[160:163], v[188:191], v[122:125]
	v_mfma_f32_16x16x32_bf16 v[118:121], v[144:147], v[210:213], v[118:121]
	v_mfma_f32_16x16x32_bf16 v[106:109], v[160:163], v[210:213], v[106:109]
	v_mfma_f32_16x16x32_bf16 v[98:101], v[144:147], v[218:221], v[98:101]
	v_mfma_f32_16x16x32_bf16 v[90:93], v[160:163], v[218:221], v[90:93]
	v_mfma_f32_16x16x32_bf16 v[82:85], v[144:147], v[226:229], v[82:85]
	v_mfma_f32_16x16x32_bf16 v[74:77], v[160:163], v[226:229], v[74:77]
	v_mfma_f32_16x16x32_bf16 v[114:117], v[164:167], v[184:187], v[114:117]
	v_mfma_f32_16x16x32_bf16 v[110:113], v[176:179], v[184:187], v[110:113]
	v_mfma_f32_16x16x32_bf16 v[102:105], v[164:167], v[192:195], v[102:105]
	v_mfma_f32_16x16x32_bf16 v[94:97], v[176:179], v[192:195], v[94:97]
	v_mfma_f32_16x16x32_bf16 v[86:89], v[164:167], v[214:217], v[86:89]
	v_mfma_f32_16x16x32_bf16 v[78:81], v[176:179], v[214:217], v[78:81]
	v_mfma_f32_16x16x32_bf16 v[70:73], v[164:167], v[222:225], v[70:73]
	v_mfma_f32_16x16x32_bf16 v[66:69], v[176:179], v[222:225], v[66:69]
	v_mfma_f32_16x16x32_bf16 v[114:117], v[172:175], v[188:191], v[114:117]
	v_mfma_f32_16x16x32_bf16 v[110:113], v[180:183], v[188:191], v[110:113]
	v_mfma_f32_16x16x32_bf16 v[102:105], v[172:175], v[210:213], v[102:105]
	v_mfma_f32_16x16x32_bf16 v[94:97], v[180:183], v[210:213], v[94:97]
	v_mfma_f32_16x16x32_bf16 v[86:89], v[172:175], v[218:221], v[86:89]
	v_mfma_f32_16x16x32_bf16 v[78:81], v[180:183], v[218:221], v[78:81]
	v_mfma_f32_16x16x32_bf16 v[70:73], v[172:175], v[226:229], v[70:73]
	v_mfma_f32_16x16x32_bf16 v[66:69], v[180:183], v[226:229], v[66:69]
	s_barrier
	s_add_i32 s16, s16, s4
	v_lshl_add_u64 v[152:153], s[0:1], 0, v[132:133]
	s_mov_b32 m0, s16
	ds_read_b128 v[184:187], v170 offset:16384
	ds_read_b128 v[188:191], v170 offset:17408
	ds_read_b128 v[192:195], v170 offset:18432
	ds_read_b128 v[210:213], v170 offset:19456
	ds_read_b128 v[214:217], v170 offset:20480
	ds_read_b128 v[218:221], v170 offset:21504
	ds_read_b128 v[222:225], v170 offset:22528
	ds_read_b128 v[226:229], v170 offset:23552
	global_load_lds_dwordx4 v[152:153], off
	s_add_i32 m0, s16, 0x2000
	s_add_u32 s16, s0, 0x160000
	v_lshl_add_u64 v[168:169], s[0:1], 0, v[130:131]
	s_addc_u32 s17, s1, 0
	s_add_i32 s33, s33, s4
	global_load_lds_dwordx4 v[168:169], off
	v_lshl_add_u64 v[196:197], s[16:17], 0, v[132:133]
	s_mov_b32 m0, s33
	v_lshl_add_u64 v[230:231], s[30:31], 0, v[130:131]
	global_load_lds_dwordx4 v[196:197], off
	s_add_i32 m0, s33, 0x2000
	v_lshl_add_u64 v[196:197], s[16:17], 0, v[130:131]
	global_load_lds_dwordx4 v[196:197], off
	s_mov_b32 m0, s6
	v_lshl_add_u64 v[196:197], s[30:31], 0, v[132:133]
	global_load_lds_dwordx4 v[196:197], off
	s_mov_b32 m0, s7
	s_nop 0
	global_load_lds_dwordx4 v[230:231], off
	s_waitcnt vmcnt(8) lgkmcnt(0)
	s_barrier
; #define PG8_STAGE(bufoff, gbase, voff) do { _Pragma("unroll") for (int _i = 0; _i < 2; ++_i) \
;         __builtin_amdgcn_global_load_lds((const unsigned*)((const char*)(gbase) + (voff)[_i]), (LAS unsigned*)(lds + (bufoff) + ldsw + _i * 8192), 16, 0, 0); } while (0)
; #define PG8_LDA(dst, b, h) do { _Pragma("unroll") for (int m = 0; m < 4; ++m) _Pragma("unroll") for (int k = 0; k < 2; ++k) dst[m][k] = *(const LAS bf16x8*)(lds + PG8_SA(b, h) + aoff + m * 2048 + k * 1024); } while (0)
; #define PG8_LDB(dst, b, h) do { _Pragma("unroll") for (int n = 0; n < 2; ++n) _Pragma("unroll") for (int k = 0; k < 2; ++k) dst[n][k] = *(const LAS bf16x8*)(lds + PG8_SB(b, h) + boff + n * 2048 + k * 1024); } while (0)
; #define PG8_MMA(ai, bj, At, Bt) do { __builtin_amdgcn_s_setprio(1); _Pragma("unroll") for (int m = 0; m < 4; ++m) _Pragma("unroll") for (int n = 0; n < 2; ++n) _Pragma("unroll") for (int k = 0; k < 2; ++k) \
;         acc[ai][bj][m][n] = __builtin_amdgcn_mfma_f32_16x16x32_bf16(Bt[n][k], At[m][k], acc[ai][bj][m][n], 0, 0, 0); __builtin_amdgcn_s_setprio(0); } while (0)
; #define PG8_WAIT_V(n) asm volatile("s_waitcnt vmcnt(" #n ")" ::: "memory")
; #define PG8_WAIT_L(n) asm volatile("s_waitcnt lgkmcnt(" #n ")" ::: "memory")
; #define PG8_BAR __builtin_amdgcn_s_barrier()
; #define PG8_SCHED __builtin_amdgcn_sched_barrier(0)
; template <class Epi, class Sched = StaticOrder, bool ALIGN_EPI = true>
; __device__ __forceinline__ void gemm_phase(LAS unsigned char* lds, const Gemm g, const Sched& S, const Epi& E) {
;     ...
;             PG8_WAIT_V(8); PG8_WAIT_L(0); PG8_BAR; PG8_MMA(1, 0, At, B0); PG8_MMA(1, 1, At, B1); PG8_BAR; PG8_SCHED;
;             PG8_LDB(B0, 1, 0); PG8_LDB(B1, 1, 1); PG8_SCHED; PG8_LDA(At, 1, 0); PG8_STAGE(PG8_SA(0, 1), a2 + hstep, voffA);
;             PG8_WAIT_V(8); PG8_WAIT_L(0); PG8_BAR; PG8_MMA(0, 0, At, B0); PG8_MMA(0, 1, At, B1); PG8_BAR; PG8_SCHED;
	v_mfma_f32_16x16x32_bf16 v[62:65], v[140:143], v[184:187], v[62:65]
	v_mfma_f32_16x16x32_bf16 v[58:61], v[148:151], v[184:187], v[58:61]
	v_mfma_f32_16x16x32_bf16 v[50:53], v[140:143], v[192:195], v[50:53]
	v_mfma_f32_16x16x32_bf16 v[42:45], v[148:151], v[192:195], v[42:45]
	v_mfma_f32_16x16x32_bf16 v[34:37], v[140:143], v[214:217], v[34:37]
	v_mfma_f32_16x16x32_bf16 v[26:29], v[148:151], v[214:217], v[26:29]
	v_mfma_f32_16x16x32_bf16 v[18:21], v[140:143], v[222:225], v[18:21]
	v_mfma_f32_16x16x32_bf16 v[10:13], v[148:151], v[222:225], v[10:13]
	v_mfma_f32_16x16x32_bf16 v[62:65], v[144:147], v[188:191], v[62:65]
	v_mfma_f32_16x16x32_bf16 v[58:61], v[160:163], v[188:191], v[58:61]
	v_mfma_f32_16x16x32_bf16 v[50:53], v[144:147], v[210:213], v[50:53]
	v_mfma_f32_16x16x32_bf16 v[42:45], v[160:163], v[210:213], v[42:45]
	v_mfma_f32_16x16x32_bf16 v[34:37], v[144:147], v[218:221], v[34:37]
	v_mfma_f32_16x16x32_bf16 v[26:29], v[160:163], v[218:221], v[26:29]
	v_mfma_f32_16x16x32_bf16 v[18:21], v[144:147], v[226:229], v[18:21]
	v_mfma_f32_16x16x32_bf16 v[10:13], v[160:163], v[226:229], v[10:13]
	v_mfma_f32_16x16x32_bf16 v[54:57], v[164:167], v[184:187], v[54:57]
	v_mfma_f32_16x16x32_bf16 v[46:49], v[176:179], v[184:187], v[46:49]
	v_mfma_f32_16x16x32_bf16 v[38:41], v[164:167], v[192:195], v[38:41]
	v_mfma_f32_16x16x32_bf16 v[30:33], v[176:179], v[192:195], v[30:33]
	v_mfma_f32_16x16x32_bf16 v[22:25], v[164:167], v[214:217], v[22:25]
	v_mfma_f32_16x16x32_bf16 v[14:17], v[176:179], v[214:217], v[14:17]
	v_mfma_f32_16x16x32_bf16 v[6:9], v[164:167], v[222:225], v[6:9]
	v_mfma_f32_16x16x32_bf16 v[2:5], v[176:179], v[222:225], v[2:5]
	v_mfma_f32_16x16x32_bf16 v[54:57], v[172:175], v[188:191], v[54:57]
	v_mfma_f32_16x16x32_bf16 v[46:49], v[180:183], v[188:191], v[46:49]
	v_mfma_f32_16x16x32_bf16 v[38:41], v[172:175], v[210:213], v[38:41]
	v_mfma_f32_16x16x32_bf16 v[30:33], v[180:183], v[210:213], v[30:33]
	v_mfma_f32_16x16x32_bf16 v[22:25], v[172:175], v[218:221], v[22:25]
	v_mfma_f32_16x16x32_bf16 v[14:17], v[180:183], v[218:221], v[14:17]
	v_mfma_f32_16x16x32_bf16 v[6:9], v[172:175], v[226:229], v[6:9]
	v_mfma_f32_16x16x32_bf16 v[2:5], v[180:183], v[226:229], v[2:5]
	s_barrier
	s_add_i32 s33, 0, 0x18000
	s_add_i32 s44, 0, 0x1c000
	v_add_u32_e32 v160, s33, v135
	v_add_u32_e32 v171, s44, v135
	ds_read_b128 v[140:143], v160
	ds_read_b128 v[144:147], v160 offset:1024
	ds_read_b128 v[148:151], v160 offset:2048
	ds_read_b128 v[160:163], v160 offset:3072
	ds_read_b128 v[164:167], v171
	ds_read_b128 v[172:175], v171 offset:1024
	ds_read_b128 v[176:179], v171 offset:2048
	ds_read_b128 v[180:183], v171 offset:3072
	s_add_u32 s16, s30, 0x160000
	s_addc_u32 s17, s31, 0
	s_mov_b32 m0, s8
	v_lshl_add_u64 v[232:233], s[16:17], 0, v[132:133]
	ds_read_b128 v[184:187], v170 offset:32768
	ds_read_b128 v[188:191], v170 offset:33792
	ds_read_b128 v[192:195], v170 offset:34816
	ds_read_b128 v[210:213], v170 offset:35840
	ds_read_b128 v[214:217], v170 offset:36864
	ds_read_b128 v[218:221], v170 offset:37888
	ds_read_b128 v[222:225], v170 offset:38912
	ds_read_b128 v[226:229], v170 offset:39936
	global_load_lds_dwordx4 v[232:233], off
	s_mov_b32 m0, s9
	v_lshl_add_u64 v[232:233], s[16:17], 0, v[130:131]
	global_load_lds_dwordx4 v[232:233], off
	s_waitcnt vmcnt(8) lgkmcnt(0)
	s_barrier
	v_mfma_f32_16x16x32_bf16 v[126:129], v[140:143], v[184:187], v[126:129]
	v_mfma_f32_16x16x32_bf16 v[122:125], v[148:151], v[184:187], v[122:125]
	v_mfma_f32_16x16x32_bf16 v[118:121], v[140:143], v[192:195], v[118:121]
	v_mfma_f32_16x16x32_bf16 v[106:109], v[148:151], v[192:195], v[106:109]
	v_mfma_f32_16x16x32_bf16 v[98:101], v[140:143], v[214:217], v[98:101]
	v_mfma_f32_16x16x32_bf16 v[90:93], v[148:151], v[214:217], v[90:93]
	v_mfma_f32_16x16x32_bf16 v[82:85], v[140:143], v[222:225], v[82:85]
	v_mfma_f32_16x16x32_bf16 v[74:77], v[148:151], v[222:225], v[74:77]
	v_mfma_f32_16x16x32_bf16 v[126:129], v[144:147], v[188:191], v[126:129]
	v_mfma_f32_16x16x32_bf16 v[122:125], v[160:163], v[188:191], v[122:125]
	v_mfma_f32_16x16x32_bf16 v[118:121], v[144:147], v[210:213], v[118:121]
	v_mfma_f32_16x16x32_bf16 v[106:109], v[160:163], v[210:213], v[106:109]
	v_mfma_f32_16x16x32_bf16 v[98:101], v[144:147], v[218:221], v[98:101]
	v_mfma_f32_16x16x32_bf16 v[90:93], v[160:163], v[218:221], v[90:93]
	v_mfma_f32_16x16x32_bf16 v[82:85], v[144:147], v[226:229], v[82:85]
	v_mfma_f32_16x16x32_bf16 v[74:77], v[160:163], v[226:229], v[74:77]
	v_mfma_f32_16x16x32_bf16 v[114:117], v[164:167], v[184:187], v[114:117]
	v_mfma_f32_16x16x32_bf16 v[110:113], v[176:179], v[184:187], v[110:113]
	v_mfma_f32_16x16x32_bf16 v[102:105], v[164:167], v[192:195], v[102:105]
	v_mfma_f32_16x16x32_bf16 v[94:97], v[176:179], v[192:195], v[94:97]
	v_mfma_f32_16x16x32_bf16 v[86:89], v[164:167], v[214:217], v[86:89]
	v_mfma_f32_16x16x32_bf16 v[78:81], v[176:179], v[214:217], v[78:81]
	v_mfma_f32_16x16x32_bf16 v[70:73], v[164:167], v[222:225], v[70:73]
	v_mfma_f32_16x16x32_bf16 v[66:69], v[176:179], v[222:225], v[66:69]
	v_mfma_f32_16x16x32_bf16 v[114:117], v[172:175], v[188:191], v[114:117]
	v_mfma_f32_16x16x32_bf16 v[110:113], v[180:183], v[188:191], v[110:113]
	v_mfma_f32_16x16x32_bf16 v[102:105], v[172:175], v[210:213], v[102:105]
	v_mfma_f32_16x16x32_bf16 v[94:97], v[180:183], v[210:213], v[94:97]
	v_mfma_f32_16x16x32_bf16 v[86:89], v[172:175], v[218:221], v[86:89]
	v_mfma_f32_16x16x32_bf16 v[78:81], v[180:183], v[218:221], v[78:81]
	v_mfma_f32_16x16x32_bf16 v[70:73], v[172:175], v[226:229], v[70:73]
	v_mfma_f32_16x16x32_bf16 v[66:69], v[180:183], v[226:229], v[66:69]
	s_barrier
; #define PG8_STAGE(bufoff, gbase, voff) do { _Pragma("unroll") for (int _i = 0; _i < 2; ++_i) \
;         __builtin_amdgcn_global_load_lds((const unsigned*)((const char*)(gbase) + (voff)[_i]), (LAS unsigned*)(lds + (bufoff) + ldsw + _i * 8192), 16, 0, 0); } while (0)
; #define PG8_LDA(dst, b, h) do { _Pragma("unroll") for (int m = 0; m < 4; ++m) _Pragma("unroll") for (int k = 0; k < 2; ++k) dst[m][k] = *(const LAS bf16x8*)(lds + PG8_SA(b, h) + aoff + m * 2048 + k * 1024); } while (0)
; #define PG8_MMA(ai, bj, At, Bt) do { __builtin_amdgcn_s_setprio(1); _Pragma("unroll") for (int m = 0; m < 4; ++m) _Pragma("unroll") for (int n = 0; n < 2; ++n) _Pragma("unroll") for (int k = 0; k < 2; ++k) \
;         acc[ai][bj][m][n] = __builtin_amdgcn_mfma_f32_16x16x32_bf16(Bt[n][k], At[m][k], acc[ai][bj][m][n], 0, 0, 0); __builtin_amdgcn_s_setprio(0); } while (0)
; #define PG8_WAIT_V(n) asm volatile("s_waitcnt vmcnt(" #n ")" ::: "memory")
; #define PG8_WAIT_L(n) asm volatile("s_waitcnt lgkmcnt(" #n ")" ::: "memory")
; #define PG8_BAR __builtin_amdgcn_s_barrier()
; #define PG8_SCHED __builtin_amdgcn_sched_barrier(0)
; template <class Epi, class Sched = StaticOrder, bool ALIGN_EPI = true>
; __device__ __forceinline__ void gemm_phase(LAS unsigned char* lds, const Gemm g, const Sched& S, const Epi& E) {
;     ...
;             PG8_LDA(At, 1, 1); PG8_STAGE(PG8_SB(1, 0), b3, voffB); PG8_STAGE(PG8_SB(1, 1), b3 + hstep, voffB); PG8_STAGE(PG8_SA(1, 0), a3, voffA);
;             PG8_WAIT_V(8); PG8_WAIT_L(0); PG8_BAR; PG8_MMA(1, 0, At, B0); PG8_MMA(1, 1, At, B1); PG8_BAR; PG8_SCHED;
;         }
	s_add_i32 s16, s33, s4
	v_lshl_add_u64 v[152:153], v[152:153], 0, s[34:35]
	s_mov_b32 m0, s16
	ds_read_b128 v[184:187], v170 offset:49152
	ds_read_b128 v[188:191], v170 offset:50176
	ds_read_b128 v[192:195], v170 offset:51200
	ds_read_b128 v[210:213], v170 offset:52224
	ds_read_b128 v[214:217], v170 offset:53248
	ds_read_b128 v[218:221], v170 offset:54272
	ds_read_b128 v[222:225], v170 offset:55296
	ds_read_b128 v[226:229], v170 offset:56320
	global_load_lds_dwordx4 v[152:153], off
	s_add_i32 m0, s16, 0x2000
	s_add_u32 s0, s0, 0x160080
	v_lshl_add_u64 v[152:153], v[168:169], 0, s[34:35]
	s_addc_u32 s1, s1, 0
	s_add_i32 s16, s44, s4
	global_load_lds_dwordx4 v[152:153], off
	s_mov_b32 m0, s16
	v_lshl_add_u64 v[152:153], s[0:1], 0, v[132:133]
	global_load_lds_dwordx4 v[152:153], off
	s_add_i32 m0, s16, 0x2000
	v_lshl_add_u64 v[152:153], s[0:1], 0, v[130:131]
	global_load_lds_dwordx4 v[152:153], off
	s_mov_b32 m0, s10
	v_lshl_add_u64 v[152:153], v[196:197], 0, s[34:35]
	global_load_lds_dwordx4 v[152:153], off
	s_mov_b32 m0, s11
	v_lshl_add_u64 v[152:153], v[230:231], 0, s[34:35]
	global_load_lds_dwordx4 v[152:153], off
	s_waitcnt vmcnt(8) lgkmcnt(0)
	s_barrier
	v_mfma_f32_16x16x32_bf16 v[62:65], v[140:143], v[184:187], v[62:65]
	v_mfma_f32_16x16x32_bf16 v[58:61], v[148:151], v[184:187], v[58:61]
	v_mfma_f32_16x16x32_bf16 v[50:53], v[140:143], v[192:195], v[50:53]
	v_mfma_f32_16x16x32_bf16 v[42:45], v[148:151], v[192:195], v[42:45]
	v_mfma_f32_16x16x32_bf16 v[34:37], v[140:143], v[214:217], v[34:37]
	v_mfma_f32_16x16x32_bf16 v[26:29], v[148:151], v[214:217], v[26:29]
	v_mfma_f32_16x16x32_bf16 v[18:21], v[140:143], v[222:225], v[18:21]
	v_mfma_f32_16x16x32_bf16 v[10:13], v[148:151], v[222:225], v[10:13]
	v_mfma_f32_16x16x32_bf16 v[62:65], v[144:147], v[188:191], v[62:65]
	v_mfma_f32_16x16x32_bf16 v[58:61], v[160:163], v[188:191], v[58:61]
	v_mfma_f32_16x16x32_bf16 v[50:53], v[144:147], v[210:213], v[50:53]
	v_mfma_f32_16x16x32_bf16 v[42:45], v[160:163], v[210:213], v[42:45]
	v_mfma_f32_16x16x32_bf16 v[34:37], v[144:147], v[218:221], v[34:37]
	v_mfma_f32_16x16x32_bf16 v[26:29], v[160:163], v[218:221], v[26:29]
	v_mfma_f32_16x16x32_bf16 v[18:21], v[144:147], v[226:229], v[18:21]
	v_mfma_f32_16x16x32_bf16 v[10:13], v[160:163], v[226:229], v[10:13]
	v_mfma_f32_16x16x32_bf16 v[54:57], v[164:167], v[184:187], v[54:57]
	v_mfma_f32_16x16x32_bf16 v[46:49], v[176:179], v[184:187], v[46:49]
	v_mfma_f32_16x16x32_bf16 v[38:41], v[164:167], v[192:195], v[38:41]
	v_mfma_f32_16x16x32_bf16 v[30:33], v[176:179], v[192:195], v[30:33]
	v_mfma_f32_16x16x32_bf16 v[22:25], v[164:167], v[214:217], v[22:25]
	v_mfma_f32_16x16x32_bf16 v[14:17], v[176:179], v[214:217], v[14:17]
	v_mfma_f32_16x16x32_bf16 v[6:9], v[164:167], v[222:225], v[6:9]
	v_mfma_f32_16x16x32_bf16 v[2:5], v[176:179], v[222:225], v[2:5]
	v_mfma_f32_16x16x32_bf16 v[54:57], v[172:175], v[188:191], v[54:57]
	v_mfma_f32_16x16x32_bf16 v[46:49], v[180:183], v[188:191], v[46:49]
	v_mfma_f32_16x16x32_bf16 v[38:41], v[172:175], v[210:213], v[38:41]
	v_mfma_f32_16x16x32_bf16 v[30:33], v[180:183], v[210:213], v[30:33]
	v_mfma_f32_16x16x32_bf16 v[22:25], v[172:175], v[218:221], v[22:25]
	v_mfma_f32_16x16x32_bf16 v[14:17], v[180:183], v[218:221], v[14:17]
	v_mfma_f32_16x16x32_bf16 v[6:9], v[172:175], v[226:229], v[6:9]
	v_mfma_f32_16x16x32_bf16 v[2:5], v[180:183], v[226:229], v[2:5]
	s_barrier
	s_add_i32 s82, s82, 2
	s_add_u32 s79, s79, 0x100
	s_addc_u32 s92, s92, 0
	s_cmpk_gt_u32 s82, 0x55
	s_mov_b64 s[44:45], s[46:47]
	s_cbranch_scc0 .LBB0_392

; #define PG8_STAGE(bufoff, gbase, voff) do { _Pragma("unroll") for (int _i = 0; _i < 2; ++_i) \
;         __builtin_amdgcn_global_load_lds((const unsigned*)((const char*)(gbase) + (voff)[_i]), (LAS unsigned*)(lds + (bufoff) + ldsw + _i * 8192), 16, 0, 0); } while (0)
; #define PG8_LDA(dst, b, h) do { _Pragma("unroll") for (int m = 0; m < 4; ++m) _Pragma("unroll") for (int k = 0; k < 2; ++k) dst[m][k] = *(const LAS bf16x8*)(lds + PG8_SA(b, h) + aoff + m * 2048 + k * 1024); } while (0)
; #define PG8_LDB(dst, b, h) do { _Pragma("unroll") for (int n = 0; n < 2; ++n) _Pragma("unroll") for (int k = 0; k < 2; ++k) dst[n][k] = *(const LAS bf16x8*)(lds + PG8_SB(b, h) + boff + n * 2048 + k * 1024); } while (0)
; #define PG8_MMA(ai, bj, At, Bt) do { __builtin_amdgcn_s_setprio(1); _Pragma("unroll") for (int m = 0; m < 4; ++m) _Pragma("unroll") for (int n = 0; n < 2; ++n) _Pragma("unroll") for (int k = 0; k < 2; ++k) \
;         acc[ai][bj][m][n] = __builtin_amdgcn_mfma_f32_16x16x32_bf16(Bt[n][k], At[m][k], acc[ai][bj][m][n], 0, 0, 0); __builtin_amdgcn_s_setprio(0); } while (0)
; #define PG8_WAIT_V(n) asm volatile("s_waitcnt vmcnt(" #n ")" ::: "memory")
; #define PG8_WAIT_L(n) asm volatile("s_waitcnt lgkmcnt(" #n ")" ::: "memory")
; #define PG8_BAR __builtin_amdgcn_s_barrier()
; #define PG8_SCHED __builtin_amdgcn_sched_barrier(0)
; template <class Epi, class Sched = StaticOrder, bool ALIGN_EPI = true>
; __device__ __forceinline__ void gemm_phase(LAS unsigned char* lds, const Gemm g, const Sched& S, const Epi& E) {
;     ...
;             PG8_LDB(B0, 0, 0); PG8_LDB(B1, 0, 1); PG8_SCHED; PG8_LDA(At, 0, 0); PG8_STAGE(PG8_SA(1, 1), a1 + hstep, voffA);
;             PG8_WAIT_V(8); PG8_WAIT_L(0); PG8_BAR; PG8_MMA(0, 0, At, B0); PG8_MMA(0, 1, At, B1); PG8_BAR; PG8_SCHED;
;             PG8_LDA(At, 0, 1); PG8_STAGE(PG8_SB(0, 0), b2, voffB); PG8_STAGE(PG8_SB(0, 1), b2 + hstep, voffB); PG8_STAGE(PG8_SA(0, 0), a2, voffA);
;             PG8_WAIT_V(8); PG8_WAIT_L(0); PG8_BAR; PG8_MMA(1, 0, At, B0); PG8_MMA(1, 1, At, B1); PG8_BAR; PG8_SCHED;
;     ...
;         for (int a = 0; a < 2; ++a)
; #pragma unroll
;             for (int b = 0; b < 2; ++b)
; #pragma unroll
;                 for (int m = 0; m < 4; ++m)
; #pragma unroll
;                     for (int n = 0; n < 2; ++n) acc[a][b][m][n] = (f32x4){0.f, 0.f, 0.f, 0.f};
.Lmy_nb_467:
	s_add_u32 s16, s44, 0xfff80080
	s_addc_u32 s17, s45, -1
	s_add_i32 s83, 0, 0x10000
	s_cmp_eq_u32 s82, 28
	s_cselect_b32 s49, s10, s17
	s_cselect_b32 s48, s11, s16
	v_add_u32_e32 v142, s83, v144
	s_cselect_b32 s47, s21, vcc_hi
	s_cselect_b32 s46, s31, vcc_lo
	s_add_i32 s33, 0, 0x14000
	ds_read_b128 v[148:151], v142
	ds_read_b128 v[160:163], v142 offset:1024
	ds_read_b128 v[164:167], v142 offset:2048
	ds_read_b128 v[168:171], v142 offset:3072
	v_add_u32_e32 v142, s33, v144
	ds_read_b128 v[172:175], v142
	ds_read_b128 v[176:179], v142 offset:1024
	ds_read_b128 v[180:183], v142 offset:2048
	ds_read_b128 v[184:187], v142 offset:3072
	v_lshl_add_u64 v[142:143], s[44:45], 0, v[138:139]
	s_add_i32 m0, s23, 0xc000
	ds_read_b128 v[188:191], v146
	ds_read_b128 v[192:195], v146 offset:1024
	ds_read_b128 v[210:213], v146 offset:2048
	ds_read_b128 v[214:217], v146 offset:3072
	ds_read_b128 v[218:221], v146 offset:4096
	ds_read_b128 v[222:225], v146 offset:5120
	ds_read_b128 v[226:229], v146 offset:6144
	ds_read_b128 v[230:233], v146 offset:7168
	global_load_lds_dwordx4 v[142:143], off
	s_add_i32 m0, s23, 0xe000
	v_lshl_add_u64 v[142:143], s[44:45], 0, v[140:141]
	global_load_lds_dwordx4 v[142:143], off
	s_waitcnt vmcnt(8) lgkmcnt(0)
	s_barrier
	v_mfma_f32_16x16x32_bf16 v[126:129], v[148:151], v[188:191], 0
	v_mfma_f32_16x16x32_bf16 v[118:121], v[164:167], v[188:191], 0
	v_mfma_f32_16x16x32_bf16 v[110:113], v[148:151], v[210:213], 0
	v_mfma_f32_16x16x32_bf16 v[102:105], v[164:167], v[210:213], 0
	v_mfma_f32_16x16x32_bf16 v[94:97], v[148:151], v[218:221], 0
	v_mfma_f32_16x16x32_bf16 v[86:89], v[164:167], v[218:221], 0
	v_mfma_f32_16x16x32_bf16 v[78:81], v[148:151], v[226:229], 0
	v_mfma_f32_16x16x32_bf16 v[70:73], v[164:167], v[226:229], 0
	v_mfma_f32_16x16x32_bf16 v[126:129], v[160:163], v[192:195], v[126:129]
	v_mfma_f32_16x16x32_bf16 v[118:121], v[168:171], v[192:195], v[118:121]
	v_mfma_f32_16x16x32_bf16 v[110:113], v[160:163], v[214:217], v[110:113]
	v_mfma_f32_16x16x32_bf16 v[102:105], v[168:171], v[214:217], v[102:105]
	v_mfma_f32_16x16x32_bf16 v[94:97], v[160:163], v[222:225], v[94:97]
	v_mfma_f32_16x16x32_bf16 v[86:89], v[168:171], v[222:225], v[86:89]
	v_mfma_f32_16x16x32_bf16 v[78:81], v[160:163], v[230:233], v[78:81]
	v_mfma_f32_16x16x32_bf16 v[70:73], v[168:171], v[230:233], v[70:73]
	v_mfma_f32_16x16x32_bf16 v[122:125], v[172:175], v[188:191], 0
	v_mfma_f32_16x16x32_bf16 v[114:117], v[180:183], v[188:191], 0
	v_mfma_f32_16x16x32_bf16 v[106:109], v[172:175], v[210:213], 0
	v_mfma_f32_16x16x32_bf16 v[98:101], v[180:183], v[210:213], 0
	v_mfma_f32_16x16x32_bf16 v[90:93], v[172:175], v[218:221], 0
	v_mfma_f32_16x16x32_bf16 v[82:85], v[180:183], v[218:221], 0
	v_mfma_f32_16x16x32_bf16 v[74:77], v[172:175], v[226:229], 0
	v_mfma_f32_16x16x32_bf16 v[66:69], v[180:183], v[226:229], 0
	v_mfma_f32_16x16x32_bf16 v[122:125], v[176:179], v[192:195], v[122:125]
	v_mfma_f32_16x16x32_bf16 v[114:117], v[184:187], v[192:195], v[114:117]
	v_mfma_f32_16x16x32_bf16 v[106:109], v[176:179], v[214:217], v[106:109]
	v_mfma_f32_16x16x32_bf16 v[98:101], v[184:187], v[214:217], v[98:101]
	v_mfma_f32_16x16x32_bf16 v[90:93], v[176:179], v[222:225], v[90:93]
	v_mfma_f32_16x16x32_bf16 v[82:85], v[184:187], v[222:225], v[82:85]
	v_mfma_f32_16x16x32_bf16 v[74:77], v[176:179], v[230:233], v[74:77]
	v_mfma_f32_16x16x32_bf16 v[66:69], v[184:187], v[230:233], v[66:69]
	s_barrier
	s_add_i32 s16, s83, s92
	v_lshl_add_u64 v[142:143], s[46:47], 0, v[134:135]
	s_mov_b32 m0, s16
	ds_read_b128 v[188:191], v146 offset:16384
	ds_read_b128 v[192:195], v146 offset:17408
	ds_read_b128 v[210:213], v146 offset:18432
	ds_read_b128 v[214:217], v146 offset:19456
	ds_read_b128 v[218:221], v146 offset:20480
	ds_read_b128 v[222:225], v146 offset:21504
	ds_read_b128 v[226:229], v146 offset:22528
	ds_read_b128 v[230:233], v146 offset:23552
	global_load_lds_dwordx4 v[142:143], off
	s_add_i32 m0, s16, 0x2000
	s_add_u32 s16, s46, 0x80000
	v_lshl_add_u64 v[152:153], s[46:47], 0, v[130:131]
	s_addc_u32 s17, s47, 0
	s_add_i32 s33, s33, s92
	global_load_lds_dwordx4 v[152:153], off
	v_lshl_add_u64 v[196:197], s[16:17], 0, v[134:135]
	s_mov_b32 m0, s33
	v_lshl_add_u64 v[234:235], s[48:49], 0, v[132:133]
	global_load_lds_dwordx4 v[196:197], off
	s_add_i32 m0, s33, 0x2000
	v_lshl_add_u64 v[196:197], s[16:17], 0, v[130:131]
	global_load_lds_dwordx4 v[196:197], off
	s_mov_b32 m0, s23
	v_lshl_add_u64 v[196:197], s[48:49], 0, v[136:137]
	global_load_lds_dwordx4 v[196:197], off
	s_mov_b32 m0, s4
	s_nop 0
	global_load_lds_dwordx4 v[234:235], off
	s_waitcnt vmcnt(8) lgkmcnt(0)
	s_barrier
; #define PG8_STAGE(bufoff, gbase, voff) do { _Pragma("unroll") for (int _i = 0; _i < 2; ++_i) \
;         __builtin_amdgcn_global_load_lds((const unsigned*)((const char*)(gbase) + (voff)[_i]), (LAS unsigned*)(lds + (bufoff) + ldsw + _i * 8192), 16, 0, 0); } while (0)
; #define PG8_LDA(dst, b, h) do { _Pragma("unroll") for (int m = 0; m < 4; ++m) _Pragma("unroll") for (int k = 0; k < 2; ++k) dst[m][k] = *(const LAS bf16x8*)(lds + PG8_SA(b, h) + aoff + m * 2048 + k * 1024); } while (0)
; #define PG8_LDB(dst, b, h) do { _Pragma("unroll") for (int n = 0; n < 2; ++n) _Pragma("unroll") for (int k = 0; k < 2; ++k) dst[n][k] = *(const LAS bf16x8*)(lds + PG8_SB(b, h) + boff + n * 2048 + k * 1024); } while (0)
; #define PG8_MMA(ai, bj, At, Bt) do { __builtin_amdgcn_s_setprio(1); _Pragma("unroll") for (int m = 0; m < 4; ++m) _Pragma("unroll") for (int n = 0; n < 2; ++n) _Pragma("unroll") for (int k = 0; k < 2; ++k) \
;         acc[ai][bj][m][n] = __builtin_amdgcn_mfma_f32_16x16x32_bf16(Bt[n][k], At[m][k], acc[ai][bj][m][n], 0, 0, 0); __builtin_amdgcn_s_setprio(0); } while (0)
; #define PG8_WAIT_V(n) asm volatile("s_waitcnt vmcnt(" #n ")" ::: "memory")
; #define PG8_WAIT_L(n) asm volatile("s_waitcnt lgkmcnt(" #n ")" ::: "memory")
; #define PG8_BAR __builtin_amdgcn_s_barrier()
; #define PG8_SCHED __builtin_amdgcn_sched_barrier(0)
; template <class Epi, class Sched = StaticOrder, bool ALIGN_EPI = true>
; __device__ __forceinline__ void gemm_phase(LAS unsigned char* lds, const Gemm g, const Sched& S, const Epi& E) {
;     ...
;             PG8_WAIT_V(8); PG8_WAIT_L(0); PG8_BAR; PG8_MMA(1, 0, At, B0); PG8_MMA(1, 1, At, B1); PG8_BAR; PG8_SCHED;
;             PG8_LDB(B0, 1, 0); PG8_LDB(B1, 1, 1); PG8_SCHED; PG8_LDA(At, 1, 0); PG8_STAGE(PG8_SA(0, 1), a2 + hstep, voffA);
;             PG8_WAIT_V(8); PG8_WAIT_L(0); PG8_BAR; PG8_MMA(0, 0, At, B0); PG8_MMA(0, 1, At, B1); PG8_BAR; PG8_SCHED;
	v_mfma_f32_16x16x32_bf16 v[62:65], v[148:151], v[188:191], 0
	v_mfma_f32_16x16x32_bf16 v[54:57], v[164:167], v[188:191], 0
	v_mfma_f32_16x16x32_bf16 v[46:49], v[148:151], v[210:213], 0
	v_mfma_f32_16x16x32_bf16 v[38:41], v[164:167], v[210:213], 0
	v_mfma_f32_16x16x32_bf16 v[30:33], v[148:151], v[218:221], 0
	v_mfma_f32_16x16x32_bf16 v[22:25], v[164:167], v[218:221], 0
	v_mfma_f32_16x16x32_bf16 v[14:17], v[148:151], v[226:229], 0
	v_mfma_f32_16x16x32_bf16 v[6:9], v[164:167], v[226:229], 0
	v_mfma_f32_16x16x32_bf16 v[62:65], v[160:163], v[192:195], v[62:65]
	v_mfma_f32_16x16x32_bf16 v[54:57], v[168:171], v[192:195], v[54:57]
	v_mfma_f32_16x16x32_bf16 v[46:49], v[160:163], v[214:217], v[46:49]
	v_mfma_f32_16x16x32_bf16 v[38:41], v[168:171], v[214:217], v[38:41]
	v_mfma_f32_16x16x32_bf16 v[30:33], v[160:163], v[222:225], v[30:33]
	v_mfma_f32_16x16x32_bf16 v[22:25], v[168:171], v[222:225], v[22:25]
	v_mfma_f32_16x16x32_bf16 v[14:17], v[160:163], v[230:233], v[14:17]
	v_mfma_f32_16x16x32_bf16 v[6:9], v[168:171], v[230:233], v[6:9]
	v_mfma_f32_16x16x32_bf16 v[58:61], v[172:175], v[188:191], 0
	v_mfma_f32_16x16x32_bf16 v[50:53], v[180:183], v[188:191], 0
	v_mfma_f32_16x16x32_bf16 v[42:45], v[172:175], v[210:213], 0
	v_mfma_f32_16x16x32_bf16 v[34:37], v[180:183], v[210:213], 0
	v_mfma_f32_16x16x32_bf16 v[26:29], v[172:175], v[218:221], 0
	v_mfma_f32_16x16x32_bf16 v[18:21], v[180:183], v[218:221], 0
	v_mfma_f32_16x16x32_bf16 v[10:13], v[172:175], v[226:229], 0
	v_mfma_f32_16x16x32_bf16 v[2:5], v[180:183], v[226:229], 0
	v_mfma_f32_16x16x32_bf16 v[58:61], v[176:179], v[192:195], v[58:61]
	v_mfma_f32_16x16x32_bf16 v[50:53], v[184:187], v[192:195], v[50:53]
	v_mfma_f32_16x16x32_bf16 v[42:45], v[176:179], v[214:217], v[42:45]
	v_mfma_f32_16x16x32_bf16 v[34:37], v[184:187], v[214:217], v[34:37]
	v_mfma_f32_16x16x32_bf16 v[26:29], v[176:179], v[222:225], v[26:29]
	v_mfma_f32_16x16x32_bf16 v[18:21], v[184:187], v[222:225], v[18:21]
	v_mfma_f32_16x16x32_bf16 v[10:13], v[176:179], v[230:233], v[10:13]
	v_mfma_f32_16x16x32_bf16 v[2:5], v[184:187], v[230:233], v[2:5]
	s_barrier
	s_add_i32 s33, 0, 0x18000
	v_add_u32_e32 v147, s33, v144
	s_add_i32 s83, 0, 0x1c000
	ds_read_b128 v[148:151], v147
	ds_read_b128 v[160:163], v147 offset:1024
	ds_read_b128 v[164:167], v147 offset:2048
	ds_read_b128 v[168:171], v147 offset:3072
	v_add_u32_e32 v147, s83, v144
	ds_read_b128 v[172:175], v147
	ds_read_b128 v[176:179], v147 offset:1024
	ds_read_b128 v[180:183], v147 offset:2048
	ds_read_b128 v[184:187], v147 offset:3072
	s_add_u32 s16, s48, 0x80000
	s_addc_u32 s17, s49, 0
	s_mov_b32 m0, s5
	v_lshl_add_u64 v[236:237], s[16:17], 0, v[136:137]
	ds_read_b128 v[188:191], v146 offset:32768
	ds_read_b128 v[192:195], v146 offset:33792
	ds_read_b128 v[210:213], v146 offset:34816
	ds_read_b128 v[214:217], v146 offset:35840
	ds_read_b128 v[218:221], v146 offset:36864
	ds_read_b128 v[222:225], v146 offset:37888
	ds_read_b128 v[226:229], v146 offset:38912
	ds_read_b128 v[230:233], v146 offset:39936
	global_load_lds_dwordx4 v[236:237], off
	s_mov_b32 m0, s6
	v_lshl_add_u64 v[236:237], s[16:17], 0, v[132:133]
	global_load_lds_dwordx4 v[236:237], off
	s_waitcnt vmcnt(8) lgkmcnt(0)
	s_barrier
	v_mfma_f32_16x16x32_bf16 v[126:129], v[148:151], v[188:191], v[126:129]
	v_mfma_f32_16x16x32_bf16 v[118:121], v[164:167], v[188:191], v[118:121]
	v_mfma_f32_16x16x32_bf16 v[110:113], v[148:151], v[210:213], v[110:113]
	v_mfma_f32_16x16x32_bf16 v[102:105], v[164:167], v[210:213], v[102:105]
	v_mfma_f32_16x16x32_bf16 v[94:97], v[148:151], v[218:221], v[94:97]
	v_mfma_f32_16x16x32_bf16 v[86:89], v[164:167], v[218:221], v[86:89]
	v_mfma_f32_16x16x32_bf16 v[78:81], v[148:151], v[226:229], v[78:81]
	v_mfma_f32_16x16x32_bf16 v[70:73], v[164:167], v[226:229], v[70:73]
	v_mfma_f32_16x16x32_bf16 v[126:129], v[160:163], v[192:195], v[126:129]
	v_mfma_f32_16x16x32_bf16 v[118:121], v[168:171], v[192:195], v[118:121]
	v_mfma_f32_16x16x32_bf16 v[110:113], v[160:163], v[214:217], v[110:113]
	v_mfma_f32_16x16x32_bf16 v[102:105], v[168:171], v[214:217], v[102:105]
	v_mfma_f32_16x16x32_bf16 v[94:97], v[160:163], v[222:225], v[94:97]
	v_mfma_f32_16x16x32_bf16 v[86:89], v[168:171], v[222:225], v[86:89]
	v_mfma_f32_16x16x32_bf16 v[78:81], v[160:163], v[230:233], v[78:81]
	v_mfma_f32_16x16x32_bf16 v[70:73], v[168:171], v[230:233], v[70:73]
	v_mfma_f32_16x16x32_bf16 v[122:125], v[172:175], v[188:191], v[122:125]
	v_mfma_f32_16x16x32_bf16 v[114:117], v[180:183], v[188:191], v[114:117]
	v_mfma_f32_16x16x32_bf16 v[106:109], v[172:175], v[210:213], v[106:109]
	v_mfma_f32_16x16x32_bf16 v[98:101], v[180:183], v[210:213], v[98:101]
	v_mfma_f32_16x16x32_bf16 v[90:93], v[172:175], v[218:221], v[90:93]
	v_mfma_f32_16x16x32_bf16 v[82:85], v[180:183], v[218:221], v[82:85]
	v_mfma_f32_16x16x32_bf16 v[74:77], v[172:175], v[226:229], v[74:77]
	v_mfma_f32_16x16x32_bf16 v[66:69], v[180:183], v[226:229], v[66:69]
	v_mfma_f32_16x16x32_bf16 v[122:125], v[176:179], v[192:195], v[122:125]
	v_mfma_f32_16x16x32_bf16 v[114:117], v[184:187], v[192:195], v[114:117]
	v_mfma_f32_16x16x32_bf16 v[106:109], v[176:179], v[214:217], v[106:109]
	v_mfma_f32_16x16x32_bf16 v[98:101], v[184:187], v[214:217], v[98:101]
	v_mfma_f32_16x16x32_bf16 v[90:93], v[176:179], v[222:225], v[90:93]
	v_mfma_f32_16x16x32_bf16 v[82:85], v[184:187], v[222:225], v[82:85]
	v_mfma_f32_16x16x32_bf16 v[74:77], v[176:179], v[230:233], v[74:77]
	v_mfma_f32_16x16x32_bf16 v[66:69], v[184:187], v[230:233], v[66:69]
	s_barrier
;     __device__ bool next(int i, Unit& u) const { const int idx = i * G + c; if (idx >= 64) return false; u.kp = idx & 3; u.pn = (idx >> 2) & 7; u.pm = 192 + (idx >> 5); return true; }
; #define PG8_STAGE(bufoff, gbase, voff) do { _Pragma("unroll") for (int _i = 0; _i < 2; ++_i) \
;         __builtin_amdgcn_global_load_lds((const unsigned*)((const char*)(gbase) + (voff)[_i]), (LAS unsigned*)(lds + (bufoff) + ldsw + _i * 8192), 16, 0, 0); } while (0)
; #define PG8_LDA(dst, b, h) do { _Pragma("unroll") for (int m = 0; m < 4; ++m) _Pragma("unroll") for (int k = 0; k < 2; ++k) dst[m][k] = *(const LAS bf16x8*)(lds + PG8_SA(b, h) + aoff + m * 2048 + k * 1024); } while (0)
; #define PG8_LDB(dst, b, h) do { _Pragma("unroll") for (int n = 0; n < 2; ++n) _Pragma("unroll") for (int k = 0; k < 2; ++k) dst[n][k] = *(const LAS bf16x8*)(lds + PG8_SB(b, h) + boff + n * 2048 + k * 1024); } while (0)
; #define PG8_WAIT_V(n) asm volatile("s_waitcnt vmcnt(" #n ")" ::: "memory")
; #define PG8_WAIT_L(n) asm volatile("s_waitcnt lgkmcnt(" #n ")" ::: "memory")
; #define PG8_BAR __builtin_amdgcn_s_barrier()
; #define PG8_SCHED __builtin_amdgcn_sched_barrier(0)
; template <class Epi, class Sched = StaticOrder, bool ALIGN_EPI = true>
; __device__ __forceinline__ void gemm_phase(LAS unsigned char* lds, const Gemm g, const Sched& S, const Epi& E) {
;     ...
;         const bool has_next = S.next(ui + 1, nxt);
;         const char* nA = has_next ? (const char*)g.A + (size_t)nxt.pm * tstep + (size_t)nxt.kp * K * 2 : cA; const char* nB = has_next ? (const char*)g.Bt + (size_t)nxt.pn * tstep + (size_t)nxt.kp * K * 2 : cB;
;         for (int t = 0; t < nt; t += 2) {
;             const bool last = (t == nt - 2);
;             const char* a1 = cA + (size_t)(t + 1) * kstep;
;             const char* a2 = last ? nA : cA + (size_t)(t + 2) * kstep; const char* b2 = last ? nB : cB + (size_t)(t + 2) * kstep;
;             const char* a3 = a2 + kstep; const char* b3 = b2 + kstep;
;             PG8_LDB(B0, 0, 0); PG8_LDB(B1, 0, 1); PG8_SCHED; PG8_LDA(At, 0, 0); PG8_STAGE(PG8_SA(1, 1), a1 + hstep, voffA);
;     ...
;             PG8_LDA(At, 1, 1); PG8_STAGE(PG8_SB(1, 0), b3, voffB); PG8_STAGE(PG8_SB(1, 1), b3 + hstep, voffB); PG8_STAGE(PG8_SA(1, 0), a3, voffA);
;             PG8_WAIT_V(8); PG8_WAIT_L(0); PG8_BAR; PG8_MMA(1, 0, At, B0); PG8_MMA(1, 1, At, B1); PG8_BAR; PG8_SCHED;
;         }
	s_add_i32 s16, s33, s92
	v_lshl_add_u64 v[142:143], v[142:143], 0, s[34:35]
	s_mov_b32 m0, s16
	ds_read_b128 v[188:191], v146 offset:49152
	ds_read_b128 v[192:195], v146 offset:50176
	ds_read_b128 v[210:213], v146 offset:51200
	ds_read_b128 v[214:217], v146 offset:52224
	ds_read_b128 v[218:221], v146 offset:53248
	ds_read_b128 v[222:225], v146 offset:54272
	ds_read_b128 v[226:229], v146 offset:55296
	ds_read_b128 v[230:233], v146 offset:56320
	global_load_lds_dwordx4 v[142:143], off
	s_add_i32 m0, s16, 0x2000
	s_add_u32 s16, s46, 0x80080
	v_lshl_add_u64 v[142:143], v[152:153], 0, s[34:35]
	s_addc_u32 s17, s47, 0
	s_add_i32 s33, s83, s92
	global_load_lds_dwordx4 v[142:143], off
	s_mov_b32 m0, s33
	v_lshl_add_u64 v[142:143], s[16:17], 0, v[134:135]
	global_load_lds_dwordx4 v[142:143], off
	s_add_i32 m0, s33, 0x2000
	v_lshl_add_u64 v[142:143], s[16:17], 0, v[130:131]
	global_load_lds_dwordx4 v[142:143], off
	s_mov_b32 m0, s7
	v_lshl_add_u64 v[142:143], v[196:197], 0, s[34:35]
	global_load_lds_dwordx4 v[142:143], off
	s_mov_b32 m0, s8
	v_lshl_add_u64 v[142:143], v[234:235], 0, s[34:35]
	global_load_lds_dwordx4 v[142:143], off
	s_waitcnt vmcnt(8) lgkmcnt(0)
	s_barrier
	v_mfma_f32_16x16x32_bf16 v[62:65], v[148:151], v[188:191], v[62:65]
	v_mfma_f32_16x16x32_bf16 v[54:57], v[164:167], v[188:191], v[54:57]
	v_mfma_f32_16x16x32_bf16 v[46:49], v[148:151], v[210:213], v[46:49]
	v_mfma_f32_16x16x32_bf16 v[38:41], v[164:167], v[210:213], v[38:41]
	v_mfma_f32_16x16x32_bf16 v[30:33], v[148:151], v[218:221], v[30:33]
	v_mfma_f32_16x16x32_bf16 v[22:25], v[164:167], v[218:221], v[22:25]
	v_mfma_f32_16x16x32_bf16 v[14:17], v[148:151], v[226:229], v[14:17]
	v_mfma_f32_16x16x32_bf16 v[6:9], v[164:167], v[226:229], v[6:9]
	v_mfma_f32_16x16x32_bf16 v[62:65], v[160:163], v[192:195], v[62:65]
	v_mfma_f32_16x16x32_bf16 v[54:57], v[168:171], v[192:195], v[54:57]
	v_mfma_f32_16x16x32_bf16 v[46:49], v[160:163], v[214:217], v[46:49]
	v_mfma_f32_16x16x32_bf16 v[38:41], v[168:171], v[214:217], v[38:41]
	v_mfma_f32_16x16x32_bf16 v[30:33], v[160:163], v[222:225], v[30:33]
	v_mfma_f32_16x16x32_bf16 v[22:25], v[168:171], v[222:225], v[22:25]
	v_mfma_f32_16x16x32_bf16 v[14:17], v[160:163], v[230:233], v[14:17]
	v_mfma_f32_16x16x32_bf16 v[6:9], v[168:171], v[230:233], v[6:9]
	v_mfma_f32_16x16x32_bf16 v[58:61], v[172:175], v[188:191], v[58:61]
	v_mfma_f32_16x16x32_bf16 v[50:53], v[180:183], v[188:191], v[50:53]
	v_mfma_f32_16x16x32_bf16 v[42:45], v[172:175], v[210:213], v[42:45]
	v_mfma_f32_16x16x32_bf16 v[34:37], v[180:183], v[210:213], v[34:37]
	v_mfma_f32_16x16x32_bf16 v[26:29], v[172:175], v[218:221], v[26:29]
	v_mfma_f32_16x16x32_bf16 v[18:21], v[180:183], v[218:221], v[18:21]
	v_mfma_f32_16x16x32_bf16 v[10:13], v[172:175], v[226:229], v[10:13]
	v_mfma_f32_16x16x32_bf16 v[2:5], v[180:183], v[226:229], v[2:5]
	v_mfma_f32_16x16x32_bf16 v[58:61], v[176:179], v[192:195], v[58:61]
	v_mfma_f32_16x16x32_bf16 v[50:53], v[184:187], v[192:195], v[50:53]
	v_mfma_f32_16x16x32_bf16 v[42:45], v[176:179], v[214:217], v[42:45]
	v_mfma_f32_16x16x32_bf16 v[34:37], v[184:187], v[214:217], v[34:37]
	v_mfma_f32_16x16x32_bf16 v[26:29], v[176:179], v[222:225], v[26:29]
	v_mfma_f32_16x16x32_bf16 v[18:21], v[184:187], v[222:225], v[18:21]
	v_mfma_f32_16x16x32_bf16 v[10:13], v[176:179], v[230:233], v[10:13]
	v_mfma_f32_16x16x32_bf16 v[2:5], v[184:187], v[230:233], v[2:5]
	s_barrier
	s_add_i32 s82, s82, 2
	s_add_u32 s44, s44, 0x100
	s_addc_u32 s45, s45, 0
	s_add_u32 vcc_lo, vcc_lo, 0x100
	s_addc_u32 vcc_hi, vcc_hi, 0
	s_cmp_gt_u32 s82, 29
	s_cbranch_scc0 .LBB0_467
.LBB0_467:
	s_add_u32 s16, s44, 0xfff80080
	s_addc_u32 s17, s45, -1
	s_add_i32 s83, 0, 0x10000
	s_cmp_eq_u32 s82, 28
	s_cselect_b32 s49, s10, s17
	s_cselect_b32 s48, s11, s16
	v_add_u32_e32 v142, s83, v144
	s_cselect_b32 s47, s21, vcc_hi
	s_cselect_b32 s46, s31, vcc_lo
	s_add_i32 s33, 0, 0x14000
	ds_read_b128 v[148:151], v142
	ds_read_b128 v[160:163], v142 offset:1024
	ds_read_b128 v[164:167], v142 offset:2048
	ds_read_b128 v[168:171], v142 offset:3072
	v_add_u32_e32 v142, s33, v144
	ds_read_b128 v[172:175], v142
	ds_read_b128 v[176:179], v142 offset:1024
	ds_read_b128 v[180:183], v142 offset:2048
	ds_read_b128 v[184:187], v142 offset:3072
	v_lshl_add_u64 v[142:143], s[44:45], 0, v[138:139]
	s_add_i32 m0, s23, 0xc000
	ds_read_b128 v[188:191], v146
	ds_read_b128 v[192:195], v146 offset:1024
	ds_read_b128 v[210:213], v146 offset:2048
	ds_read_b128 v[214:217], v146 offset:3072
	ds_read_b128 v[218:221], v146 offset:4096
	ds_read_b128 v[222:225], v146 offset:5120
	ds_read_b128 v[226:229], v146 offset:6144
	ds_read_b128 v[230:233], v146 offset:7168
	global_load_lds_dwordx4 v[142:143], off
	s_add_i32 m0, s23, 0xe000
	v_lshl_add_u64 v[142:143], s[44:45], 0, v[140:141]
	global_load_lds_dwordx4 v[142:143], off
	s_waitcnt vmcnt(8) lgkmcnt(0)
	s_barrier
; #define PG8_STAGE(bufoff, gbase, voff) do { _Pragma("unroll") for (int _i = 0; _i < 2; ++_i) \
;         __builtin_amdgcn_global_load_lds((const unsigned*)((const char*)(gbase) + (voff)[_i]), (LAS unsigned*)(lds + (bufoff) + ldsw + _i * 8192), 16, 0, 0); } while (0)
; #define PG8_LDA(dst, b, h) do { _Pragma("unroll") for (int m = 0; m < 4; ++m) _Pragma("unroll") for (int k = 0; k < 2; ++k) dst[m][k] = *(const LAS bf16x8*)(lds + PG8_SA(b, h) + aoff + m * 2048 + k * 1024); } while (0)
; #define PG8_LDB(dst, b, h) do { _Pragma("unroll") for (int n = 0; n < 2; ++n) _Pragma("unroll") for (int k = 0; k < 2; ++k) dst[n][k] = *(const LAS bf16x8*)(lds + PG8_SB(b, h) + boff + n * 2048 + k * 1024); } while (0)
; #define PG8_MMA(ai, bj, At, Bt) do { __builtin_amdgcn_s_setprio(1); _Pragma("unroll") for (int m = 0; m < 4; ++m) _Pragma("unroll") for (int n = 0; n < 2; ++n) _Pragma("unroll") for (int k = 0; k < 2; ++k) \
;         acc[ai][bj][m][n] = __builtin_amdgcn_mfma_f32_16x16x32_bf16(Bt[n][k], At[m][k], acc[ai][bj][m][n], 0, 0, 0); __builtin_amdgcn_s_setprio(0); } while (0)
; #define PG8_WAIT_V(n) asm volatile("s_waitcnt vmcnt(" #n ")" ::: "memory")
; #define PG8_WAIT_L(n) asm volatile("s_waitcnt lgkmcnt(" #n ")" ::: "memory")
; #define PG8_BAR __builtin_amdgcn_s_barrier()
; #define PG8_SCHED __builtin_amdgcn_sched_barrier(0)
; template <class Epi, class Sched = StaticOrder, bool ALIGN_EPI = true>
; __device__ __forceinline__ void gemm_phase(LAS unsigned char* lds, const Gemm g, const Sched& S, const Epi& E) {
;     ...
;             PG8_LDB(B0, 0, 0); PG8_LDB(B1, 0, 1); PG8_SCHED; PG8_LDA(At, 0, 0); PG8_STAGE(PG8_SA(1, 1), a1 + hstep, voffA);
;             PG8_WAIT_V(8); PG8_WAIT_L(0); PG8_BAR; PG8_MMA(0, 0, At, B0); PG8_MMA(0, 1, At, B1); PG8_BAR; PG8_SCHED;
;             PG8_LDA(At, 0, 1); PG8_STAGE(PG8_SB(0, 0), b2, voffB); PG8_STAGE(PG8_SB(0, 1), b2 + hstep, voffB); PG8_STAGE(PG8_SA(0, 0), a2, voffA);
;             PG8_WAIT_V(8); PG8_WAIT_L(0); PG8_BAR; PG8_MMA(1, 0, At, B0); PG8_MMA(1, 1, At, B1); PG8_BAR; PG8_SCHED;
	v_mfma_f32_16x16x32_bf16 v[126:129], v[148:151], v[188:191], v[126:129]
	v_mfma_f32_16x16x32_bf16 v[118:121], v[164:167], v[188:191], v[118:121]
	v_mfma_f32_16x16x32_bf16 v[110:113], v[148:151], v[210:213], v[110:113]
	v_mfma_f32_16x16x32_bf16 v[102:105], v[164:167], v[210:213], v[102:105]
	v_mfma_f32_16x16x32_bf16 v[94:97], v[148:151], v[218:221], v[94:97]
	v_mfma_f32_16x16x32_bf16 v[86:89], v[164:167], v[218:221], v[86:89]
	v_mfma_f32_16x16x32_bf16 v[78:81], v[148:151], v[226:229], v[78:81]
	v_mfma_f32_16x16x32_bf16 v[70:73], v[164:167], v[226:229], v[70:73]
	v_mfma_f32_16x16x32_bf16 v[126:129], v[160:163], v[192:195], v[126:129]
	v_mfma_f32_16x16x32_bf16 v[118:121], v[168:171], v[192:195], v[118:121]
	v_mfma_f32_16x16x32_bf16 v[110:113], v[160:163], v[214:217], v[110:113]
	v_mfma_f32_16x16x32_bf16 v[102:105], v[168:171], v[214:217], v[102:105]
	v_mfma_f32_16x16x32_bf16 v[94:97], v[160:163], v[222:225], v[94:97]
	v_mfma_f32_16x16x32_bf16 v[86:89], v[168:171], v[222:225], v[86:89]
	v_mfma_f32_16x16x32_bf16 v[78:81], v[160:163], v[230:233], v[78:81]
	v_mfma_f32_16x16x32_bf16 v[70:73], v[168:171], v[230:233], v[70:73]
	v_mfma_f32_16x16x32_bf16 v[122:125], v[172:175], v[188:191], v[122:125]
	v_mfma_f32_16x16x32_bf16 v[114:117], v[180:183], v[188:191], v[114:117]
	v_mfma_f32_16x16x32_bf16 v[106:109], v[172:175], v[210:213], v[106:109]
	v_mfma_f32_16x16x32_bf16 v[98:101], v[180:183], v[210:213], v[98:101]
	v_mfma_f32_16x16x32_bf16 v[90:93], v[172:175], v[218:221], v[90:93]
	v_mfma_f32_16x16x32_bf16 v[82:85], v[180:183], v[218:221], v[82:85]
	v_mfma_f32_16x16x32_bf16 v[74:77], v[172:175], v[226:229], v[74:77]
	v_mfma_f32_16x16x32_bf16 v[66:69], v[180:183], v[226:229], v[66:69]
	v_mfma_f32_16x16x32_bf16 v[122:125], v[176:179], v[192:195], v[122:125]
	v_mfma_f32_16x16x32_bf16 v[114:117], v[184:187], v[192:195], v[114:117]
	v_mfma_f32_16x16x32_bf16 v[106:109], v[176:179], v[214:217], v[106:109]
	v_mfma_f32_16x16x32_bf16 v[98:101], v[184:187], v[214:217], v[98:101]
	v_mfma_f32_16x16x32_bf16 v[90:93], v[176:179], v[222:225], v[90:93]
	v_mfma_f32_16x16x32_bf16 v[82:85], v[184:187], v[222:225], v[82:85]
	v_mfma_f32_16x16x32_bf16 v[74:77], v[176:179], v[230:233], v[74:77]
	v_mfma_f32_16x16x32_bf16 v[66:69], v[184:187], v[230:233], v[66:69]
	s_barrier
	s_add_i32 s16, s83, s92
	v_lshl_add_u64 v[142:143], s[46:47], 0, v[134:135]
	s_mov_b32 m0, s16
	ds_read_b128 v[188:191], v146 offset:16384
	ds_read_b128 v[192:195], v146 offset:17408
	ds_read_b128 v[210:213], v146 offset:18432
	ds_read_b128 v[214:217], v146 offset:19456
	ds_read_b128 v[218:221], v146 offset:20480
	ds_read_b128 v[222:225], v146 offset:21504
	ds_read_b128 v[226:229], v146 offset:22528
	ds_read_b128 v[230:233], v146 offset:23552
	global_load_lds_dwordx4 v[142:143], off
	s_add_i32 m0, s16, 0x2000
	s_add_u32 s16, s46, 0x80000
	v_lshl_add_u64 v[152:153], s[46:47], 0, v[130:131]
	s_addc_u32 s17, s47, 0
	s_add_i32 s33, s33, s92
	global_load_lds_dwordx4 v[152:153], off
	v_lshl_add_u64 v[196:197], s[16:17], 0, v[134:135]
	s_mov_b32 m0, s33
	v_lshl_add_u64 v[234:235], s[48:49], 0, v[132:133]
	global_load_lds_dwordx4 v[196:197], off
	s_add_i32 m0, s33, 0x2000
	v_lshl_add_u64 v[196:197], s[16:17], 0, v[130:131]
	global_load_lds_dwordx4 v[196:197], off
	s_mov_b32 m0, s23
	v_lshl_add_u64 v[196:197], s[48:49], 0, v[136:137]
	global_load_lds_dwordx4 v[196:197], off
	s_mov_b32 m0, s4
	s_nop 0
	global_load_lds_dwordx4 v[234:235], off
	s_waitcnt vmcnt(8) lgkmcnt(0)
	s_barrier
	v_mfma_f32_16x16x32_bf16 v[62:65], v[148:151], v[188:191], v[62:65]
	v_mfma_f32_16x16x32_bf16 v[54:57], v[164:167], v[188:191], v[54:57]
	v_mfma_f32_16x16x32_bf16 v[46:49], v[148:151], v[210:213], v[46:49]
	v_mfma_f32_16x16x32_bf16 v[38:41], v[164:167], v[210:213], v[38:41]
	v_mfma_f32_16x16x32_bf16 v[30:33], v[148:151], v[218:221], v[30:33]
	v_mfma_f32_16x16x32_bf16 v[22:25], v[164:167], v[218:221], v[22:25]
	v_mfma_f32_16x16x32_bf16 v[14:17], v[148:151], v[226:229], v[14:17]
	v_mfma_f32_16x16x32_bf16 v[6:9], v[164:167], v[226:229], v[6:9]
	v_mfma_f32_16x16x32_bf16 v[62:65], v[160:163], v[192:195], v[62:65]
	v_mfma_f32_16x16x32_bf16 v[54:57], v[168:171], v[192:195], v[54:57]
	v_mfma_f32_16x16x32_bf16 v[46:49], v[160:163], v[214:217], v[46:49]
	v_mfma_f32_16x16x32_bf16 v[38:41], v[168:171], v[214:217], v[38:41]
	v_mfma_f32_16x16x32_bf16 v[30:33], v[160:163], v[222:225], v[30:33]
	v_mfma_f32_16x16x32_bf16 v[22:25], v[168:171], v[222:225], v[22:25]
	v_mfma_f32_16x16x32_bf16 v[14:17], v[160:163], v[230:233], v[14:17]
	v_mfma_f32_16x16x32_bf16 v[6:9], v[168:171], v[230:233], v[6:9]
	v_mfma_f32_16x16x32_bf16 v[58:61], v[172:175], v[188:191], v[58:61]
	v_mfma_f32_16x16x32_bf16 v[50:53], v[180:183], v[188:191], v[50:53]
	v_mfma_f32_16x16x32_bf16 v[42:45], v[172:175], v[210:213], v[42:45]
	v_mfma_f32_16x16x32_bf16 v[34:37], v[180:183], v[210:213], v[34:37]
	v_mfma_f32_16x16x32_bf16 v[26:29], v[172:175], v[218:221], v[26:29]
	v_mfma_f32_16x16x32_bf16 v[18:21], v[180:183], v[218:221], v[18:21]
	v_mfma_f32_16x16x32_bf16 v[10:13], v[172:175], v[226:229], v[10:13]
	v_mfma_f32_16x16x32_bf16 v[2:5], v[180:183], v[226:229], v[2:5]
	v_mfma_f32_16x16x32_bf16 v[58:61], v[176:179], v[192:195], v[58:61]
	v_mfma_f32_16x16x32_bf16 v[50:53], v[184:187], v[192:195], v[50:53]
	v_mfma_f32_16x16x32_bf16 v[42:45], v[176:179], v[214:217], v[42:45]
	v_mfma_f32_16x16x32_bf16 v[34:37], v[184:187], v[214:217], v[34:37]
	v_mfma_f32_16x16x32_bf16 v[26:29], v[176:179], v[222:225], v[26:29]
	v_mfma_f32_16x16x32_bf16 v[18:21], v[184:187], v[222:225], v[18:21]
	v_mfma_f32_16x16x32_bf16 v[10:13], v[176:179], v[230:233], v[10:13]
	v_mfma_f32_16x16x32_bf16 v[2:5], v[184:187], v[230:233], v[2:5]
	s_barrier
; #define PG8_STAGE(bufoff, gbase, voff) do { _Pragma("unroll") for (int _i = 0; _i < 2; ++_i) \
;         __builtin_amdgcn_global_load_lds((const unsigned*)((const char*)(gbase) + (voff)[_i]), (LAS unsigned*)(lds + (bufoff) + ldsw + _i * 8192), 16, 0, 0); } while (0)
; #define PG8_LDA(dst, b, h) do { _Pragma("unroll") for (int m = 0; m < 4; ++m) _Pragma("unroll") for (int k = 0; k < 2; ++k) dst[m][k] = *(const LAS bf16x8*)(lds + PG8_SA(b, h) + aoff + m * 2048 + k * 1024); } while (0)
; #define PG8_LDB(dst, b, h) do { _Pragma("unroll") for (int n = 0; n < 2; ++n) _Pragma("unroll") for (int k = 0; k < 2; ++k) dst[n][k] = *(const LAS bf16x8*)(lds + PG8_SB(b, h) + boff + n * 2048 + k * 1024); } while (0)
; #define PG8_MMA(ai, bj, At, Bt) do { __builtin_amdgcn_s_setprio(1); _Pragma("unroll") for (int m = 0; m < 4; ++m) _Pragma("unroll") for (int n = 0; n < 2; ++n) _Pragma("unroll") for (int k = 0; k < 2; ++k) \
;         acc[ai][bj][m][n] = __builtin_amdgcn_mfma_f32_16x16x32_bf16(Bt[n][k], At[m][k], acc[ai][bj][m][n], 0, 0, 0); __builtin_amdgcn_s_setprio(0); } while (0)
; #define PG8_WAIT_V(n) asm volatile("s_waitcnt vmcnt(" #n ")" ::: "memory")
; template <class Epi, class Sched = StaticOrder, bool ALIGN_EPI = true>
; __device__ __forceinline__ void gemm_phase(LAS unsigned char* lds, const Gemm g, const Sched& S, const Epi& E) {
;     ...
;             PG8_LDB(B0, 0, 0); PG8_LDB(B1, 0, 1); PG8_SCHED; PG8_LDA(At, 0, 0); PG8_STAGE(PG8_SA(1, 1), a1 + hstep, voffA);
;             PG8_WAIT_V(8); PG8_WAIT_L(0); PG8_BAR; PG8_MMA(0, 0, At, B0); PG8_MMA(0, 1, At, B1); PG8_BAR; PG8_SCHED;
;             PG8_LDA(At, 0, 1); PG8_STAGE(PG8_SB(0, 0), b2, voffB); PG8_STAGE(PG8_SB(0, 1), b2 + hstep, voffB); PG8_STAGE(PG8_SA(0, 0), a2, voffA);
;             PG8_WAIT_V(8); PG8_WAIT_L(0); PG8_BAR; PG8_MMA(1, 0, At, B0); PG8_MMA(1, 1, At, B1); PG8_BAR; PG8_SCHED;
;             PG8_LDB(B0, 1, 0); PG8_LDB(B1, 1, 1); PG8_SCHED; PG8_LDA(At, 1, 0); PG8_STAGE(PG8_SA(0, 1), a2 + hstep, voffA);
;             PG8_WAIT_V(8); PG8_WAIT_L(0); PG8_BAR; PG8_MMA(0, 0, At, B0); PG8_MMA(0, 1, At, B1); PG8_BAR; PG8_SCHED;
;             PG8_LDA(At, 1, 1); PG8_STAGE(PG8_SB(1, 0), b3, voffB); PG8_STAGE(PG8_SB(1, 1), b3 + hstep, voffB); PG8_STAGE(PG8_SA(1, 0), a3, voffA);
;             PG8_WAIT_V(8); PG8_WAIT_L(0); PG8_BAR; PG8_MMA(1, 0, At, B0); PG8_MMA(1, 1, At, B1); PG8_BAR; PG8_SCHED;
	s_add_i32 s33, 0, 0x18000
	v_add_u32_e32 v147, s33, v144
	s_add_i32 s83, 0, 0x1c000
	ds_read_b128 v[148:151], v147
	ds_read_b128 v[160:163], v147 offset:1024
	ds_read_b128 v[164:167], v147 offset:2048
	ds_read_b128 v[168:171], v147 offset:3072
	v_add_u32_e32 v147, s83, v144
	ds_read_b128 v[172:175], v147
	ds_read_b128 v[176:179], v147 offset:1024
	ds_read_b128 v[180:183], v147 offset:2048
	ds_read_b128 v[184:187], v147 offset:3072
	s_add_u32 s16, s48, 0x80000
	s_addc_u32 s17, s49, 0
	s_mov_b32 m0, s5
	v_lshl_add_u64 v[236:237], s[16:17], 0, v[136:137]
	ds_read_b128 v[188:191], v146 offset:32768
	ds_read_b128 v[192:195], v146 offset:33792
	ds_read_b128 v[210:213], v146 offset:34816
	ds_read_b128 v[214:217], v146 offset:35840
	ds_read_b128 v[218:221], v146 offset:36864
	ds_read_b128 v[222:225], v146 offset:37888
	ds_read_b128 v[226:229], v146 offset:38912
	ds_read_b128 v[230:233], v146 offset:39936
	global_load_lds_dwordx4 v[236:237], off
	s_mov_b32 m0, s6
	v_lshl_add_u64 v[236:237], s[16:17], 0, v[132:133]
	global_load_lds_dwordx4 v[236:237], off
	s_waitcnt vmcnt(8) lgkmcnt(0)
	s_barrier
	v_mfma_f32_16x16x32_bf16 v[126:129], v[148:151], v[188:191], v[126:129]
	v_mfma_f32_16x16x32_bf16 v[118:121], v[164:167], v[188:191], v[118:121]
	v_mfma_f32_16x16x32_bf16 v[110:113], v[148:151], v[210:213], v[110:113]
	v_mfma_f32_16x16x32_bf16 v[102:105], v[164:167], v[210:213], v[102:105]
	v_mfma_f32_16x16x32_bf16 v[94:97], v[148:151], v[218:221], v[94:97]
	v_mfma_f32_16x16x32_bf16 v[86:89], v[164:167], v[218:221], v[86:89]
	v_mfma_f32_16x16x32_bf16 v[78:81], v[148:151], v[226:229], v[78:81]
	v_mfma_f32_16x16x32_bf16 v[70:73], v[164:167], v[226:229], v[70:73]
	v_mfma_f32_16x16x32_bf16 v[126:129], v[160:163], v[192:195], v[126:129]
	v_mfma_f32_16x16x32_bf16 v[118:121], v[168:171], v[192:195], v[118:121]
	v_mfma_f32_16x16x32_bf16 v[110:113], v[160:163], v[214:217], v[110:113]
	v_mfma_f32_16x16x32_bf16 v[102:105], v[168:171], v[214:217], v[102:105]
	v_mfma_f32_16x16x32_bf16 v[94:97], v[160:163], v[222:225], v[94:97]
	v_mfma_f32_16x16x32_bf16 v[86:89], v[168:171], v[222:225], v[86:89]
	v_mfma_f32_16x16x32_bf16 v[78:81], v[160:163], v[230:233], v[78:81]
	v_mfma_f32_16x16x32_bf16 v[70:73], v[168:171], v[230:233], v[70:73]
	v_mfma_f32_16x16x32_bf16 v[122:125], v[172:175], v[188:191], v[122:125]
	v_mfma_f32_16x16x32_bf16 v[114:117], v[180:183], v[188:191], v[114:117]
	v_mfma_f32_16x16x32_bf16 v[106:109], v[172:175], v[210:213], v[106:109]
	v_mfma_f32_16x16x32_bf16 v[98:101], v[180:183], v[210:213], v[98:101]
	v_mfma_f32_16x16x32_bf16 v[90:93], v[172:175], v[218:221], v[90:93]
	v_mfma_f32_16x16x32_bf16 v[82:85], v[180:183], v[218:221], v[82:85]
	v_mfma_f32_16x16x32_bf16 v[74:77], v[172:175], v[226:229], v[74:77]
	v_mfma_f32_16x16x32_bf16 v[66:69], v[180:183], v[226:229], v[66:69]
	v_mfma_f32_16x16x32_bf16 v[122:125], v[176:179], v[192:195], v[122:125]
	v_mfma_f32_16x16x32_bf16 v[114:117], v[184:187], v[192:195], v[114:117]
	v_mfma_f32_16x16x32_bf16 v[106:109], v[176:179], v[214:217], v[106:109]
	v_mfma_f32_16x16x32_bf16 v[98:101], v[184:187], v[214:217], v[98:101]
	v_mfma_f32_16x16x32_bf16 v[90:93], v[176:179], v[222:225], v[90:93]
	v_mfma_f32_16x16x32_bf16 v[82:85], v[184:187], v[222:225], v[82:85]
	v_mfma_f32_16x16x32_bf16 v[74:77], v[176:179], v[230:233], v[74:77]
	v_mfma_f32_16x16x32_bf16 v[66:69], v[184:187], v[230:233], v[66:69]
	s_barrier
	s_add_i32 s16, s33, s92
	v_lshl_add_u64 v[142:143], v[142:143], 0, s[34:35]
	s_mov_b32 m0, s16
	ds_read_b128 v[188:191], v146 offset:49152
	ds_read_b128 v[192:195], v146 offset:50176
	ds_read_b128 v[210:213], v146 offset:51200
	ds_read_b128 v[214:217], v146 offset:52224
	ds_read_b128 v[218:221], v146 offset:53248
	ds_read_b128 v[222:225], v146 offset:54272
	ds_read_b128 v[226:229], v146 offset:55296
	ds_read_b128 v[230:233], v146 offset:56320
	global_load_lds_dwordx4 v[142:143], off
	s_add_i32 m0, s16, 0x2000
	s_add_u32 s16, s46, 0x80080
	v_lshl_add_u64 v[142:143], v[152:153], 0, s[34:35]
	s_addc_u32 s17, s47, 0
	s_add_i32 s33, s83, s92
	global_load_lds_dwordx4 v[142:143], off
	s_mov_b32 m0, s33
	v_lshl_add_u64 v[142:143], s[16:17], 0, v[134:135]
	global_load_lds_dwordx4 v[142:143], off
	s_add_i32 m0, s33, 0x2000
	v_lshl_add_u64 v[142:143], s[16:17], 0, v[130:131]
	global_load_lds_dwordx4 v[142:143], off
	s_mov_b32 m0, s7
	v_lshl_add_u64 v[142:143], v[196:197], 0, s[34:35]
	global_load_lds_dwordx4 v[142:143], off
	s_mov_b32 m0, s8
	v_lshl_add_u64 v[142:143], v[234:235], 0, s[34:35]
	global_load_lds_dwordx4 v[142:143], off
	s_waitcnt vmcnt(8) lgkmcnt(0)
	s_barrier
	v_mfma_f32_16x16x32_bf16 v[62:65], v[148:151], v[188:191], v[62:65]
	v_mfma_f32_16x16x32_bf16 v[54:57], v[164:167], v[188:191], v[54:57]
	v_mfma_f32_16x16x32_bf16 v[46:49], v[148:151], v[210:213], v[46:49]
	v_mfma_f32_16x16x32_bf16 v[38:41], v[164:167], v[210:213], v[38:41]
	v_mfma_f32_16x16x32_bf16 v[30:33], v[148:151], v[218:221], v[30:33]
	v_mfma_f32_16x16x32_bf16 v[22:25], v[164:167], v[218:221], v[22:25]
	v_mfma_f32_16x16x32_bf16 v[14:17], v[148:151], v[226:229], v[14:17]
	v_mfma_f32_16x16x32_bf16 v[6:9], v[164:167], v[226:229], v[6:9]
	v_mfma_f32_16x16x32_bf16 v[62:65], v[160:163], v[192:195], v[62:65]
	v_mfma_f32_16x16x32_bf16 v[54:57], v[168:171], v[192:195], v[54:57]
	v_mfma_f32_16x16x32_bf16 v[46:49], v[160:163], v[214:217], v[46:49]
	v_mfma_f32_16x16x32_bf16 v[38:41], v[168:171], v[214:217], v[38:41]
	v_mfma_f32_16x16x32_bf16 v[30:33], v[160:163], v[222:225], v[30:33]
	v_mfma_f32_16x16x32_bf16 v[22:25], v[168:171], v[222:225], v[22:25]
	v_mfma_f32_16x16x32_bf16 v[14:17], v[160:163], v[230:233], v[14:17]
	v_mfma_f32_16x16x32_bf16 v[6:9], v[168:171], v[230:233], v[6:9]
	v_mfma_f32_16x16x32_bf16 v[58:61], v[172:175], v[188:191], v[58:61]
	v_mfma_f32_16x16x32_bf16 v[50:53], v[180:183], v[188:191], v[50:53]
	v_mfma_f32_16x16x32_bf16 v[42:45], v[172:175], v[210:213], v[42:45]
	v_mfma_f32_16x16x32_bf16 v[34:37], v[180:183], v[210:213], v[34:37]
	v_mfma_f32_16x16x32_bf16 v[26:29], v[172:175], v[218:221], v[26:29]
	v_mfma_f32_16x16x32_bf16 v[18:21], v[180:183], v[218:221], v[18:21]
	v_mfma_f32_16x16x32_bf16 v[10:13], v[172:175], v[226:229], v[10:13]
	v_mfma_f32_16x16x32_bf16 v[2:5], v[180:183], v[226:229], v[2:5]
	v_mfma_f32_16x16x32_bf16 v[58:61], v[176:179], v[192:195], v[58:61]
	v_mfma_f32_16x16x32_bf16 v[50:53], v[184:187], v[192:195], v[50:53]
	v_mfma_f32_16x16x32_bf16 v[42:45], v[176:179], v[214:217], v[42:45]
	v_mfma_f32_16x16x32_bf16 v[34:37], v[184:187], v[214:217], v[34:37]
	v_mfma_f32_16x16x32_bf16 v[26:29], v[176:179], v[222:225], v[26:29]
	v_mfma_f32_16x16x32_bf16 v[18:21], v[184:187], v[222:225], v[18:21]
	v_mfma_f32_16x16x32_bf16 v[10:13], v[176:179], v[230:233], v[10:13]
	v_mfma_f32_16x16x32_bf16 v[2:5], v[184:187], v[230:233], v[2:5]
	s_barrier
	s_add_i32 s82, s82, 2
	s_add_u32 s44, s44, 0x100
	s_addc_u32 s45, s45, 0
	s_add_u32 vcc_lo, vcc_lo, 0x100
	s_addc_u32 vcc_hi, vcc_hi, 0
	s_cmp_gt_u32 s82, 29
	s_cbranch_scc0 .LBB0_467
